# GEMM K-loop restructured in 6 phases: frag double-buffer in regs, single mid-iteration barrier, global loads one full iteration ahead, swizzled unpadded LDS; attn prefetch hoists
# speedup vs baseline: 1.0324x; 1.0179x over previous
.LBB0_242:
	v_lshlrev_b32_e32 v4, 4, v2
	v_and_b32_e32 v4, 0x70, v4
	v_mov_b32_e32 v5, 0
	v_lshl_add_u64 v[6:7], s[86:87], 0, v[4:5]
	s_mov_b64 s[6:7], 0x18e50000
	v_lshrrev_b32_e32 v1, 3, v2
	v_lshl_add_u64 v[130:131], v[6:7], 0, s[6:7]
	s_mov_b64 s[6:7], 0x300000
	s_add_u32 s4, s86, 0x3c50000
	v_lshl_add_u64 v[132:133], v[6:7], 0, s[6:7]
	v_mul_u32_u24_e32 v6, 0x48, v1
	s_addc_u32 s5, s87, 0
	v_lshlrev_b32_e32 v6, 1, v6
	s_add_i32 s6, 0, 0x12000
	v_add3_u32 v146, 0, v6, v4
	v_add3_u32 v147, s6, v6, v4
	v_and_b32_e32 v4, 15, v2
	v_lshrrev_b32_e32 v6, 1, v2
	s_movk_i32 s7, 0x180
	v_and_or_b32 v4, v6, s7, v4
	v_mul_u32_u24_e32 v4, 0x90, v4
	v_and_b32_e32 v6, 48, v2
	v_add3_u32 v148, 0, v4, v6
	v_and_b32_e32 v4, 0xcf, v2
	v_mov_b32_e32 v3, v2
	v_mul_u32_u24_e32 v4, 0x90, v4
	s_lshr_b32 s3, s2, 3
	s_and_b32 s10, s2, 7
	v_add3_u32 v149, s6, v4, v6
	v_lshrrev_b32_e32 v4, 1, v1
	v_and_b32_e32 v4, 7, v4
	v_and_b32_e32 v7, 7, v2
	v_xor_b32_e32 v4, v4, v7
	v_lshlrev_b32_e32 v4, 4, v4
	v_lshl_add_u32 v146, v1, 7, v4
	v_add_u32_e32 v147, 0x10000, v146
	v_and_b32_e32 v4, 15, v2
	v_lshrrev_b32_e32 v7, 1, v4
	v_bfe_u32 v216, v2, 4, 2
	v_xor_b32_e32 v7, v7, v216
	v_lshlrev_b32_e32 v7, 4, v7
	v_lshrrev_b32_e32 v216, 8, v2
	v_lshl_add_u32 v216, v216, 7, v4
	v_lshl_add_u32 v148, v216, 7, v7
	v_xor_b32_e32 v216, 64, v148
	v_bfe_u32 v217, v2, 6, 2
	v_lshl_add_u32 v217, v217, 6, v4
	v_lshl_add_u32 v149, v217, 7, v7
	v_add_u32_e32 v149, 0x10000, v149
	v_xor_b32_e32 v217, 64, v149
	v_ashrrev_i32_e32 v4, 1, v3
	v_and_b32_e32 v7, 15, v3
	s_movk_i32 s6, 0xff80
	v_and_b32_e32 v2, 7, v2
	v_and_b32_e32 v6, 0xc0, v3
	v_and_or_b32 v150, v4, s6, v7
	s_add_u32 s6, s86, 0x2f82000
	v_lshrrev_b32_e32 v3, 2, v3
	v_lshlrev_b32_e32 v4, 4, v2
	s_mul_i32 s10, s10, 33
	s_addc_u32 s7, s87, 0
	v_and_or_b32 v151, v3, 12, v6
	s_ashr_i32 s11, s33, 3
	v_lshl_add_u64 v[134:135], s[86:87], 0, v[4:5]
	s_mov_b32 s12, 0x20000
	s_mov_b32 s13, 0x40000
	s_mov_b32 s14, 0x60000
	s_mov_b32 s15, 0x18e50000
	s_waitcnt lgkmcnt(0)
	s_mov_b32 s16, 0x18e70000
	s_mov_b32 s17, 0x18e90000
	s_mov_b32 s28, 0x18eb0000
	s_mov_b32 s29, 0x300000
	s_mov_b32 s38, 0x320000
	s_mov_b32 s39, 0x340000
	s_mov_b32 s42, 0x360000
	s_mov_b32 s43, 0x3e0f83e1
	s_movk_i32 s44, 0xdf00
	s_movk_i32 s45, 0xff
	s_movk_i32 s46, 0xff00
	s_branch .LBB0_245

.LBB0_248:
	s_lshl_b32 s56, s52, 8
	v_or_b32_e32 v2, s56, v1
	v_ashrrev_i32_e32 v3, 31, v2
	v_lshlrev_b64 v[62:63], 11, v[2:3]
	v_lshl_add_u64 v[2:3], v[130:131], 0, v[62:63]
	v_add_co_u32_e32 v6, vcc, 0x20000, v2
	s_lshl_b32 s53, s47, 8
	s_nop 0
	v_addc_co_u32_e32 v7, vcc, 0, v3, vcc
	v_or_b32_e32 v4, s53, v1
	global_load_dwordx4 v[30:33], v[2:3], off
	global_load_dwordx4 v[34:37], v[6:7], off
	v_add_co_u32_e32 v6, vcc, 0x40000, v2
	v_ashrrev_i32_e32 v5, 31, v4
	s_nop 0
	v_addc_co_u32_e32 v7, vcc, 0, v3, vcc
	v_lshlrev_b64 v[64:65], 11, v[4:5]
	v_add_co_u32_e32 v2, vcc, 0x60000, v2
	v_lshl_add_u64 v[4:5], v[132:133], 0, v[64:65]
	s_nop 0
	v_addc_co_u32_e32 v3, vcc, 0, v3, vcc
	global_load_dwordx4 v[38:41], v[6:7], off
	global_load_dwordx4 v[42:45], v[2:3], off
	v_add_co_u32_e32 v2, vcc, s12, v4
	s_waitcnt vmcnt(63) expcnt(7) lgkmcnt(15)
	s_nop 0
	v_addc_co_u32_e32 v3, vcc, 0, v5, vcc
	s_barrier
	global_load_dwordx4 v[46:49], v[4:5], off
	global_load_dwordx4 v[50:53], v[2:3], off
	v_add_co_u32_e32 v2, vcc, s13, v4
	s_mov_b32 s57, 0
	s_nop 0
	v_addc_co_u32_e32 v3, vcc, 0, v5, vcc
	v_add_co_u32_e32 v4, vcc, s14, v4
	s_mov_b64 s[8:9], 0
	s_nop 0
	v_addc_co_u32_e32 v5, vcc, 0, v5, vcc
	global_load_dwordx4 v[54:57], v[2:3], off
	global_load_dwordx4 v[58:61], v[4:5], off
	v_mov_b32_e32 v2, 0
	v_mov_b32_e32 v3, v2
	v_mov_b32_e32 v4, v2
	v_mov_b32_e32 v5, v2
	v_mov_b32_e32 v6, v2
	v_mov_b32_e32 v7, v2
	v_mov_b32_e32 v8, v2
	v_mov_b32_e32 v9, v2
	v_mov_b32_e32 v10, v2
	v_mov_b32_e32 v11, v2
	v_mov_b32_e32 v12, v2
	v_mov_b32_e32 v13, v2
	v_mov_b32_e32 v14, v2
	v_mov_b32_e32 v15, v2
	v_mov_b32_e32 v16, v2
	v_mov_b32_e32 v17, v2
	v_mov_b32_e32 v18, v2
	v_mov_b32_e32 v19, v2
	v_mov_b32_e32 v20, v2
	v_mov_b32_e32 v21, v2
	v_mov_b32_e32 v22, v2
	v_mov_b32_e32 v23, v2
	v_mov_b32_e32 v24, v2
	v_mov_b32_e32 v25, v2
	v_mov_b32_e32 v26, v2
	v_mov_b32_e32 v27, v2
	v_mov_b32_e32 v28, v2
	v_lshl_add_u64 v[136:137], v[134:135], 0, v[62:63]
	v_lshl_add_u64 v[138:139], v[134:135], 0, v[64:65]
	v_mov_b32_e32 v29, v2
	v_mov_b32_e32 v62, v2
	v_mov_b32_e32 v63, v2
	v_mov_b32_e32 v64, v2
	v_mov_b32_e32 v65, v2
	v_mov_b32_e32 v66, v2
	v_mov_b32_e32 v67, v2
	v_mov_b32_e32 v68, v2
	v_mov_b32_e32 v69, v2
	v_mov_b32_e32 v70, v2
	v_mov_b32_e32 v71, v2
	v_mov_b32_e32 v72, v2
	v_mov_b32_e32 v73, v2
	v_mov_b32_e32 v74, v2
	v_mov_b32_e32 v75, v2
	v_mov_b32_e32 v76, v2
	v_mov_b32_e32 v77, v2
	v_mov_b32_e32 v78, v2
	v_mov_b32_e32 v79, v2
	v_mov_b32_e32 v80, v2
	v_mov_b32_e32 v81, v2
	v_mov_b32_e32 v82, v2
	v_mov_b32_e32 v83, v2
	v_mov_b32_e32 v84, v2
	s_waitcnt vmcnt(7)
	ds_write_b128 v146, v[30:33]
	s_waitcnt vmcnt(6)
	ds_write_b128 v146, v[34:37] offset:8192
	s_waitcnt vmcnt(5)
	ds_write_b128 v146, v[38:41] offset:16384
	s_waitcnt vmcnt(4)
	ds_write_b128 v146, v[42:45] offset:24576
	s_waitcnt vmcnt(3)
	ds_write_b128 v147, v[46:49]
	s_waitcnt vmcnt(2)
	ds_write_b128 v147, v[50:53] offset:8192
	s_waitcnt vmcnt(1)
	ds_write_b128 v147, v[54:57] offset:16384
	s_waitcnt vmcnt(0)
	ds_write_b128 v147, v[58:61] offset:24576
	v_mov_b32_e32 v30, v2
	v_mov_b32_e32 v31, v2
	v_mov_b32_e32 v32, v2
	v_mov_b32_e32 v33, v2
	v_mov_b32_e32 v34, v2
	v_mov_b32_e32 v35, v2
	v_mov_b32_e32 v36, v2
	v_mov_b32_e32 v37, v2
	v_mov_b32_e32 v38, v2
	v_mov_b32_e32 v39, v2
	v_mov_b32_e32 v40, v2
	v_mov_b32_e32 v41, v2
	v_mov_b32_e32 v42, v2
	v_mov_b32_e32 v43, v2
	v_mov_b32_e32 v44, v2
	v_mov_b32_e32 v45, v2
	v_mov_b32_e32 v46, v2
	v_mov_b32_e32 v47, v2
	v_mov_b32_e32 v48, v2
	v_mov_b32_e32 v49, v2
	v_mov_b32_e32 v50, v2
	v_mov_b32_e32 v51, v2
	v_mov_b32_e32 v52, v2
	v_mov_b32_e32 v53, v2
	v_mov_b32_e32 v54, v2
	v_mov_b32_e32 v55, v2
	v_mov_b32_e32 v56, v2
	v_mov_b32_e32 v57, v2
	v_mov_b32_e32 v58, v2
	v_mov_b32_e32 v59, v2
	v_mov_b32_e32 v60, v2
	v_mov_b32_e32 v61, v2
	v_mov_b32_e32 v85, v2
	v_mov_b32_e32 v86, v2
	v_mov_b32_e32 v87, v2
	v_mov_b32_e32 v88, v2
	v_mov_b32_e32 v89, v2
	v_mov_b32_e32 v90, v2
	v_mov_b32_e32 v91, v2
	v_mov_b32_e32 v92, v2
	v_mov_b32_e32 v93, v2
	v_mov_b32_e32 v94, v2
	v_mov_b32_e32 v95, v2
	v_mov_b32_e32 v96, v2
	v_mov_b32_e32 v97, v2
	v_mov_b32_e32 v98, v2
	v_mov_b32_e32 v99, v2
	v_mov_b32_e32 v100, v2
	v_mov_b32_e32 v101, v2
	v_mov_b32_e32 v102, v2
	v_mov_b32_e32 v103, v2
	v_mov_b32_e32 v104, v2
	v_mov_b32_e32 v105, v2
	v_mov_b32_e32 v106, v2
	v_mov_b32_e32 v107, v2
	v_mov_b32_e32 v108, v2
	v_mov_b32_e32 v109, v2
	v_mov_b32_e32 v110, v2
	v_mov_b32_e32 v111, v2
	v_mov_b32_e32 v112, v2
	v_mov_b32_e32 v113, v2
	v_mov_b32_e32 v114, v2
	v_mov_b32_e32 v115, v2
	v_mov_b32_e32 v116, v2
	v_mov_b32_e32 v117, v2
	v_mov_b32_e32 v118, v2
	v_mov_b32_e32 v119, v2
	v_mov_b32_e32 v120, v2
	v_mov_b32_e32 v121, v2
	v_mov_b32_e32 v122, v2
	v_mov_b32_e32 v123, v2
	v_mov_b32_e32 v124, v2
	v_mov_b32_e32 v125, v2
	v_mov_b32_e32 v126, v2
	v_mov_b32_e32 v127, v2
	v_mov_b32_e32 v128, v2
	v_mov_b32_e32 v129, v2
	s_waitcnt lgkmcnt(0)
	s_barrier
	v_lshl_add_u64 v[140:141], v[136:137], 0, s[8:9]
	v_add_co_u32_e32 v142, vcc, s15, v140
	s_nop 1
	v_addc_co_u32_e32 v143, vcc, 0, v141, vcc
	v_add_co_u32_e32 v144, vcc, s16, v140
	s_nop 1
	v_addc_co_u32_e32 v145, vcc, 0, v141, vcc
	v_add_co_u32_e32 v156, vcc, s17, v140
	s_nop 1
	v_addc_co_u32_e32 v157, vcc, 0, v141, vcc
	v_add_co_u32_e32 v160, vcc, s28, v140
	s_nop 1
	v_addc_co_u32_e32 v161, vcc, 0, v141, vcc
	global_load_dwordx4 v[140:143], v[142:143], off offset:128
	global_load_dwordx4 v[152:155], v[144:145], off offset:128
	global_load_dwordx4 v[156:159], v[156:157], off offset:128
	global_load_dwordx4 v[160:163], v[160:161], off offset:128
	v_lshl_add_u64 v[144:145], v[138:139], 0, s[8:9]
	v_add_co_u32_e32 v164, vcc, s29, v144
	s_nop 1
	v_addc_co_u32_e32 v165, vcc, 0, v145, vcc
	v_add_co_u32_e32 v168, vcc, s38, v144
	s_nop 1
	v_addc_co_u32_e32 v169, vcc, 0, v145, vcc
	v_add_co_u32_e32 v172, vcc, s39, v144
	s_nop 1
	v_addc_co_u32_e32 v173, vcc, 0, v145, vcc
	v_add_co_u32_e32 v144, vcc, s42, v144
	s_nop 1
	v_addc_co_u32_e32 v145, vcc, 0, v145, vcc
	global_load_dwordx4 v[164:167], v[164:165], off offset:128
	global_load_dwordx4 v[168:171], v[168:169], off offset:128
	global_load_dwordx4 v[172:175], v[172:173], off offset:128
	global_load_dwordx4 v[176:179], v[144:145], off offset:128
	v_mov_b32_e32 v223, v148
	v_mov_b32_e32 v248, v216
	v_mov_b32_e32 v249, v149
	v_mov_b32_e32 v250, v217
	v_xor_b32_e32 v251, 0x8000, v146
	v_xor_b32_e32 v252, 0x8000, v147
	ds_read_b128 v[180:183], v223
	ds_read_b128 v[184:187], v223 offset:2048
	ds_read_b128 v[188:191], v223 offset:4096
	ds_read_b128 v[192:195], v223 offset:6144
	ds_read_b128 v[212:215], v249
	ds_read_b128 v[218:221], v249 offset:2048
	ds_read_b128 v[224:227], v249 offset:4096
	ds_read_b128 v[228:231], v249 offset:6144
.Lg2_p4_loop:
	ds_read_b128 v[196:199], v223 offset:8192
	ds_read_b128 v[200:203], v223 offset:10240
	ds_read_b128 v[204:207], v223 offset:12288
	ds_read_b128 v[208:211], v223 offset:14336
	s_waitcnt lgkmcnt(4)
	v_mfma_f32_16x16x32_bf16 v[126:129], v[212:215], v[180:183], v[126:129]
	v_mfma_f32_16x16x32_bf16 v[122:125], v[218:221], v[180:183], v[122:125]
	v_mfma_f32_16x16x32_bf16 v[118:121], v[224:227], v[180:183], v[118:121]
	v_mfma_f32_16x16x32_bf16 v[114:117], v[228:231], v[180:183], v[114:117]
	v_mfma_f32_16x16x32_bf16 v[110:113], v[212:215], v[184:187], v[110:113]
	v_mfma_f32_16x16x32_bf16 v[106:109], v[218:221], v[184:187], v[106:109]
	v_mfma_f32_16x16x32_bf16 v[102:105], v[224:227], v[184:187], v[102:105]
	v_mfma_f32_16x16x32_bf16 v[98:101], v[228:231], v[184:187], v[98:101]
	v_mfma_f32_16x16x32_bf16 v[94:97], v[212:215], v[188:191], v[94:97]
	v_mfma_f32_16x16x32_bf16 v[90:93], v[218:221], v[188:191], v[90:93]
	v_mfma_f32_16x16x32_bf16 v[86:89], v[224:227], v[188:191], v[86:89]
	v_mfma_f32_16x16x32_bf16 v[82:85], v[228:231], v[188:191], v[82:85]
	v_mfma_f32_16x16x32_bf16 v[78:81], v[212:215], v[192:195], v[78:81]
	v_mfma_f32_16x16x32_bf16 v[74:77], v[218:221], v[192:195], v[74:77]
	v_mfma_f32_16x16x32_bf16 v[70:73], v[224:227], v[192:195], v[70:73]
	v_mfma_f32_16x16x32_bf16 v[66:69], v[228:231], v[192:195], v[66:69]
	ds_read_b128 v[180:183], v248
	ds_read_b128 v[184:187], v248 offset:2048
	ds_read_b128 v[188:191], v248 offset:4096
	ds_read_b128 v[192:195], v248 offset:6144
	ds_read_b128 v[232:235], v250
	ds_read_b128 v[236:239], v250 offset:2048
	ds_read_b128 v[240:243], v250 offset:4096
	ds_read_b128 v[244:247], v250 offset:6144
	s_waitcnt lgkmcnt(8)
	v_mfma_f32_16x16x32_bf16 v[62:65], v[212:215], v[196:199], v[62:65]
	v_mfma_f32_16x16x32_bf16 v[58:61], v[218:221], v[196:199], v[58:61]
	v_mfma_f32_16x16x32_bf16 v[54:57], v[224:227], v[196:199], v[54:57]
	v_mfma_f32_16x16x32_bf16 v[50:53], v[228:231], v[196:199], v[50:53]
	v_mfma_f32_16x16x32_bf16 v[46:49], v[212:215], v[200:203], v[46:49]
	v_mfma_f32_16x16x32_bf16 v[42:45], v[218:221], v[200:203], v[42:45]
	v_mfma_f32_16x16x32_bf16 v[38:41], v[224:227], v[200:203], v[38:41]
	v_mfma_f32_16x16x32_bf16 v[34:37], v[228:231], v[200:203], v[34:37]
	v_mfma_f32_16x16x32_bf16 v[30:33], v[212:215], v[204:207], v[30:33]
	v_mfma_f32_16x16x32_bf16 v[26:29], v[218:221], v[204:207], v[26:29]
	v_mfma_f32_16x16x32_bf16 v[22:25], v[224:227], v[204:207], v[22:25]
	v_mfma_f32_16x16x32_bf16 v[18:21], v[228:231], v[204:207], v[18:21]
	v_mfma_f32_16x16x32_bf16 v[14:17], v[212:215], v[208:211], v[14:17]
	v_mfma_f32_16x16x32_bf16 v[10:13], v[218:221], v[208:211], v[10:13]
	v_mfma_f32_16x16x32_bf16 v[6:9], v[224:227], v[208:211], v[6:9]
	v_mfma_f32_16x16x32_bf16 v[2:5], v[228:231], v[208:211], v[2:5]
	ds_read_b128 v[196:199], v248 offset:8192
	ds_read_b128 v[200:203], v248 offset:10240
	ds_read_b128 v[204:207], v248 offset:12288
	ds_read_b128 v[208:211], v248 offset:14336
	s_waitcnt lgkmcnt(4)
	v_mfma_f32_16x16x32_bf16 v[126:129], v[232:235], v[180:183], v[126:129]
	v_mfma_f32_16x16x32_bf16 v[122:125], v[236:239], v[180:183], v[122:125]
	s_waitcnt vmcnt(7)
	ds_write_b128 v251, v[140:143]
	v_mfma_f32_16x16x32_bf16 v[118:121], v[240:243], v[180:183], v[118:121]
	v_mfma_f32_16x16x32_bf16 v[114:117], v[244:247], v[180:183], v[114:117]
	s_waitcnt vmcnt(6)
	ds_write_b128 v251, v[152:155] offset:8192
	v_mfma_f32_16x16x32_bf16 v[110:113], v[232:235], v[184:187], v[110:113]
	v_mfma_f32_16x16x32_bf16 v[106:109], v[236:239], v[184:187], v[106:109]
	s_waitcnt vmcnt(5)
	ds_write_b128 v251, v[156:159] offset:16384
	v_mfma_f32_16x16x32_bf16 v[102:105], v[240:243], v[184:187], v[102:105]
	v_mfma_f32_16x16x32_bf16 v[98:101], v[244:247], v[184:187], v[98:101]
	s_waitcnt vmcnt(4)
	ds_write_b128 v251, v[160:163] offset:24576
	v_mfma_f32_16x16x32_bf16 v[94:97], v[232:235], v[188:191], v[94:97]
	v_mfma_f32_16x16x32_bf16 v[90:93], v[236:239], v[188:191], v[90:93]
	s_waitcnt vmcnt(3)
	ds_write_b128 v252, v[164:167]
	v_mfma_f32_16x16x32_bf16 v[86:89], v[240:243], v[188:191], v[86:89]
	v_mfma_f32_16x16x32_bf16 v[82:85], v[244:247], v[188:191], v[82:85]
	s_waitcnt vmcnt(2)
	ds_write_b128 v252, v[168:171] offset:8192
	v_mfma_f32_16x16x32_bf16 v[78:81], v[232:235], v[192:195], v[78:81]
	v_mfma_f32_16x16x32_bf16 v[74:77], v[236:239], v[192:195], v[74:77]
	s_waitcnt vmcnt(1)
	ds_write_b128 v252, v[172:175] offset:16384
	v_mfma_f32_16x16x32_bf16 v[70:73], v[240:243], v[192:195], v[70:73]
	v_mfma_f32_16x16x32_bf16 v[66:69], v[244:247], v[192:195], v[66:69]
	s_waitcnt vmcnt(0)
	ds_write_b128 v252, v[176:179] offset:24576
	s_waitcnt lgkmcnt(0)
	s_barrier
	s_add_u32 s8, s8, 0x80
	s_addc_u32 s9, s9, 0
	s_cmpk_eq_i32 s8, 0x780
	s_cbranch_scc1 .Lg2_p4_tail
	v_xor_b32_e32 v223, 0x8000, v223
	v_xor_b32_e32 v249, 0x8000, v249
	v_xor_b32_e32 v248, 0x8000, v248
	v_xor_b32_e32 v250, 0x8000, v250
	v_xor_b32_e32 v251, 0x8000, v251
	v_xor_b32_e32 v252, 0x8000, v252
	ds_read_b128 v[180:183], v223
	ds_read_b128 v[184:187], v223 offset:2048
	ds_read_b128 v[188:191], v223 offset:4096
	ds_read_b128 v[192:195], v223 offset:6144
	ds_read_b128 v[212:215], v249
	ds_read_b128 v[218:221], v249 offset:2048
	ds_read_b128 v[224:227], v249 offset:4096
	ds_read_b128 v[228:231], v249 offset:6144
	v_mfma_f32_16x16x32_bf16 v[62:65], v[232:235], v[196:199], v[62:65]
	v_lshl_add_u64 v[140:141], v[136:137], 0, s[8:9]
	v_add_co_u32_e32 v142, vcc, s15, v140
	v_mfma_f32_16x16x32_bf16 v[58:61], v[236:239], v[196:199], v[58:61]
	s_nop 1
	v_addc_co_u32_e32 v143, vcc, 0, v141, vcc
	v_mfma_f32_16x16x32_bf16 v[54:57], v[240:243], v[196:199], v[54:57]
	v_add_co_u32_e32 v144, vcc, s16, v140
	s_nop 1
	v_mfma_f32_16x16x32_bf16 v[50:53], v[244:247], v[196:199], v[50:53]
	v_addc_co_u32_e32 v145, vcc, 0, v141, vcc
	v_add_co_u32_e32 v156, vcc, s17, v140
	v_mfma_f32_16x16x32_bf16 v[46:49], v[232:235], v[200:203], v[46:49]
	s_nop 1
	v_addc_co_u32_e32 v157, vcc, 0, v141, vcc
	v_mfma_f32_16x16x32_bf16 v[42:45], v[236:239], v[200:203], v[42:45]
	v_add_co_u32_e32 v160, vcc, s28, v140
	s_nop 1
	v_mfma_f32_16x16x32_bf16 v[38:41], v[240:243], v[200:203], v[38:41]
	v_addc_co_u32_e32 v161, vcc, 0, v141, vcc
	global_load_dwordx4 v[140:143], v[142:143], off offset:128
	v_mfma_f32_16x16x32_bf16 v[34:37], v[244:247], v[200:203], v[34:37]
	global_load_dwordx4 v[152:155], v[144:145], off offset:128
	global_load_dwordx4 v[156:159], v[156:157], off offset:128
	global_load_dwordx4 v[160:163], v[160:161], off offset:128
	v_mfma_f32_16x16x32_bf16 v[30:33], v[232:235], v[204:207], v[30:33]
	v_lshl_add_u64 v[144:145], v[138:139], 0, s[8:9]
	v_add_co_u32_e32 v164, vcc, s29, v144
	v_mfma_f32_16x16x32_bf16 v[26:29], v[236:239], v[204:207], v[26:29]
	s_nop 1
	v_addc_co_u32_e32 v165, vcc, 0, v145, vcc
	v_mfma_f32_16x16x32_bf16 v[22:25], v[240:243], v[204:207], v[22:25]
	v_add_co_u32_e32 v168, vcc, s38, v144
	s_nop 1
	v_mfma_f32_16x16x32_bf16 v[18:21], v[244:247], v[204:207], v[18:21]
	v_addc_co_u32_e32 v169, vcc, 0, v145, vcc
	v_add_co_u32_e32 v172, vcc, s39, v144
	v_mfma_f32_16x16x32_bf16 v[14:17], v[232:235], v[208:211], v[14:17]
	s_nop 1
	v_addc_co_u32_e32 v173, vcc, 0, v145, vcc
	v_mfma_f32_16x16x32_bf16 v[10:13], v[236:239], v[208:211], v[10:13]
	v_add_co_u32_e32 v144, vcc, s42, v144
	s_nop 1
	v_mfma_f32_16x16x32_bf16 v[6:9], v[240:243], v[208:211], v[6:9]
	v_addc_co_u32_e32 v145, vcc, 0, v145, vcc
	global_load_dwordx4 v[164:167], v[164:165], off offset:128
	v_mfma_f32_16x16x32_bf16 v[2:5], v[244:247], v[208:211], v[2:5]
	global_load_dwordx4 v[168:171], v[168:169], off offset:128
	global_load_dwordx4 v[172:175], v[172:173], off offset:128
	global_load_dwordx4 v[176:179], v[144:145], off offset:128
	s_branch .Lg2_p4_loop
.Lg2_p4_tail:
	v_mfma_f32_16x16x32_bf16 v[62:65], v[232:235], v[196:199], v[62:65]
	v_mfma_f32_16x16x32_bf16 v[58:61], v[236:239], v[196:199], v[58:61]
	v_mfma_f32_16x16x32_bf16 v[54:57], v[240:243], v[196:199], v[54:57]
	v_mfma_f32_16x16x32_bf16 v[50:53], v[244:247], v[196:199], v[50:53]
	v_mfma_f32_16x16x32_bf16 v[46:49], v[232:235], v[200:203], v[46:49]
	v_mfma_f32_16x16x32_bf16 v[42:45], v[236:239], v[200:203], v[42:45]
	v_mfma_f32_16x16x32_bf16 v[38:41], v[240:243], v[200:203], v[38:41]
	v_mfma_f32_16x16x32_bf16 v[34:37], v[244:247], v[200:203], v[34:37]
	v_mfma_f32_16x16x32_bf16 v[30:33], v[232:235], v[204:207], v[30:33]
	v_mfma_f32_16x16x32_bf16 v[26:29], v[236:239], v[204:207], v[26:29]
	v_mfma_f32_16x16x32_bf16 v[22:25], v[240:243], v[204:207], v[22:25]
	v_mfma_f32_16x16x32_bf16 v[18:21], v[244:247], v[204:207], v[18:21]
	v_mfma_f32_16x16x32_bf16 v[14:17], v[232:235], v[208:211], v[14:17]
	v_mfma_f32_16x16x32_bf16 v[10:13], v[236:239], v[208:211], v[10:13]
	v_mfma_f32_16x16x32_bf16 v[6:9], v[240:243], v[208:211], v[6:9]
	v_mfma_f32_16x16x32_bf16 v[2:5], v[244:247], v[208:211], v[2:5]
	ds_read_b128 v[136:139], v149 offset:32768
	ds_read_b128 v[140:143], v149 offset:34816
	ds_read_b128 v[152:155], v149 offset:36864
	ds_read_b128 v[156:159], v149 offset:38912
	ds_read_b128 v[160:163], v148 offset:32768
	ds_read_b128 v[164:167], v148 offset:34816
	ds_read_b128 v[168:171], v148 offset:36864
	ds_read_b128 v[172:175], v148 offset:38912
	s_setprio 1
	s_waitcnt lgkmcnt(3)
	v_mfma_f32_16x16x32_bf16 v[126:129], v[136:139], v[160:163], v[126:129]
	v_mfma_f32_16x16x32_bf16 v[122:125], v[140:143], v[160:163], v[122:125]
	v_mfma_f32_16x16x32_bf16 v[118:121], v[152:155], v[160:163], v[118:121]
	v_mfma_f32_16x16x32_bf16 v[114:117], v[156:159], v[160:163], v[114:117]
	s_waitcnt lgkmcnt(2)
	v_mfma_f32_16x16x32_bf16 v[110:113], v[136:139], v[164:167], v[110:113]
	v_mfma_f32_16x16x32_bf16 v[106:109], v[140:143], v[164:167], v[106:109]
	v_mfma_f32_16x16x32_bf16 v[102:105], v[152:155], v[164:167], v[102:105]
	v_mfma_f32_16x16x32_bf16 v[98:101], v[156:159], v[164:167], v[98:101]
	s_waitcnt lgkmcnt(1)
	v_mfma_f32_16x16x32_bf16 v[94:97], v[136:139], v[168:171], v[94:97]
	v_mfma_f32_16x16x32_bf16 v[90:93], v[140:143], v[168:171], v[90:93]
	v_mfma_f32_16x16x32_bf16 v[86:89], v[152:155], v[168:171], v[86:89]
	v_mfma_f32_16x16x32_bf16 v[82:85], v[156:159], v[168:171], v[82:85]
	s_waitcnt lgkmcnt(0)
	v_mfma_f32_16x16x32_bf16 v[78:81], v[136:139], v[172:175], v[78:81]
	v_mfma_f32_16x16x32_bf16 v[74:77], v[140:143], v[172:175], v[74:77]
	v_mfma_f32_16x16x32_bf16 v[70:73], v[152:155], v[172:175], v[70:73]
	v_mfma_f32_16x16x32_bf16 v[66:69], v[156:159], v[172:175], v[66:69]
	s_setprio 0
	ds_read_b128 v[160:163], v148 offset:40960
	ds_read_b128 v[164:167], v148 offset:43008
	ds_read_b128 v[168:171], v148 offset:45056
	ds_read_b128 v[172:175], v148 offset:47104
	s_setprio 1
	s_waitcnt lgkmcnt(3)
	v_mfma_f32_16x16x32_bf16 v[62:65], v[136:139], v[160:163], v[62:65]
	v_mfma_f32_16x16x32_bf16 v[58:61], v[140:143], v[160:163], v[58:61]
	v_mfma_f32_16x16x32_bf16 v[54:57], v[152:155], v[160:163], v[54:57]
	v_mfma_f32_16x16x32_bf16 v[50:53], v[156:159], v[160:163], v[50:53]
	s_waitcnt lgkmcnt(2)
	v_mfma_f32_16x16x32_bf16 v[46:49], v[136:139], v[164:167], v[46:49]
	v_mfma_f32_16x16x32_bf16 v[42:45], v[140:143], v[164:167], v[42:45]
	v_mfma_f32_16x16x32_bf16 v[38:41], v[152:155], v[164:167], v[38:41]
	v_mfma_f32_16x16x32_bf16 v[34:37], v[156:159], v[164:167], v[34:37]
	s_waitcnt lgkmcnt(1)
	v_mfma_f32_16x16x32_bf16 v[30:33], v[136:139], v[168:171], v[30:33]
	v_mfma_f32_16x16x32_bf16 v[26:29], v[140:143], v[168:171], v[26:29]
	v_mfma_f32_16x16x32_bf16 v[22:25], v[152:155], v[168:171], v[22:25]
	v_mfma_f32_16x16x32_bf16 v[18:21], v[156:159], v[168:171], v[18:21]
	s_waitcnt lgkmcnt(0)
	v_mfma_f32_16x16x32_bf16 v[14:17], v[136:139], v[172:175], v[14:17]
	v_mfma_f32_16x16x32_bf16 v[10:13], v[140:143], v[172:175], v[10:13]
	v_mfma_f32_16x16x32_bf16 v[6:9], v[152:155], v[172:175], v[6:9]
	v_mfma_f32_16x16x32_bf16 v[2:5], v[156:159], v[172:175], v[2:5]
	s_setprio 0
	ds_read_b128 v[136:139], v217 offset:32768
	ds_read_b128 v[140:143], v217 offset:34816
	ds_read_b128 v[152:155], v217 offset:36864
	ds_read_b128 v[156:159], v217 offset:38912
	ds_read_b128 v[160:163], v216 offset:32768
	ds_read_b128 v[164:167], v216 offset:34816
	ds_read_b128 v[168:171], v216 offset:36864
	ds_read_b128 v[172:175], v216 offset:38912
	s_setprio 1
	s_waitcnt lgkmcnt(3)
	v_mfma_f32_16x16x32_bf16 v[126:129], v[136:139], v[160:163], v[126:129]
	v_mfma_f32_16x16x32_bf16 v[122:125], v[140:143], v[160:163], v[122:125]
	v_mfma_f32_16x16x32_bf16 v[118:121], v[152:155], v[160:163], v[118:121]
	v_mfma_f32_16x16x32_bf16 v[114:117], v[156:159], v[160:163], v[114:117]
	s_waitcnt lgkmcnt(2)
	v_mfma_f32_16x16x32_bf16 v[110:113], v[136:139], v[164:167], v[110:113]
	v_mfma_f32_16x16x32_bf16 v[106:109], v[140:143], v[164:167], v[106:109]
	v_mfma_f32_16x16x32_bf16 v[102:105], v[152:155], v[164:167], v[102:105]
	v_mfma_f32_16x16x32_bf16 v[98:101], v[156:159], v[164:167], v[98:101]
	s_waitcnt lgkmcnt(1)
	v_mfma_f32_16x16x32_bf16 v[94:97], v[136:139], v[168:171], v[94:97]
	v_mfma_f32_16x16x32_bf16 v[90:93], v[140:143], v[168:171], v[90:93]
	v_mfma_f32_16x16x32_bf16 v[86:89], v[152:155], v[168:171], v[86:89]
	v_mfma_f32_16x16x32_bf16 v[82:85], v[156:159], v[168:171], v[82:85]
	s_waitcnt lgkmcnt(0)
	v_mfma_f32_16x16x32_bf16 v[78:81], v[136:139], v[172:175], v[78:81]
	v_mfma_f32_16x16x32_bf16 v[74:77], v[140:143], v[172:175], v[74:77]
	v_mfma_f32_16x16x32_bf16 v[70:73], v[152:155], v[172:175], v[70:73]
	v_mfma_f32_16x16x32_bf16 v[66:69], v[156:159], v[172:175], v[66:69]
	s_setprio 0
	ds_read_b128 v[160:163], v216 offset:40960
	ds_read_b128 v[164:167], v216 offset:43008
	ds_read_b128 v[168:171], v216 offset:45056
	ds_read_b128 v[172:175], v216 offset:47104
	s_setprio 1
	s_waitcnt lgkmcnt(3)
	v_mfma_f32_16x16x32_bf16 v[62:65], v[136:139], v[160:163], v[62:65]
	v_mfma_f32_16x16x32_bf16 v[58:61], v[140:143], v[160:163], v[58:61]
	v_mfma_f32_16x16x32_bf16 v[54:57], v[152:155], v[160:163], v[54:57]
	v_mfma_f32_16x16x32_bf16 v[50:53], v[156:159], v[160:163], v[50:53]
	s_waitcnt lgkmcnt(2)
	v_mfma_f32_16x16x32_bf16 v[46:49], v[136:139], v[164:167], v[46:49]
	v_mfma_f32_16x16x32_bf16 v[42:45], v[140:143], v[164:167], v[42:45]
	v_mfma_f32_16x16x32_bf16 v[38:41], v[152:155], v[164:167], v[38:41]
	v_mfma_f32_16x16x32_bf16 v[34:37], v[156:159], v[164:167], v[34:37]
	s_waitcnt lgkmcnt(1)
	v_mfma_f32_16x16x32_bf16 v[30:33], v[136:139], v[168:171], v[30:33]
	v_mfma_f32_16x16x32_bf16 v[26:29], v[140:143], v[168:171], v[26:29]
	v_mfma_f32_16x16x32_bf16 v[22:25], v[152:155], v[168:171], v[22:25]
	v_mfma_f32_16x16x32_bf16 v[18:21], v[156:159], v[168:171], v[18:21]
	s_waitcnt lgkmcnt(0)
	v_mfma_f32_16x16x32_bf16 v[14:17], v[136:139], v[172:175], v[14:17]
	v_mfma_f32_16x16x32_bf16 v[10:13], v[140:143], v[172:175], v[10:13]
	v_mfma_f32_16x16x32_bf16 v[6:9], v[152:155], v[172:175], v[6:9]
	v_mfma_f32_16x16x32_bf16 v[2:5], v[156:159], v[172:175], v[2:5]
	s_setprio 0
	v_add_u32_e32 v152, s56, v150
	v_mul_hi_i32 v136, v152, s43
	v_lshrrev_b32_e32 v137, 31, v136
	v_ashrrev_i32_e32 v136, 11, v136
	v_add_u32_e32 v139, v136, v137
	v_mad_i32_i24 v142, v139, s44, v152
	v_lshlrev_b32_e32 v141, 13, v139
	v_cmp_lt_i32_e32 vcc, s45, v142
	v_mov_b64_e32 v[136:137], s[40:41]
	v_add3_u32 v138, v141, v142, s46
	s_barrier
	s_and_saveexec_b64 s[8:9], vcc
	s_xor_b64 s[8:9], exec, s[8:9]
	s_cbranch_execz .LBB0_252
	v_add3_u32 v140, v141, v142, s46
	v_mov_b64_e32 v[136:137], s[36:37]
	s_or_saveexec_b64 s[8:9], s[8:9]
	v_lshl_add_u32 v141, v139, 8, v142
	s_xor_b64 exec, exec, s[8:9]
	s_branch .LBB0_253

.LBB0_354:
	s_mul_hi_i32 s0, s3, 0x2e8ba2e9
	s_lshr_b32 s1, s0, 31
	s_ashr_i32 s0, s0, 4
	s_add_i32 s40, s0, s1
	s_lshl_b32 s0, s40, 2
	s_sub_i32 s1, 33, s0
	s_min_u32 s1, s1, 4
	v_cvt_f32_ubyte0_e32 v2, s1
	v_rcp_iflag_f32_e32 v2, v2
	s_sub_i32 s41, 0, s1
	s_mul_i32 s37, s40, 0xffffffa8
	s_add_i32 s37, s37, s3
	v_mul_f32_e32 v2, 0x4f7ffffe, v2
	v_cvt_u32_f32_e32 v2, v2
	s_abs_i32 s39, s37
	s_ashr_i32 s38, s37, 31
	s_mulk_i32 s40, 0x54
	v_readfirstlane_b32 s42, v2
	s_mul_i32 s41, s41, s42
	s_mul_hi_u32 s41, s42, s41
	s_add_i32 s42, s42, s41
	s_mul_hi_u32 s41, s39, s42
	s_mul_i32 s42, s41, s1
	s_sub_i32 s39, s39, s42
	s_add_i32 s42, s41, 1
	s_sub_i32 s43, s39, s1
	s_cmp_ge_u32 s39, s1
	s_cselect_b32 s41, s42, s41
	s_cselect_b32 s39, s43, s39
	s_add_i32 s42, s41, 1
	s_cmp_ge_u32 s39, s1
	s_cselect_b32 s39, s42, s41
	s_xor_b32 s39, s39, s38
	s_sub_i32 s38, s39, s38
	s_add_i32 s0, s0, s6
	s_mul_i32 s41, s1, s38
	s_add_i32 s0, s0, s37
	s_sub_i32 s0, s0, s41
	s_lshl_b32 s37, s0, 8
	v_or_b32_e32 v2, s37, v1
	v_ashrrev_i32_e32 v3, 31, v2
	v_lshlrev_b64 v[2:3], 11, v[2:3]
	v_lshl_add_u64 v[2:3], v[132:133], 0, v[2:3]
	v_add_co_u32_e32 v6, vcc, s9, v2
	s_lshl_b32 s38, s38, 8
	s_nop 0
	v_addc_co_u32_e32 v7, vcc, 0, v3, vcc
	v_or_b32_e32 v4, s38, v1
	global_load_dwordx4 v[20:23], v[2:3], off
	global_load_dwordx4 v[24:27], v[6:7], off
	v_add_co_u32_e32 v6, vcc, s10, v2
	v_ashrrev_i32_e32 v5, 31, v4
	s_nop 0
	v_addc_co_u32_e32 v7, vcc, 0, v3, vcc
	v_lshlrev_b64 v[52:53], 11, v[4:5]
	v_add_co_u32_e32 v2, vcc, s11, v2
	v_lshl_add_u64 v[4:5], v[134:135], 0, v[52:53]
	s_nop 0
	v_addc_co_u32_e32 v3, vcc, 0, v3, vcc
	global_load_dwordx4 v[28:31], v[6:7], off
	global_load_dwordx4 v[32:35], v[2:3], off
	v_add_co_u32_e32 v2, vcc, s9, v4
	s_waitcnt vmcnt(63) expcnt(7) lgkmcnt(15)
	s_nop 0
	v_addc_co_u32_e32 v3, vcc, 0, v5, vcc
	s_barrier
	global_load_dwordx4 v[36:39], v[4:5], off
	global_load_dwordx4 v[40:43], v[2:3], off
	v_add_co_u32_e32 v2, vcc, s10, v4
	s_sub_i32 s41, s8, s41
	s_nop 0
	v_addc_co_u32_e32 v3, vcc, 0, v5, vcc
	v_add_co_u32_e32 v4, vcc, s11, v4
	s_sub_i32 s40, s41, s40
	s_nop 0
	v_addc_co_u32_e32 v5, vcc, 0, v5, vcc
	global_load_dwordx4 v[44:47], v[2:3], off
	global_load_dwordx4 v[48:51], v[4:5], off
	v_lshl_add_u32 v54, s40, 8, v1
	v_ashrrev_i32_e32 v55, 31, v54
	v_lshl_add_u64 v[140:141], v[138:139], 0, v[52:53]
	v_lshlrev_b64 v[52:53], 11, v[54:55]
	s_mov_b64 s[0:1], 0
	s_mov_b32 s39, 0
	v_mov_b32_e32 v2, 0
	v_mov_b32_e32 v3, v131
	v_mov_b32_e32 v4, v131
	v_mov_b32_e32 v5, v131
	v_mov_b32_e32 v6, 0
	v_mov_b32_e32 v7, v131
	v_mov_b32_e32 v8, v131
	v_mov_b32_e32 v9, v131
	v_mov_b32_e32 v10, 0
	v_mov_b32_e32 v11, v131
	v_mov_b32_e32 v12, v131
	v_mov_b32_e32 v13, v131
	v_mov_b32_e32 v14, 0
	v_mov_b32_e32 v15, v131
	v_mov_b32_e32 v16, v131
	v_mov_b32_e32 v17, v131
	v_mov_b32_e32 v18, 0
	v_lshl_add_u64 v[142:143], v[138:139], 0, v[52:53]
	v_mov_b32_e32 v19, v131
	v_mov_b32_e32 v52, v131
	v_mov_b32_e32 v53, v131
	v_mov_b32_e32 v54, 0
	v_mov_b32_e32 v55, v131
	v_mov_b32_e32 v56, v131
	v_mov_b32_e32 v57, v131
	v_mov_b32_e32 v58, 0
	v_mov_b32_e32 v59, v131
	v_mov_b32_e32 v60, v131
	v_mov_b32_e32 v61, v131
	v_mov_b32_e32 v62, 0
	v_mov_b32_e32 v63, v131
	v_mov_b32_e32 v64, v131
	v_mov_b32_e32 v65, v131
	v_mov_b32_e32 v66, 0
	v_mov_b32_e32 v67, v131
	v_mov_b32_e32 v68, v131
	v_mov_b32_e32 v69, v131
	v_mov_b32_e32 v70, 0
	v_mov_b32_e32 v71, v131
	v_mov_b32_e32 v72, v131
	v_mov_b32_e32 v73, v131
	v_mov_b32_e32 v74, 0
	s_waitcnt vmcnt(7)
	ds_write_b128 v144, v[20:23]
	s_waitcnt vmcnt(6)
	ds_write_b128 v144, v[24:27] offset:8192
	s_waitcnt vmcnt(5)
	ds_write_b128 v144, v[28:31] offset:16384
	s_waitcnt vmcnt(4)
	ds_write_b128 v144, v[32:35] offset:24576
	s_waitcnt vmcnt(3)
	ds_write_b128 v145, v[36:39]
	s_waitcnt vmcnt(2)
	ds_write_b128 v145, v[40:43] offset:8192
	s_waitcnt vmcnt(1)
	ds_write_b128 v145, v[44:47] offset:16384
	s_waitcnt vmcnt(0)
	ds_write_b128 v145, v[48:51] offset:24576
	v_mov_b32_e32 v20, v131
	v_mov_b32_e32 v21, v131
	v_mov_b32_e32 v22, 0
	v_mov_b32_e32 v23, v131
	v_mov_b32_e32 v24, v131
	v_mov_b32_e32 v25, v131
	v_mov_b32_e32 v26, 0
	v_mov_b32_e32 v27, v131
	v_mov_b32_e32 v28, v131
	v_mov_b32_e32 v29, v131
	v_mov_b32_e32 v30, 0
	v_mov_b32_e32 v31, v131
	v_mov_b32_e32 v32, v131
	v_mov_b32_e32 v33, v131
	v_mov_b32_e32 v34, 0
	v_mov_b32_e32 v35, v131
	v_mov_b32_e32 v36, v131
	v_mov_b32_e32 v37, v131
	v_mov_b32_e32 v38, 0
	v_mov_b32_e32 v39, v131
	v_mov_b32_e32 v40, v131
	v_mov_b32_e32 v41, v131
	v_mov_b32_e32 v42, 0
	v_mov_b32_e32 v43, v131
	v_mov_b32_e32 v44, v131
	v_mov_b32_e32 v45, v131
	v_mov_b32_e32 v46, 0
	v_mov_b32_e32 v47, v131
	v_mov_b32_e32 v48, v131
	v_mov_b32_e32 v49, v131
	v_mov_b32_e32 v50, 0
	v_mov_b32_e32 v51, v131
	v_mov_b32_e32 v75, v131
	v_mov_b32_e32 v76, v131
	v_mov_b32_e32 v77, v131
	v_mov_b32_e32 v78, 0
	v_mov_b32_e32 v79, v131
	v_mov_b32_e32 v80, v131
	v_mov_b32_e32 v81, v131
	v_mov_b32_e32 v82, 0
	v_mov_b32_e32 v83, v131
	v_mov_b32_e32 v84, v131
	v_mov_b32_e32 v85, v131
	v_mov_b32_e32 v86, 0
	v_mov_b32_e32 v87, v131
	v_mov_b32_e32 v88, v131
	v_mov_b32_e32 v89, v131
	v_mov_b32_e32 v90, 0
	v_mov_b32_e32 v91, v131
	v_mov_b32_e32 v92, v131
	v_mov_b32_e32 v93, v131
	v_mov_b32_e32 v94, 0
	v_mov_b32_e32 v95, v131
	v_mov_b32_e32 v96, v131
	v_mov_b32_e32 v97, v131
	v_mov_b32_e32 v98, 0
	v_mov_b32_e32 v99, v131
	v_mov_b32_e32 v100, v131
	v_mov_b32_e32 v101, v131
	v_mov_b32_e32 v102, 0
	v_mov_b32_e32 v103, v131
	v_mov_b32_e32 v104, v131
	v_mov_b32_e32 v105, v131
	v_mov_b32_e32 v106, 0
	v_mov_b32_e32 v107, v131
	v_mov_b32_e32 v108, v131
	v_mov_b32_e32 v109, v131
	v_mov_b32_e32 v110, 0
	v_mov_b32_e32 v111, v131
	v_mov_b32_e32 v112, v131
	v_mov_b32_e32 v113, v131
	v_mov_b32_e32 v114, 0
	v_mov_b32_e32 v115, v131
	v_mov_b32_e32 v116, v131
	v_mov_b32_e32 v117, v131
	v_mov_b32_e32 v118, 0
	v_mov_b32_e32 v119, v131
	v_mov_b32_e32 v120, v131
	v_mov_b32_e32 v121, v131
	v_mov_b32_e32 v122, 0
	v_mov_b32_e32 v123, v131
	v_mov_b32_e32 v124, v131
	v_mov_b32_e32 v125, v131
	v_mov_b32_e32 v126, 0
	v_mov_b32_e32 v127, v131
	v_mov_b32_e32 v128, v131
	v_mov_b32_e32 v129, v131
	s_waitcnt lgkmcnt(0)
	s_barrier
	v_lshl_add_u64 v[150:151], v[142:143], 0, s[0:1]
	v_add_co_u32_e32 v152, vcc, s12, v150
	s_nop 1
	v_addc_co_u32_e32 v153, vcc, 0, v151, vcc
	v_add_co_u32_e32 v154, vcc, s13, v150
	s_nop 1
	v_addc_co_u32_e32 v155, vcc, 0, v151, vcc
	v_add_co_u32_e32 v158, vcc, s14, v150
	s_nop 1
	v_addc_co_u32_e32 v159, vcc, 0, v151, vcc
	v_add_co_u32_e32 v162, vcc, s15, v150
	s_nop 1
	v_addc_co_u32_e32 v163, vcc, 0, v151, vcc
	global_load_dwordx4 v[150:153], v[152:153], off offset:128
	global_load_dwordx4 v[154:157], v[154:155], off offset:128
	global_load_dwordx4 v[158:161], v[158:159], off offset:128
	global_load_dwordx4 v[162:165], v[162:163], off offset:128
	v_lshl_add_u64 v[174:175], v[140:141], 0, s[0:1]
	v_add_co_u32_e32 v166, vcc, s16, v174
	s_nop 1
	v_addc_co_u32_e32 v167, vcc, 0, v175, vcc
	v_add_co_u32_e32 v170, vcc, s17, v174
	s_nop 1
	v_addc_co_u32_e32 v171, vcc, 0, v175, vcc
	v_add_co_u32_e32 v176, vcc, s28, v174
	s_nop 1
	v_addc_co_u32_e32 v177, vcc, 0, v175, vcc
	v_add_co_u32_e32 v178, vcc, s29, v174
	s_nop 1
	v_addc_co_u32_e32 v179, vcc, 0, v175, vcc
	global_load_dwordx4 v[166:169], v[166:167], off offset:128
	global_load_dwordx4 v[170:173], v[170:171], off offset:128
	global_load_dwordx4 v[174:177], v[176:177], off offset:128
	global_load_dwordx4 v[178:181], v[178:179], off offset:128
	v_mov_b32_e32 v214, v146
	v_mov_b32_e32 v215, v216
	v_mov_b32_e32 v223, v147
	v_mov_b32_e32 v252, v217
	v_xor_b32_e32 v253, 0x8000, v144
	v_xor_b32_e32 v254, 0x8000, v145
	ds_read_b128 v[182:185], v214
	ds_read_b128 v[186:189], v214 offset:2048
	ds_read_b128 v[190:193], v214 offset:4096
	ds_read_b128 v[194:197], v214 offset:6144
	ds_read_b128 v[218:221], v223
	ds_read_b128 v[224:227], v223 offset:2048
	ds_read_b128 v[228:231], v223 offset:4096
	ds_read_b128 v[232:235], v223 offset:6144
.Lg2_p6_loop:
	ds_read_b128 v[198:201], v214 offset:8192
	ds_read_b128 v[202:205], v214 offset:10240
	ds_read_b128 v[206:209], v214 offset:12288
	ds_read_b128 v[210:213], v214 offset:14336
	s_waitcnt lgkmcnt(4)
	v_mfma_f32_16x16x32_bf16 v[126:129], v[218:221], v[182:185], v[126:129]
	v_mfma_f32_16x16x32_bf16 v[122:125], v[224:227], v[182:185], v[122:125]
	v_mfma_f32_16x16x32_bf16 v[118:121], v[228:231], v[182:185], v[118:121]
	v_mfma_f32_16x16x32_bf16 v[114:117], v[232:235], v[182:185], v[114:117]
	v_mfma_f32_16x16x32_bf16 v[110:113], v[218:221], v[186:189], v[110:113]
	v_mfma_f32_16x16x32_bf16 v[106:109], v[224:227], v[186:189], v[106:109]
	v_mfma_f32_16x16x32_bf16 v[102:105], v[228:231], v[186:189], v[102:105]
	v_mfma_f32_16x16x32_bf16 v[98:101], v[232:235], v[186:189], v[98:101]
	v_mfma_f32_16x16x32_bf16 v[94:97], v[218:221], v[190:193], v[94:97]
	v_mfma_f32_16x16x32_bf16 v[90:93], v[224:227], v[190:193], v[90:93]
	v_mfma_f32_16x16x32_bf16 v[86:89], v[228:231], v[190:193], v[86:89]
	v_mfma_f32_16x16x32_bf16 v[82:85], v[232:235], v[190:193], v[82:85]
	v_mfma_f32_16x16x32_bf16 v[78:81], v[218:221], v[194:197], v[78:81]
	v_mfma_f32_16x16x32_bf16 v[74:77], v[224:227], v[194:197], v[74:77]
	v_mfma_f32_16x16x32_bf16 v[70:73], v[228:231], v[194:197], v[70:73]
	v_mfma_f32_16x16x32_bf16 v[66:69], v[232:235], v[194:197], v[66:69]
	ds_read_b128 v[182:185], v215
	ds_read_b128 v[186:189], v215 offset:2048
	ds_read_b128 v[190:193], v215 offset:4096
	ds_read_b128 v[194:197], v215 offset:6144
	ds_read_b128 v[236:239], v252
	ds_read_b128 v[240:243], v252 offset:2048
	ds_read_b128 v[244:247], v252 offset:4096
	ds_read_b128 v[248:251], v252 offset:6144
	s_waitcnt lgkmcnt(8)
	v_mfma_f32_16x16x32_bf16 v[62:65], v[218:221], v[198:201], v[62:65]
	v_mfma_f32_16x16x32_bf16 v[58:61], v[224:227], v[198:201], v[58:61]
	v_mfma_f32_16x16x32_bf16 v[54:57], v[228:231], v[198:201], v[54:57]
	v_mfma_f32_16x16x32_bf16 v[50:53], v[232:235], v[198:201], v[50:53]
	v_mfma_f32_16x16x32_bf16 v[46:49], v[218:221], v[202:205], v[46:49]
	v_mfma_f32_16x16x32_bf16 v[42:45], v[224:227], v[202:205], v[42:45]
	v_mfma_f32_16x16x32_bf16 v[38:41], v[228:231], v[202:205], v[38:41]
	v_mfma_f32_16x16x32_bf16 v[34:37], v[232:235], v[202:205], v[34:37]
	v_mfma_f32_16x16x32_bf16 v[30:33], v[218:221], v[206:209], v[30:33]
	v_mfma_f32_16x16x32_bf16 v[26:29], v[224:227], v[206:209], v[26:29]
	v_mfma_f32_16x16x32_bf16 v[22:25], v[228:231], v[206:209], v[22:25]
	v_mfma_f32_16x16x32_bf16 v[18:21], v[232:235], v[206:209], v[18:21]
	v_mfma_f32_16x16x32_bf16 v[14:17], v[218:221], v[210:213], v[14:17]
	v_mfma_f32_16x16x32_bf16 v[10:13], v[224:227], v[210:213], v[10:13]
	v_mfma_f32_16x16x32_bf16 v[6:9], v[228:231], v[210:213], v[6:9]
	v_mfma_f32_16x16x32_bf16 v[2:5], v[232:235], v[210:213], v[2:5]
	ds_read_b128 v[198:201], v215 offset:8192
	ds_read_b128 v[202:205], v215 offset:10240
	ds_read_b128 v[206:209], v215 offset:12288
	ds_read_b128 v[210:213], v215 offset:14336
	s_waitcnt lgkmcnt(4)
	v_mfma_f32_16x16x32_bf16 v[126:129], v[236:239], v[182:185], v[126:129]
	v_mfma_f32_16x16x32_bf16 v[122:125], v[240:243], v[182:185], v[122:125]
	s_waitcnt vmcnt(7)
	ds_write_b128 v253, v[150:153]
	v_mfma_f32_16x16x32_bf16 v[118:121], v[244:247], v[182:185], v[118:121]
	v_mfma_f32_16x16x32_bf16 v[114:117], v[248:251], v[182:185], v[114:117]
	s_waitcnt vmcnt(6)
	ds_write_b128 v253, v[154:157] offset:8192
	v_mfma_f32_16x16x32_bf16 v[110:113], v[236:239], v[186:189], v[110:113]
	v_mfma_f32_16x16x32_bf16 v[106:109], v[240:243], v[186:189], v[106:109]
	s_waitcnt vmcnt(5)
	ds_write_b128 v253, v[158:161] offset:16384
	v_mfma_f32_16x16x32_bf16 v[102:105], v[244:247], v[186:189], v[102:105]
	v_mfma_f32_16x16x32_bf16 v[98:101], v[248:251], v[186:189], v[98:101]
	s_waitcnt vmcnt(4)
	ds_write_b128 v253, v[162:165] offset:24576
	v_mfma_f32_16x16x32_bf16 v[94:97], v[236:239], v[190:193], v[94:97]
	v_mfma_f32_16x16x32_bf16 v[90:93], v[240:243], v[190:193], v[90:93]
	s_waitcnt vmcnt(3)
	ds_write_b128 v254, v[166:169]
	v_mfma_f32_16x16x32_bf16 v[86:89], v[244:247], v[190:193], v[86:89]
	v_mfma_f32_16x16x32_bf16 v[82:85], v[248:251], v[190:193], v[82:85]
	s_waitcnt vmcnt(2)
	ds_write_b128 v254, v[170:173] offset:8192
	v_mfma_f32_16x16x32_bf16 v[78:81], v[236:239], v[194:197], v[78:81]
	v_mfma_f32_16x16x32_bf16 v[74:77], v[240:243], v[194:197], v[74:77]
	s_waitcnt vmcnt(1)
	ds_write_b128 v254, v[174:177] offset:16384
	v_mfma_f32_16x16x32_bf16 v[70:73], v[244:247], v[194:197], v[70:73]
	v_mfma_f32_16x16x32_bf16 v[66:69], v[248:251], v[194:197], v[66:69]
	s_waitcnt vmcnt(0)
	ds_write_b128 v254, v[178:181] offset:24576
	s_waitcnt lgkmcnt(0)
	s_barrier
	s_add_u32 s0, s0, 0x80
	s_addc_u32 s1, s1, 0
	s_cmpk_eq_i32 s0, 0x780
	s_cbranch_scc1 .Lg2_p6_tail
	v_xor_b32_e32 v214, 0x8000, v214
	v_xor_b32_e32 v223, 0x8000, v223
	v_xor_b32_e32 v215, 0x8000, v215
	v_xor_b32_e32 v252, 0x8000, v252
	v_xor_b32_e32 v253, 0x8000, v253
	v_xor_b32_e32 v254, 0x8000, v254
	ds_read_b128 v[182:185], v214
	ds_read_b128 v[186:189], v214 offset:2048
	ds_read_b128 v[190:193], v214 offset:4096
	ds_read_b128 v[194:197], v214 offset:6144
	ds_read_b128 v[218:221], v223
	ds_read_b128 v[224:227], v223 offset:2048
	ds_read_b128 v[228:231], v223 offset:4096
	ds_read_b128 v[232:235], v223 offset:6144
	v_mfma_f32_16x16x32_bf16 v[62:65], v[236:239], v[198:201], v[62:65]
	v_lshl_add_u64 v[150:151], v[142:143], 0, s[0:1]
	v_add_co_u32_e32 v152, vcc, s12, v150
	v_mfma_f32_16x16x32_bf16 v[58:61], v[240:243], v[198:201], v[58:61]
	s_nop 1
	v_addc_co_u32_e32 v153, vcc, 0, v151, vcc
	v_mfma_f32_16x16x32_bf16 v[54:57], v[244:247], v[198:201], v[54:57]
	v_add_co_u32_e32 v154, vcc, s13, v150
	s_nop 1
	v_mfma_f32_16x16x32_bf16 v[50:53], v[248:251], v[198:201], v[50:53]
	v_addc_co_u32_e32 v155, vcc, 0, v151, vcc
	v_add_co_u32_e32 v158, vcc, s14, v150
	v_mfma_f32_16x16x32_bf16 v[46:49], v[236:239], v[202:205], v[46:49]
	s_nop 1
	v_addc_co_u32_e32 v159, vcc, 0, v151, vcc
	v_mfma_f32_16x16x32_bf16 v[42:45], v[240:243], v[202:205], v[42:45]
	v_add_co_u32_e32 v162, vcc, s15, v150
	s_nop 1
	v_mfma_f32_16x16x32_bf16 v[38:41], v[244:247], v[202:205], v[38:41]
	v_addc_co_u32_e32 v163, vcc, 0, v151, vcc
	global_load_dwordx4 v[150:153], v[152:153], off offset:128
	v_mfma_f32_16x16x32_bf16 v[34:37], v[248:251], v[202:205], v[34:37]
	global_load_dwordx4 v[154:157], v[154:155], off offset:128
	global_load_dwordx4 v[158:161], v[158:159], off offset:128
	global_load_dwordx4 v[162:165], v[162:163], off offset:128
	v_mfma_f32_16x16x32_bf16 v[30:33], v[236:239], v[206:209], v[30:33]
	v_lshl_add_u64 v[174:175], v[140:141], 0, s[0:1]
	v_add_co_u32_e32 v166, vcc, s16, v174
	v_mfma_f32_16x16x32_bf16 v[26:29], v[240:243], v[206:209], v[26:29]
	s_nop 1
	v_addc_co_u32_e32 v167, vcc, 0, v175, vcc
	v_mfma_f32_16x16x32_bf16 v[22:25], v[244:247], v[206:209], v[22:25]
	v_add_co_u32_e32 v170, vcc, s17, v174
	s_nop 1
	v_mfma_f32_16x16x32_bf16 v[18:21], v[248:251], v[206:209], v[18:21]
	v_addc_co_u32_e32 v171, vcc, 0, v175, vcc
	v_add_co_u32_e32 v176, vcc, s28, v174
	v_mfma_f32_16x16x32_bf16 v[14:17], v[236:239], v[210:213], v[14:17]
	s_nop 1
	v_addc_co_u32_e32 v177, vcc, 0, v175, vcc
	v_mfma_f32_16x16x32_bf16 v[10:13], v[240:243], v[210:213], v[10:13]
	v_add_co_u32_e32 v178, vcc, s29, v174
	s_nop 1
	v_mfma_f32_16x16x32_bf16 v[6:9], v[244:247], v[210:213], v[6:9]
	v_addc_co_u32_e32 v179, vcc, 0, v175, vcc
	global_load_dwordx4 v[166:169], v[166:167], off offset:128
	v_mfma_f32_16x16x32_bf16 v[2:5], v[248:251], v[210:213], v[2:5]
	global_load_dwordx4 v[170:173], v[170:171], off offset:128
	global_load_dwordx4 v[174:177], v[176:177], off offset:128
	global_load_dwordx4 v[178:181], v[178:179], off offset:128
	s_branch .Lg2_p6_loop
.Lg2_p6_tail:
	v_mfma_f32_16x16x32_bf16 v[62:65], v[236:239], v[198:201], v[62:65]
	v_mfma_f32_16x16x32_bf16 v[58:61], v[240:243], v[198:201], v[58:61]
	v_mfma_f32_16x16x32_bf16 v[54:57], v[244:247], v[198:201], v[54:57]
	v_mfma_f32_16x16x32_bf16 v[50:53], v[248:251], v[198:201], v[50:53]
	v_mfma_f32_16x16x32_bf16 v[46:49], v[236:239], v[202:205], v[46:49]
	v_mfma_f32_16x16x32_bf16 v[42:45], v[240:243], v[202:205], v[42:45]
	v_mfma_f32_16x16x32_bf16 v[38:41], v[244:247], v[202:205], v[38:41]
	v_mfma_f32_16x16x32_bf16 v[34:37], v[248:251], v[202:205], v[34:37]
	v_mfma_f32_16x16x32_bf16 v[30:33], v[236:239], v[206:209], v[30:33]
	v_mfma_f32_16x16x32_bf16 v[26:29], v[240:243], v[206:209], v[26:29]
	v_mfma_f32_16x16x32_bf16 v[22:25], v[244:247], v[206:209], v[22:25]
	v_mfma_f32_16x16x32_bf16 v[18:21], v[248:251], v[206:209], v[18:21]
	v_mfma_f32_16x16x32_bf16 v[14:17], v[236:239], v[210:213], v[14:17]
	v_mfma_f32_16x16x32_bf16 v[10:13], v[240:243], v[210:213], v[10:13]
	v_mfma_f32_16x16x32_bf16 v[6:9], v[244:247], v[210:213], v[6:9]
	v_mfma_f32_16x16x32_bf16 v[2:5], v[248:251], v[210:213], v[2:5]
	ds_read_b128 v[140:143], v147 offset:32768
	ds_read_b128 v[150:153], v147 offset:34816
	ds_read_b128 v[154:157], v147 offset:36864
	ds_read_b128 v[158:161], v147 offset:38912
	ds_read_b128 v[162:165], v146 offset:32768
	ds_read_b128 v[166:169], v146 offset:34816
	ds_read_b128 v[170:173], v146 offset:36864
	ds_read_b128 v[174:177], v146 offset:38912
	s_setprio 1
	s_waitcnt lgkmcnt(3)
	v_mfma_f32_16x16x32_bf16 v[126:129], v[140:143], v[162:165], v[126:129]
	v_mfma_f32_16x16x32_bf16 v[122:125], v[150:153], v[162:165], v[122:125]
	v_mfma_f32_16x16x32_bf16 v[118:121], v[154:157], v[162:165], v[118:121]
	v_mfma_f32_16x16x32_bf16 v[114:117], v[158:161], v[162:165], v[114:117]
	s_waitcnt lgkmcnt(2)
	v_mfma_f32_16x16x32_bf16 v[110:113], v[140:143], v[166:169], v[110:113]
	v_mfma_f32_16x16x32_bf16 v[106:109], v[150:153], v[166:169], v[106:109]
	v_mfma_f32_16x16x32_bf16 v[102:105], v[154:157], v[166:169], v[102:105]
	v_mfma_f32_16x16x32_bf16 v[98:101], v[158:161], v[166:169], v[98:101]
	s_waitcnt lgkmcnt(1)
	v_mfma_f32_16x16x32_bf16 v[94:97], v[140:143], v[170:173], v[94:97]
	v_mfma_f32_16x16x32_bf16 v[90:93], v[150:153], v[170:173], v[90:93]
	v_mfma_f32_16x16x32_bf16 v[86:89], v[154:157], v[170:173], v[86:89]
	v_mfma_f32_16x16x32_bf16 v[82:85], v[158:161], v[170:173], v[82:85]
	s_waitcnt lgkmcnt(0)
	v_mfma_f32_16x16x32_bf16 v[78:81], v[140:143], v[174:177], v[78:81]
	v_mfma_f32_16x16x32_bf16 v[74:77], v[150:153], v[174:177], v[74:77]
	v_mfma_f32_16x16x32_bf16 v[70:73], v[154:157], v[174:177], v[70:73]
	v_mfma_f32_16x16x32_bf16 v[66:69], v[158:161], v[174:177], v[66:69]
	s_setprio 0
	ds_read_b128 v[162:165], v146 offset:40960
	ds_read_b128 v[166:169], v146 offset:43008
	ds_read_b128 v[170:173], v146 offset:45056
	ds_read_b128 v[174:177], v146 offset:47104
	s_setprio 1
	s_waitcnt lgkmcnt(3)
	v_mfma_f32_16x16x32_bf16 v[62:65], v[140:143], v[162:165], v[62:65]
	v_mfma_f32_16x16x32_bf16 v[58:61], v[150:153], v[162:165], v[58:61]
	v_mfma_f32_16x16x32_bf16 v[54:57], v[154:157], v[162:165], v[54:57]
	v_mfma_f32_16x16x32_bf16 v[50:53], v[158:161], v[162:165], v[50:53]
	s_waitcnt lgkmcnt(2)
	v_mfma_f32_16x16x32_bf16 v[46:49], v[140:143], v[166:169], v[46:49]
	v_mfma_f32_16x16x32_bf16 v[42:45], v[150:153], v[166:169], v[42:45]
	v_mfma_f32_16x16x32_bf16 v[38:41], v[154:157], v[166:169], v[38:41]
	v_mfma_f32_16x16x32_bf16 v[34:37], v[158:161], v[166:169], v[34:37]
	s_waitcnt lgkmcnt(1)
	v_mfma_f32_16x16x32_bf16 v[30:33], v[140:143], v[170:173], v[30:33]
	v_mfma_f32_16x16x32_bf16 v[26:29], v[150:153], v[170:173], v[26:29]
	v_mfma_f32_16x16x32_bf16 v[22:25], v[154:157], v[170:173], v[22:25]
	v_mfma_f32_16x16x32_bf16 v[18:21], v[158:161], v[170:173], v[18:21]
	s_waitcnt lgkmcnt(0)
	v_mfma_f32_16x16x32_bf16 v[14:17], v[140:143], v[174:177], v[14:17]
	v_mfma_f32_16x16x32_bf16 v[10:13], v[150:153], v[174:177], v[10:13]
	v_mfma_f32_16x16x32_bf16 v[6:9], v[154:157], v[174:177], v[6:9]
	v_mfma_f32_16x16x32_bf16 v[2:5], v[158:161], v[174:177], v[2:5]
	s_setprio 0
	ds_read_b128 v[140:143], v217 offset:32768
	ds_read_b128 v[150:153], v217 offset:34816
	ds_read_b128 v[154:157], v217 offset:36864
	ds_read_b128 v[158:161], v217 offset:38912
	ds_read_b128 v[162:165], v216 offset:32768
	ds_read_b128 v[166:169], v216 offset:34816
	ds_read_b128 v[170:173], v216 offset:36864
	ds_read_b128 v[174:177], v216 offset:38912
	s_setprio 1
	s_waitcnt lgkmcnt(3)
	v_mfma_f32_16x16x32_bf16 v[126:129], v[140:143], v[162:165], v[126:129]
	v_mfma_f32_16x16x32_bf16 v[122:125], v[150:153], v[162:165], v[122:125]
	v_mfma_f32_16x16x32_bf16 v[118:121], v[154:157], v[162:165], v[118:121]
	v_mfma_f32_16x16x32_bf16 v[114:117], v[158:161], v[162:165], v[114:117]
	s_waitcnt lgkmcnt(2)
	v_mfma_f32_16x16x32_bf16 v[110:113], v[140:143], v[166:169], v[110:113]
	v_mfma_f32_16x16x32_bf16 v[106:109], v[150:153], v[166:169], v[106:109]
	v_mfma_f32_16x16x32_bf16 v[102:105], v[154:157], v[166:169], v[102:105]
	v_mfma_f32_16x16x32_bf16 v[98:101], v[158:161], v[166:169], v[98:101]
	s_waitcnt lgkmcnt(1)
	v_mfma_f32_16x16x32_bf16 v[94:97], v[140:143], v[170:173], v[94:97]
	v_mfma_f32_16x16x32_bf16 v[162:165], v[150:153], v[170:173], v[90:93]
	v_mfma_f32_16x16x32_bf16 v[86:89], v[154:157], v[170:173], v[86:89]
	v_mfma_f32_16x16x32_bf16 v[82:85], v[158:161], v[170:173], v[82:85]
	s_waitcnt lgkmcnt(0)
	v_mfma_f32_16x16x32_bf16 v[78:81], v[140:143], v[174:177], v[78:81]
	v_mfma_f32_16x16x32_bf16 v[74:77], v[150:153], v[174:177], v[74:77]
	v_mfma_f32_16x16x32_bf16 v[70:73], v[154:157], v[174:177], v[70:73]
	v_mfma_f32_16x16x32_bf16 v[66:69], v[158:161], v[174:177], v[66:69]
	s_setprio 0
	ds_read_b128 v[90:93], v216 offset:40960
	ds_read_b128 v[166:169], v216 offset:43008
	ds_read_b128 v[170:173], v216 offset:45056
	ds_read_b128 v[174:177], v216 offset:47104
	s_setprio 1
	s_waitcnt lgkmcnt(3)
	v_mfma_f32_16x16x32_bf16 v[62:65], v[140:143], v[90:93], v[62:65]
	v_mfma_f32_16x16x32_bf16 v[58:61], v[150:153], v[90:93], v[58:61]
	v_mfma_f32_16x16x32_bf16 v[54:57], v[154:157], v[90:93], v[54:57]
	v_mfma_f32_16x16x32_bf16 v[50:53], v[158:161], v[90:93], v[50:53]
	s_waitcnt lgkmcnt(2)
	v_mfma_f32_16x16x32_bf16 v[46:49], v[140:143], v[166:169], v[46:49]
	v_mfma_f32_16x16x32_bf16 v[42:45], v[150:153], v[166:169], v[42:45]
	v_mfma_f32_16x16x32_bf16 v[38:41], v[154:157], v[166:169], v[38:41]
	v_mfma_f32_16x16x32_bf16 v[34:37], v[158:161], v[166:169], v[34:37]
	s_waitcnt lgkmcnt(1)
	v_mfma_f32_16x16x32_bf16 v[30:33], v[140:143], v[170:173], v[30:33]
	v_mfma_f32_16x16x32_bf16 v[26:29], v[150:153], v[170:173], v[26:29]
	v_mfma_f32_16x16x32_bf16 v[22:25], v[154:157], v[170:173], v[22:25]
	v_mfma_f32_16x16x32_bf16 v[18:21], v[158:161], v[170:173], v[18:21]
	s_waitcnt lgkmcnt(0)
	v_mfma_f32_16x16x32_bf16 v[14:17], v[140:143], v[174:177], v[14:17]
	v_mfma_f32_16x16x32_bf16 v[10:13], v[150:153], v[174:177], v[10:13]
	v_mfma_f32_16x16x32_bf16 v[6:9], v[154:157], v[174:177], v[6:9]
	v_mfma_f32_16x16x32_bf16 v[2:5], v[158:161], v[174:177], v[2:5]
	s_setprio 0
	v_mul_f32_e32 v93, 0xbfb8aa3b, v126
	v_exp_f32_e32 v93, v93
	v_mul_f32_e32 v130, 0xbfb8aa3b, v127
	v_exp_f32_e32 v130, v130
	v_mul_f32_e32 v141, 0xbfb8aa3b, v129
	v_add_f32_e32 v93, 1.0, v93
	v_rcp_f32_e32 v140, v93
	v_add_f32_e32 v93, 1.0, v130
	v_mul_f32_e32 v130, 0xbfb8aa3b, v128
	v_exp_f32_e32 v130, v130
	v_exp_f32_e32 v143, v141
	v_rcp_f32_e32 v141, v93
	v_or_b32_e32 v90, s38, v148
	v_add_f32_e32 v93, 1.0, v130
	v_rcp_f32_e32 v142, v93
	v_add_f32_e32 v93, 1.0, v143
	v_rcp_f32_e32 v143, v93
	v_pk_mul_f32 v[126:127], v[126:127], v[140:141]
	v_mul_f32_e32 v93, 0xbfb8aa3b, v118
	v_pk_mul_f32 v[122:123], v[122:123], v[126:127]
	v_pk_mul_f32 v[126:127], v[128:129], v[142:143]
	v_cvt_pk_bf16_f32 v122, v122, v123
	v_exp_f32_e32 v93, v93
	v_mul_f32_e32 v123, 0xbfb8aa3b, v119
	v_pk_mul_f32 v[124:125], v[124:125], v[126:127]
	v_exp_f32_e32 v126, v123
	v_cvt_pk_bf16_f32 v123, v124, v125
	v_add_f32_e32 v93, 1.0, v93
	v_mul_f32_e32 v125, 0xbfb8aa3b, v120
	v_rcp_f32_e32 v124, v93
	v_add_f32_e32 v93, 1.0, v126
	v_exp_f32_e32 v126, v125
	v_mul_f32_e32 v125, 0xbfb8aa3b, v121
	v_exp_f32_e32 v127, v125
	v_rcp_f32_e32 v125, v93
	v_add_f32_e32 v93, 1.0, v126
	v_rcp_f32_e32 v126, v93
	v_add_f32_e32 v93, 1.0, v127
	v_rcp_f32_e32 v127, v93
	v_ashrrev_i32_e32 v90, 1, v90
	v_pk_mul_f32 v[118:119], v[118:119], v[124:125]
	v_ashrrev_i32_e32 v91, 31, v90
	v_pk_mul_f32 v[114:115], v[114:115], v[118:119]
	v_pk_mul_f32 v[118:119], v[120:121], v[126:127]
	v_add_u32_e32 v92, s37, v149
	v_lshl_add_u64 v[90:91], v[90:91], 1, v[136:137]
	v_pk_mul_f32 v[116:117], v[116:117], v[118:119]
	v_mad_i64_i32 v[150:151], s[0:1], v92, s36, v[90:91]
	v_cvt_pk_bf16_f32 v114, v114, v115
	v_cvt_pk_bf16_f32 v115, v116, v117
	v_mul_f32_e32 v93, 0xbfb8aa3b, v110
	s_barrier
	global_store_dwordx2 v[150:151], v[114:115], off offset:32
	v_exp_f32_e32 v93, v93
	v_mul_f32_e32 v114, 0xbfb8aa3b, v111
	v_exp_f32_e32 v115, v114
	v_or_b32_e32 v118, 16, v92
	v_add_f32_e32 v93, 1.0, v93
	v_rcp_f32_e32 v114, v93
	v_add_f32_e32 v93, 1.0, v115
	v_mul_f32_e32 v115, 0xbfb8aa3b, v112
	v_exp_f32_e32 v116, v115
	v_mul_f32_e32 v115, 0xbfb8aa3b, v113
	v_exp_f32_e32 v117, v115
	v_rcp_f32_e32 v115, v93
	v_add_f32_e32 v93, 1.0, v116
	v_rcp_f32_e32 v116, v93
	v_add_f32_e32 v93, 1.0, v117
	v_rcp_f32_e32 v117, v93
	v_pk_mul_f32 v[110:111], v[110:111], v[114:115]
	v_mul_f32_e32 v93, 0xbfb8aa3b, v102
	v_pk_mul_f32 v[106:107], v[106:107], v[110:111]
	v_pk_mul_f32 v[110:111], v[112:113], v[116:117]
	v_cvt_pk_bf16_f32 v106, v106, v107
	v_exp_f32_e32 v93, v93
	v_mul_f32_e32 v107, 0xbfb8aa3b, v103
	v_pk_mul_f32 v[108:109], v[108:109], v[110:111]
	v_exp_f32_e32 v110, v107
	v_cvt_pk_bf16_f32 v107, v108, v109
	v_add_f32_e32 v93, 1.0, v93
	v_mul_f32_e32 v109, 0xbfb8aa3b, v104
	v_rcp_f32_e32 v108, v93
	v_add_f32_e32 v93, 1.0, v110
	v_exp_f32_e32 v110, v109
	v_mul_f32_e32 v109, 0xbfb8aa3b, v105
	v_exp_f32_e32 v111, v109
	v_rcp_f32_e32 v109, v93
	v_add_f32_e32 v93, 1.0, v110
	v_rcp_f32_e32 v110, v93
	v_add_f32_e32 v93, 1.0, v111
	v_rcp_f32_e32 v111, v93
	v_pk_mul_f32 v[102:103], v[102:103], v[108:109]
	v_mad_i64_i32 v[118:119], s[0:1], v118, s36, v[90:91]
	v_pk_mul_f32 v[98:99], v[98:99], v[102:103]
	v_pk_mul_f32 v[102:103], v[104:105], v[110:111]
	v_cvt_pk_bf16_f32 v98, v98, v99
	v_pk_mul_f32 v[100:101], v[100:101], v[102:103]
	v_mul_f32_e32 v93, 0xbfb8aa3b, v94
	v_cvt_pk_bf16_f32 v99, v100, v101
	global_store_dwordx2 v[118:119], v[98:99], off offset:32
	v_exp_f32_e32 v93, v93
	v_mul_f32_e32 v98, 0xbfb8aa3b, v95
	v_exp_f32_e32 v99, v98
	v_or_b32_e32 v102, 32, v92
	v_add_f32_e32 v93, 1.0, v93
	v_rcp_f32_e32 v98, v93
	v_add_f32_e32 v93, 1.0, v99
	v_mul_f32_e32 v99, 0xbfb8aa3b, v96
	v_exp_f32_e32 v100, v99
	v_mul_f32_e32 v99, 0xbfb8aa3b, v97
	v_exp_f32_e32 v101, v99
	v_rcp_f32_e32 v99, v93
	v_add_f32_e32 v93, 1.0, v100
	v_rcp_f32_e32 v100, v93
	v_add_f32_e32 v93, 1.0, v101
	v_rcp_f32_e32 v101, v93
	v_pk_mul_f32 v[94:95], v[94:95], v[98:99]
	v_mul_f32_e32 v93, 0xbfb8aa3b, v86
	v_pk_mul_f32 v[94:95], v[162:163], v[94:95]
	v_exp_f32_e32 v93, v93
	v_cvt_pk_bf16_f32 v94, v94, v95
	v_mul_f32_e32 v95, 0xbfb8aa3b, v87
	v_exp_f32_e32 v98, v95
	v_pk_mul_f32 v[96:97], v[96:97], v[100:101]
	v_add_f32_e32 v93, 1.0, v93
	v_pk_mul_f32 v[96:97], v[164:165], v[96:97]
	v_mad_i64_i32 v[102:103], s[0:1], v102, s36, v[90:91]
	v_cvt_pk_bf16_f32 v95, v96, v97
	v_mul_f32_e32 v97, 0xbfb8aa3b, v88
	v_rcp_f32_e32 v96, v93
	v_add_f32_e32 v93, 1.0, v98
	v_exp_f32_e32 v98, v97
	v_mul_f32_e32 v97, 0xbfb8aa3b, v89
	v_exp_f32_e32 v99, v97
	v_rcp_f32_e32 v97, v93
	v_add_f32_e32 v93, 1.0, v98
	v_rcp_f32_e32 v98, v93
	v_add_f32_e32 v93, 1.0, v99
	v_rcp_f32_e32 v99, v93
	v_pk_mul_f32 v[86:87], v[86:87], v[96:97]
	s_add_i32 s3, s3, s7
	v_pk_mul_f32 v[82:83], v[82:83], v[86:87]
	v_pk_mul_f32 v[86:87], v[88:89], v[98:99]
	v_cvt_pk_bf16_f32 v82, v82, v83
	v_pk_mul_f32 v[84:85], v[84:85], v[86:87]
	v_or_b32_e32 v86, 48, v92
	v_cvt_pk_bf16_f32 v83, v84, v85
	global_store_dwordx2 v[102:103], v[82:83], off offset:32
	v_mul_f32_e32 v82, 0xbfb8aa3b, v78
	v_mul_f32_e32 v83, 0xbfb8aa3b, v79
	v_exp_f32_e32 v82, v82
	v_exp_f32_e32 v83, v83
	v_mul_f32_e32 v84, 0xbfb8aa3b, v80
	v_mul_f32_e32 v85, 0xbfb8aa3b, v81
	v_exp_f32_e32 v84, v84
	v_exp_f32_e32 v85, v85
	v_add_f32_e32 v82, 1.0, v82
	v_add_f32_e32 v83, 1.0, v83
	v_rcp_f32_e32 v82, v82
	v_rcp_f32_e32 v83, v83
	v_add_f32_e32 v84, 1.0, v84
	v_add_f32_e32 v85, 1.0, v85
	v_rcp_f32_e32 v84, v84
	v_rcp_f32_e32 v85, v85
	v_pk_mul_f32 v[78:79], v[78:79], v[82:83]
	v_mad_i64_i32 v[86:87], s[0:1], v86, s36, v[90:91]
	v_pk_mul_f32 v[74:75], v[74:75], v[78:79]
	v_pk_mul_f32 v[78:79], v[80:81], v[84:85]
	v_cvt_pk_bf16_f32 v74, v74, v75
	v_mul_f32_e32 v75, 0xbfb8aa3b, v70
	v_pk_mul_f32 v[76:77], v[76:77], v[78:79]
	v_exp_f32_e32 v78, v75
	v_mul_f32_e32 v75, 0xbfb8aa3b, v71
	v_exp_f32_e32 v79, v75
	v_cvt_pk_bf16_f32 v75, v76, v77
	v_add_f32_e32 v76, 1.0, v78
	v_mul_f32_e32 v78, 0xbfb8aa3b, v72
	v_add_f32_e32 v77, 1.0, v79
	v_mul_f32_e32 v79, 0xbfb8aa3b, v73
	v_exp_f32_e32 v78, v78
	v_exp_f32_e32 v79, v79
	v_rcp_f32_e32 v76, v76
	v_rcp_f32_e32 v77, v77
	v_add_f32_e32 v78, 1.0, v78
	v_add_f32_e32 v79, 1.0, v79
	v_rcp_f32_e32 v78, v78
	v_rcp_f32_e32 v79, v79
	v_pk_mul_f32 v[70:71], v[70:71], v[76:77]
	s_add_i32 s8, s8, s7
	v_pk_mul_f32 v[66:67], v[66:67], v[70:71]
	v_pk_mul_f32 v[70:71], v[72:73], v[78:79]
	v_cvt_pk_bf16_f32 v66, v66, v67
	v_pk_mul_f32 v[68:69], v[68:69], v[70:71]
	v_or_b32_e32 v70, 64, v92
	v_cvt_pk_bf16_f32 v67, v68, v69
	global_store_dwordx2 v[86:87], v[66:67], off offset:32
	v_mul_f32_e32 v66, 0xbfb8aa3b, v62
	v_mul_f32_e32 v67, 0xbfb8aa3b, v63
	v_exp_f32_e32 v66, v66
	v_exp_f32_e32 v67, v67
	v_mul_f32_e32 v68, 0xbfb8aa3b, v64
	v_mul_f32_e32 v69, 0xbfb8aa3b, v65
	v_exp_f32_e32 v68, v68
	v_exp_f32_e32 v69, v69
	v_add_f32_e32 v66, 1.0, v66
	v_add_f32_e32 v67, 1.0, v67
	v_rcp_f32_e32 v66, v66
	v_rcp_f32_e32 v67, v67
	v_add_f32_e32 v68, 1.0, v68
	v_add_f32_e32 v69, 1.0, v69
	v_rcp_f32_e32 v68, v68
	v_rcp_f32_e32 v69, v69
	v_pk_mul_f32 v[62:63], v[62:63], v[66:67]
	v_mad_i64_i32 v[70:71], s[0:1], v70, s36, v[90:91]
	v_pk_mul_f32 v[58:59], v[58:59], v[62:63]
	v_pk_mul_f32 v[62:63], v[64:65], v[68:69]
	v_cvt_pk_bf16_f32 v58, v58, v59
	v_mul_f32_e32 v59, 0xbfb8aa3b, v54
	v_pk_mul_f32 v[60:61], v[60:61], v[62:63]
	v_exp_f32_e32 v62, v59
	v_mul_f32_e32 v59, 0xbfb8aa3b, v55
	v_exp_f32_e32 v63, v59
	v_cvt_pk_bf16_f32 v59, v60, v61
	v_add_f32_e32 v60, 1.0, v62
	v_mul_f32_e32 v62, 0xbfb8aa3b, v56
	v_add_f32_e32 v61, 1.0, v63
	v_mul_f32_e32 v63, 0xbfb8aa3b, v57
	v_exp_f32_e32 v62, v62
	v_exp_f32_e32 v63, v63
	v_rcp_f32_e32 v60, v60
	v_rcp_f32_e32 v61, v61
	v_add_f32_e32 v62, 1.0, v62
	v_add_f32_e32 v63, 1.0, v63
	v_rcp_f32_e32 v62, v62
	v_rcp_f32_e32 v63, v63
	v_pk_mul_f32 v[54:55], v[54:55], v[60:61]
	s_cmpk_gt_i32 s3, 0x2d5
	v_pk_mul_f32 v[50:51], v[50:51], v[54:55]
	v_pk_mul_f32 v[54:55], v[56:57], v[62:63]
	v_cvt_pk_bf16_f32 v50, v50, v51
	v_pk_mul_f32 v[52:53], v[52:53], v[54:55]
	v_or_b32_e32 v54, 0x50, v92
	v_cvt_pk_bf16_f32 v51, v52, v53
	global_store_dwordx2 v[70:71], v[50:51], off offset:32
	v_mul_f32_e32 v50, 0xbfb8aa3b, v46
	v_mul_f32_e32 v51, 0xbfb8aa3b, v47
	v_exp_f32_e32 v50, v50
	v_exp_f32_e32 v51, v51
	v_mul_f32_e32 v52, 0xbfb8aa3b, v48
	v_mul_f32_e32 v53, 0xbfb8aa3b, v49
	v_exp_f32_e32 v52, v52
	v_exp_f32_e32 v53, v53
	v_add_f32_e32 v50, 1.0, v50
	v_add_f32_e32 v51, 1.0, v51
	v_rcp_f32_e32 v50, v50
	v_rcp_f32_e32 v51, v51
	v_add_f32_e32 v52, 1.0, v52
	v_add_f32_e32 v53, 1.0, v53
	v_rcp_f32_e32 v52, v52
	v_rcp_f32_e32 v53, v53
	v_pk_mul_f32 v[46:47], v[46:47], v[50:51]
	v_mad_i64_i32 v[54:55], s[0:1], v54, s36, v[90:91]
	v_pk_mul_f32 v[42:43], v[42:43], v[46:47]
	v_pk_mul_f32 v[46:47], v[48:49], v[52:53]
	v_cvt_pk_bf16_f32 v42, v42, v43
	v_mul_f32_e32 v43, 0xbfb8aa3b, v38
	v_pk_mul_f32 v[44:45], v[44:45], v[46:47]
	v_exp_f32_e32 v46, v43
	v_mul_f32_e32 v43, 0xbfb8aa3b, v39
	v_exp_f32_e32 v47, v43
	v_cvt_pk_bf16_f32 v43, v44, v45
	v_add_f32_e32 v44, 1.0, v46
	v_mul_f32_e32 v46, 0xbfb8aa3b, v40
	v_add_f32_e32 v45, 1.0, v47
	v_mul_f32_e32 v47, 0xbfb8aa3b, v41
	v_exp_f32_e32 v46, v46
	v_exp_f32_e32 v47, v47
	v_rcp_f32_e32 v44, v44
	v_rcp_f32_e32 v45, v45
	v_add_f32_e32 v46, 1.0, v46
	v_add_f32_e32 v47, 1.0, v47
	v_rcp_f32_e32 v46, v46
	v_rcp_f32_e32 v47, v47
	v_pk_mul_f32 v[38:39], v[38:39], v[44:45]
	global_store_dwordx2 v[150:151], v[122:123], off
	v_pk_mul_f32 v[34:35], v[34:35], v[38:39]
	v_pk_mul_f32 v[38:39], v[40:41], v[46:47]
	v_cvt_pk_bf16_f32 v34, v34, v35
	v_pk_mul_f32 v[36:37], v[36:37], v[38:39]
	v_or_b32_e32 v38, 0x60, v92
	v_cvt_pk_bf16_f32 v35, v36, v37
	global_store_dwordx2 v[54:55], v[34:35], off offset:32
	v_mul_f32_e32 v34, 0xbfb8aa3b, v30
	v_mul_f32_e32 v35, 0xbfb8aa3b, v31
	v_exp_f32_e32 v34, v34
	v_exp_f32_e32 v35, v35
	v_mul_f32_e32 v36, 0xbfb8aa3b, v32
	v_mul_f32_e32 v37, 0xbfb8aa3b, v33
	v_exp_f32_e32 v36, v36
	v_exp_f32_e32 v37, v37
	v_add_f32_e32 v34, 1.0, v34
	v_add_f32_e32 v35, 1.0, v35
	v_rcp_f32_e32 v34, v34
	v_rcp_f32_e32 v35, v35
	v_add_f32_e32 v36, 1.0, v36
	v_add_f32_e32 v37, 1.0, v37
	v_rcp_f32_e32 v36, v36
	v_rcp_f32_e32 v37, v37
	v_pk_mul_f32 v[30:31], v[30:31], v[34:35]
	v_mad_i64_i32 v[38:39], s[0:1], v38, s36, v[90:91]
	v_pk_mul_f32 v[26:27], v[26:27], v[30:31]
	v_pk_mul_f32 v[30:31], v[32:33], v[36:37]
	v_cvt_pk_bf16_f32 v26, v26, v27
	v_mul_f32_e32 v27, 0xbfb8aa3b, v22
	v_pk_mul_f32 v[28:29], v[28:29], v[30:31]
	v_exp_f32_e32 v30, v27
	v_mul_f32_e32 v27, 0xbfb8aa3b, v23
	v_exp_f32_e32 v31, v27
	v_cvt_pk_bf16_f32 v27, v28, v29
	v_add_f32_e32 v28, 1.0, v30
	v_mul_f32_e32 v30, 0xbfb8aa3b, v24
	v_add_f32_e32 v29, 1.0, v31
	v_mul_f32_e32 v31, 0xbfb8aa3b, v25
	v_exp_f32_e32 v30, v30
	v_exp_f32_e32 v31, v31
	v_rcp_f32_e32 v28, v28
	v_rcp_f32_e32 v29, v29
	v_add_f32_e32 v30, 1.0, v30
	v_add_f32_e32 v31, 1.0, v31
	v_rcp_f32_e32 v30, v30
	v_rcp_f32_e32 v31, v31
	v_pk_mul_f32 v[22:23], v[22:23], v[28:29]
	global_store_dwordx2 v[118:119], v[106:107], off
	v_pk_mul_f32 v[18:19], v[18:19], v[22:23]
	v_pk_mul_f32 v[22:23], v[24:25], v[30:31]
	v_cvt_pk_bf16_f32 v18, v18, v19
	v_pk_mul_f32 v[20:21], v[20:21], v[22:23]
	v_or_b32_e32 v22, 0x70, v92
	v_cvt_pk_bf16_f32 v19, v20, v21
	global_store_dwordx2 v[38:39], v[18:19], off offset:32
	v_mul_f32_e32 v18, 0xbfb8aa3b, v14
	v_mul_f32_e32 v19, 0xbfb8aa3b, v15
	v_exp_f32_e32 v18, v18
	v_exp_f32_e32 v19, v19
	v_mul_f32_e32 v20, 0xbfb8aa3b, v16
	v_mul_f32_e32 v21, 0xbfb8aa3b, v17
	v_exp_f32_e32 v20, v20
	v_exp_f32_e32 v21, v21
	v_add_f32_e32 v18, 1.0, v18
	v_add_f32_e32 v19, 1.0, v19
	v_rcp_f32_e32 v18, v18
	v_rcp_f32_e32 v19, v19
	v_add_f32_e32 v20, 1.0, v20
	v_add_f32_e32 v21, 1.0, v21
	v_rcp_f32_e32 v20, v20
	v_rcp_f32_e32 v21, v21
	v_pk_mul_f32 v[14:15], v[14:15], v[18:19]
	v_mad_i64_i32 v[22:23], s[0:1], v22, s36, v[90:91]
	v_pk_mul_f32 v[10:11], v[10:11], v[14:15]
	v_pk_mul_f32 v[14:15], v[16:17], v[20:21]
	v_cvt_pk_bf16_f32 v10, v10, v11
	v_mul_f32_e32 v11, 0xbfb8aa3b, v6
	v_pk_mul_f32 v[12:13], v[12:13], v[14:15]
	v_exp_f32_e32 v14, v11
	v_mul_f32_e32 v11, 0xbfb8aa3b, v7
	v_exp_f32_e32 v15, v11
	v_cvt_pk_bf16_f32 v11, v12, v13
	v_add_f32_e32 v12, 1.0, v14
	v_mul_f32_e32 v14, 0xbfb8aa3b, v8
	v_add_f32_e32 v13, 1.0, v15
	v_mul_f32_e32 v15, 0xbfb8aa3b, v9
	v_exp_f32_e32 v14, v14
	v_exp_f32_e32 v15, v15
	v_rcp_f32_e32 v12, v12
	v_rcp_f32_e32 v13, v13
	v_add_f32_e32 v14, 1.0, v14
	v_add_f32_e32 v15, 1.0, v15
	v_rcp_f32_e32 v14, v14
	v_rcp_f32_e32 v15, v15
	v_pk_mul_f32 v[6:7], v[6:7], v[12:13]
	global_store_dwordx2 v[102:103], v[94:95], off
	v_pk_mul_f32 v[2:3], v[2:3], v[6:7]
	v_pk_mul_f32 v[6:7], v[8:9], v[14:15]
	v_cvt_pk_bf16_f32 v2, v2, v3
	v_pk_mul_f32 v[4:5], v[4:5], v[6:7]
	global_store_dwordx2 v[86:87], v[74:75], off
	v_cvt_pk_bf16_f32 v3, v4, v5
	global_store_dwordx2 v[70:71], v[58:59], off
	global_store_dwordx2 v[54:55], v[42:43], off
	global_store_dwordx2 v[38:39], v[26:27], off
	global_store_dwordx2 v[22:23], v[10:11], off
	global_store_dwordx2 v[22:23], v[2:3], off offset:32
	s_cbranch_scc0 .LBB0_354

.LBB0_372:
	v_lshlrev_b32_e32 v4, 4, v2
	v_and_b32_e32 v4, 0x70, v4
	v_mov_b32_e32 v5, 0
	v_lshl_add_u64 v[6:7], s[86:87], 0, v[4:5]
	s_mov_b64 s[6:7], 0x21250000
	v_lshrrev_b32_e32 v1, 3, v2
	v_lshl_add_u64 v[130:131], v[6:7], 0, s[6:7]
	s_mov_b64 s[6:7], 0x1b00000
	s_add_u32 s4, s86, 0x3c50000
	v_lshl_add_u64 v[132:133], v[6:7], 0, s[6:7]
	v_mul_u32_u24_e32 v6, 0x48, v1
	s_addc_u32 s5, s87, 0
	v_lshlrev_b32_e32 v6, 1, v6
	s_add_i32 s6, 0, 0x12000
	v_add3_u32 v146, 0, v6, v4
	v_add3_u32 v147, s6, v6, v4
	v_and_b32_e32 v4, 15, v2
	v_lshrrev_b32_e32 v6, 1, v2
	s_movk_i32 s7, 0x180
	v_and_or_b32 v4, v6, s7, v4
	v_mul_u32_u24_e32 v4, 0x90, v4
	v_and_b32_e32 v6, 48, v2
	v_add3_u32 v148, 0, v4, v6
	v_and_b32_e32 v4, 0xcf, v2
	v_mov_b32_e32 v3, v2
	v_mul_u32_u24_e32 v4, 0x90, v4
	s_lshr_b32 s3, s2, 3
	s_and_b32 s10, s2, 7
	v_add3_u32 v149, s6, v4, v6
	v_lshrrev_b32_e32 v4, 1, v1
	v_and_b32_e32 v4, 7, v4
	v_and_b32_e32 v7, 7, v2
	v_xor_b32_e32 v4, v4, v7
	v_lshlrev_b32_e32 v4, 4, v4
	v_lshl_add_u32 v146, v1, 7, v4
	v_add_u32_e32 v147, 0x10000, v146
	v_and_b32_e32 v4, 15, v2
	v_lshrrev_b32_e32 v7, 1, v4
	v_bfe_u32 v216, v2, 4, 2
	v_xor_b32_e32 v7, v7, v216
	v_lshlrev_b32_e32 v7, 4, v7
	v_lshrrev_b32_e32 v216, 8, v2
	v_lshl_add_u32 v216, v216, 7, v4
	v_lshl_add_u32 v148, v216, 7, v7
	v_xor_b32_e32 v216, 64, v148
	v_bfe_u32 v217, v2, 6, 2
	v_lshl_add_u32 v217, v217, 6, v4
	v_lshl_add_u32 v149, v217, 7, v7
	v_add_u32_e32 v149, 0x10000, v149
	v_xor_b32_e32 v217, 64, v149
	v_ashrrev_i32_e32 v4, 1, v3
	v_and_b32_e32 v7, 15, v3
	s_movk_i32 s6, 0xff80
	v_and_b32_e32 v2, 7, v2
	v_and_b32_e32 v6, 0xc0, v3
	v_and_or_b32 v150, v4, s6, v7
	s_add_u32 s6, s86, 0x2f85000
	v_lshrrev_b32_e32 v3, 2, v3
	v_lshlrev_b32_e32 v4, 4, v2
	s_mul_i32 s10, s10, 33
	s_addc_u32 s7, s87, 0
	v_and_or_b32 v151, v3, 12, v6
	s_ashr_i32 s11, s33, 3
	v_lshl_add_u64 v[134:135], s[86:87], 0, v[4:5]
	s_movk_i32 s12, 0x1600
	s_mov_b32 s13, 0x58000
	s_mov_b32 s14, 0xb0000
	s_mov_b32 s15, 0x108000
	s_waitcnt lgkmcnt(0)
	s_mov_b32 s16, 0x21250000
	s_mov_b32 s17, 0x212a8000
	s_mov_b32 s28, 0x21300000
	s_mov_b32 s29, 0x21358000
	s_mov_b32 s36, 0x1b00000
	s_mov_b32 s37, 0x1b58000
	s_mov_b32 s38, 0x1bb0000
	s_mov_b32 s39, 0x1c08000
	s_mov_b32 s40, 0x3e0f83e1
	s_movk_i32 s41, 0xdf00
	s_movk_i32 s42, 0xff
	s_movk_i32 s43, 0xff00
	s_branch .LBB0_375

.LBB0_378:
	s_lshl_b32 s47, s45, 8
	v_or_b32_e32 v27, s47, v1
	v_mad_i64_i32 v[2:3], s[8:9], v27, s12, v[130:131]
	v_add_co_u32_e32 v6, vcc, 0x58000, v2
	s_lshl_b32 s46, s44, 8
	s_nop 0
	v_addc_co_u32_e32 v7, vcc, 0, v3, vcc
	global_load_dwordx4 v[28:31], v[2:3], off
	global_load_dwordx4 v[32:35], v[6:7], off
	v_add_co_u32_e32 v6, vcc, 0xb0000, v2
	v_or_b32_e32 v60, s46, v1
	s_nop 0
	v_addc_co_u32_e32 v7, vcc, 0, v3, vcc
	v_add_co_u32_e32 v2, vcc, 0x108000, v2
	v_mad_i64_i32 v[4:5], s[8:9], v60, s12, v[132:133]
	s_nop 0
	v_addc_co_u32_e32 v3, vcc, 0, v3, vcc
	global_load_dwordx4 v[36:39], v[6:7], off
	global_load_dwordx4 v[40:43], v[2:3], off
	v_add_co_u32_e32 v2, vcc, s13, v4
	s_waitcnt vmcnt(63) expcnt(7) lgkmcnt(15)
	s_nop 0
	v_addc_co_u32_e32 v3, vcc, 0, v5, vcc
	s_barrier
	global_load_dwordx4 v[44:47], v[4:5], off
	global_load_dwordx4 v[48:51], v[2:3], off
	v_add_co_u32_e32 v2, vcc, s14, v4
	s_mov_b32 s52, 0
	s_nop 0
	v_addc_co_u32_e32 v3, vcc, 0, v5, vcc
	v_add_co_u32_e32 v4, vcc, s15, v4
	s_mov_b64 s[8:9], 0
	s_nop 0
	v_addc_co_u32_e32 v5, vcc, 0, v5, vcc
	global_load_dwordx4 v[52:55], v[2:3], off
	global_load_dwordx4 v[56:59], v[4:5], off
	v_mov_b32_e32 v2, 0
	v_mov_b32_e32 v3, v2
	v_mov_b32_e32 v4, v2
	v_mov_b32_e32 v5, v2
	v_mov_b32_e32 v6, v2
	v_mov_b32_e32 v7, v2
	v_mov_b32_e32 v8, v2
	v_mov_b32_e32 v9, v2
	v_mov_b32_e32 v10, v2
	v_mov_b32_e32 v11, v2
	v_mov_b32_e32 v12, v2
	v_mov_b32_e32 v13, v2
	v_mov_b32_e32 v14, v2
	v_mov_b32_e32 v15, v2
	v_mov_b32_e32 v16, v2
	v_mov_b32_e32 v17, v2
	v_mov_b32_e32 v18, v2
	v_mov_b32_e32 v19, v2
	v_mov_b32_e32 v20, v2
	v_mov_b32_e32 v21, v2
	v_mov_b32_e32 v22, v2
	v_mov_b32_e32 v23, v2
	v_mov_b32_e32 v24, v2
	v_mov_b32_e32 v25, v2
	v_mov_b32_e32 v26, v2
	v_mad_i64_i32 v[136:137], s[56:57], v27, s12, v[134:135]
	v_mad_i64_i32 v[138:139], s[56:57], v60, s12, v[134:135]
	v_mov_b32_e32 v27, v2
	v_mov_b32_e32 v60, v2
	v_mov_b32_e32 v61, v2
	v_mov_b32_e32 v62, v2
	v_mov_b32_e32 v63, v2
	v_mov_b32_e32 v64, v2
	v_mov_b32_e32 v65, v2
	v_mov_b32_e32 v66, v2
	v_mov_b32_e32 v67, v2
	v_mov_b32_e32 v68, v2
	v_mov_b32_e32 v69, v2
	v_mov_b32_e32 v70, v2
	v_mov_b32_e32 v71, v2
	v_mov_b32_e32 v72, v2
	v_mov_b32_e32 v73, v2
	v_mov_b32_e32 v74, v2
	v_mov_b32_e32 v75, v2
	v_mov_b32_e32 v76, v2
	v_mov_b32_e32 v77, v2
	v_mov_b32_e32 v78, v2
	v_mov_b32_e32 v79, v2
	v_mov_b32_e32 v80, v2
	v_mov_b32_e32 v81, v2
	v_mov_b32_e32 v82, v2
	s_waitcnt vmcnt(7)
	ds_write_b128 v146, v[28:31]
	s_waitcnt vmcnt(6)
	ds_write_b128 v146, v[32:35] offset:8192
	s_waitcnt vmcnt(5)
	ds_write_b128 v146, v[36:39] offset:16384
	s_waitcnt vmcnt(4)
	ds_write_b128 v146, v[40:43] offset:24576
	s_waitcnt vmcnt(3)
	ds_write_b128 v147, v[44:47]
	s_waitcnt vmcnt(2)
	ds_write_b128 v147, v[48:51] offset:8192
	s_waitcnt vmcnt(1)
	ds_write_b128 v147, v[52:55] offset:16384
	s_waitcnt vmcnt(0)
	ds_write_b128 v147, v[56:59] offset:24576
	v_mov_b32_e32 v28, v2
	v_mov_b32_e32 v29, v2
	v_mov_b32_e32 v30, v2
	v_mov_b32_e32 v31, v2
	v_mov_b32_e32 v32, v2
	v_mov_b32_e32 v33, v2
	v_mov_b32_e32 v34, v2
	v_mov_b32_e32 v35, v2
	v_mov_b32_e32 v36, v2
	v_mov_b32_e32 v37, v2
	v_mov_b32_e32 v38, v2
	v_mov_b32_e32 v39, v2
	v_mov_b32_e32 v40, v2
	v_mov_b32_e32 v41, v2
	v_mov_b32_e32 v42, v2
	v_mov_b32_e32 v43, v2
	v_mov_b32_e32 v44, v2
	v_mov_b32_e32 v45, v2
	v_mov_b32_e32 v46, v2
	v_mov_b32_e32 v47, v2
	v_mov_b32_e32 v48, v2
	v_mov_b32_e32 v49, v2
	v_mov_b32_e32 v50, v2
	v_mov_b32_e32 v51, v2
	v_mov_b32_e32 v52, v2
	v_mov_b32_e32 v53, v2
	v_mov_b32_e32 v54, v2
	v_mov_b32_e32 v55, v2
	v_mov_b32_e32 v56, v2
	v_mov_b32_e32 v57, v2
	v_mov_b32_e32 v58, v2
	v_mov_b32_e32 v59, v2
	v_mov_b32_e32 v83, v2
	v_mov_b32_e32 v84, v2
	v_mov_b32_e32 v85, v2
	v_mov_b32_e32 v86, v2
	v_mov_b32_e32 v87, v2
	v_mov_b32_e32 v88, v2
	v_mov_b32_e32 v89, v2
	v_mov_b32_e32 v90, v2
	v_mov_b32_e32 v91, v2
	v_mov_b32_e32 v92, v2
	v_mov_b32_e32 v93, v2
	v_mov_b32_e32 v94, v2
	v_mov_b32_e32 v95, v2
	v_mov_b32_e32 v96, v2
	v_mov_b32_e32 v97, v2
	v_mov_b32_e32 v98, v2
	v_mov_b32_e32 v99, v2
	v_mov_b32_e32 v100, v2
	v_mov_b32_e32 v101, v2
	v_mov_b32_e32 v102, v2
	v_mov_b32_e32 v103, v2
	v_mov_b32_e32 v104, v2
	v_mov_b32_e32 v105, v2
	v_mov_b32_e32 v106, v2
	v_mov_b32_e32 v107, v2
	v_mov_b32_e32 v108, v2
	v_mov_b32_e32 v109, v2
	v_mov_b32_e32 v110, v2
	v_mov_b32_e32 v111, v2
	v_mov_b32_e32 v112, v2
	v_mov_b32_e32 v113, v2
	v_mov_b32_e32 v114, v2
	v_mov_b32_e32 v115, v2
	v_mov_b32_e32 v116, v2
	v_mov_b32_e32 v117, v2
	v_mov_b32_e32 v118, v2
	v_mov_b32_e32 v119, v2
	v_mov_b32_e32 v120, v2
	v_mov_b32_e32 v121, v2
	v_mov_b32_e32 v122, v2
	v_mov_b32_e32 v123, v2
	v_mov_b32_e32 v124, v2
	v_mov_b32_e32 v125, v2
	v_mov_b32_e32 v126, v2
	v_mov_b32_e32 v127, v2
	v_mov_b32_e32 v128, v2
	v_mov_b32_e32 v129, v2
	s_waitcnt lgkmcnt(0)
	s_barrier
	v_lshl_add_u64 v[140:141], v[136:137], 0, s[8:9]
	v_add_co_u32_e32 v142, vcc, s16, v140
	s_nop 1
	v_addc_co_u32_e32 v143, vcc, 0, v141, vcc
	v_add_co_u32_e32 v144, vcc, s17, v140
	s_nop 1
	v_addc_co_u32_e32 v145, vcc, 0, v141, vcc
	v_add_co_u32_e32 v156, vcc, s28, v140
	s_nop 1
	v_addc_co_u32_e32 v157, vcc, 0, v141, vcc
	v_add_co_u32_e32 v160, vcc, s29, v140
	s_nop 1
	v_addc_co_u32_e32 v161, vcc, 0, v141, vcc
	global_load_dwordx4 v[140:143], v[142:143], off offset:128
	global_load_dwordx4 v[152:155], v[144:145], off offset:128
	global_load_dwordx4 v[156:159], v[156:157], off offset:128
	global_load_dwordx4 v[160:163], v[160:161], off offset:128
	v_lshl_add_u64 v[144:145], v[138:139], 0, s[8:9]
	v_add_co_u32_e32 v164, vcc, s36, v144
	s_nop 1
	v_addc_co_u32_e32 v165, vcc, 0, v145, vcc
	v_add_co_u32_e32 v168, vcc, s37, v144
	s_nop 1
	v_addc_co_u32_e32 v169, vcc, 0, v145, vcc
	v_add_co_u32_e32 v172, vcc, s38, v144
	s_nop 1
	v_addc_co_u32_e32 v173, vcc, 0, v145, vcc
	v_add_co_u32_e32 v144, vcc, s39, v144
	s_nop 1
	v_addc_co_u32_e32 v145, vcc, 0, v145, vcc
	global_load_dwordx4 v[164:167], v[164:165], off offset:128
	global_load_dwordx4 v[168:171], v[168:169], off offset:128
	global_load_dwordx4 v[172:175], v[172:173], off offset:128
	global_load_dwordx4 v[176:179], v[144:145], off offset:128
	v_mov_b32_e32 v223, v148
	v_mov_b32_e32 v248, v216
	v_mov_b32_e32 v249, v149
	v_mov_b32_e32 v250, v217
	v_xor_b32_e32 v251, 0x8000, v146
	v_xor_b32_e32 v252, 0x8000, v147
	ds_read_b128 v[180:183], v223
	ds_read_b128 v[184:187], v223 offset:2048
	ds_read_b128 v[188:191], v223 offset:4096
	ds_read_b128 v[192:195], v223 offset:6144
	ds_read_b128 v[212:215], v249
	ds_read_b128 v[218:221], v249 offset:2048
	ds_read_b128 v[224:227], v249 offset:4096
	ds_read_b128 v[228:231], v249 offset:6144
.Lg2_p7_loop:
	ds_read_b128 v[196:199], v223 offset:8192
	ds_read_b128 v[200:203], v223 offset:10240
	ds_read_b128 v[204:207], v223 offset:12288
	ds_read_b128 v[208:211], v223 offset:14336
	s_waitcnt lgkmcnt(4)
	v_mfma_f32_16x16x32_bf16 v[126:129], v[212:215], v[180:183], v[126:129]
	v_mfma_f32_16x16x32_bf16 v[122:125], v[218:221], v[180:183], v[122:125]
	v_mfma_f32_16x16x32_bf16 v[118:121], v[224:227], v[180:183], v[118:121]
	v_mfma_f32_16x16x32_bf16 v[114:117], v[228:231], v[180:183], v[114:117]
	v_mfma_f32_16x16x32_bf16 v[110:113], v[212:215], v[184:187], v[110:113]
	v_mfma_f32_16x16x32_bf16 v[106:109], v[218:221], v[184:187], v[106:109]
	v_mfma_f32_16x16x32_bf16 v[102:105], v[224:227], v[184:187], v[102:105]
	v_mfma_f32_16x16x32_bf16 v[98:101], v[228:231], v[184:187], v[98:101]
	v_mfma_f32_16x16x32_bf16 v[94:97], v[212:215], v[188:191], v[94:97]
	v_mfma_f32_16x16x32_bf16 v[90:93], v[218:221], v[188:191], v[90:93]
	v_mfma_f32_16x16x32_bf16 v[86:89], v[224:227], v[188:191], v[86:89]
	v_mfma_f32_16x16x32_bf16 v[82:85], v[228:231], v[188:191], v[82:85]
	v_mfma_f32_16x16x32_bf16 v[78:81], v[212:215], v[192:195], v[78:81]
	v_mfma_f32_16x16x32_bf16 v[74:77], v[218:221], v[192:195], v[74:77]
	v_mfma_f32_16x16x32_bf16 v[70:73], v[224:227], v[192:195], v[70:73]
	v_mfma_f32_16x16x32_bf16 v[66:69], v[228:231], v[192:195], v[66:69]
	ds_read_b128 v[180:183], v248
	ds_read_b128 v[184:187], v248 offset:2048
	ds_read_b128 v[188:191], v248 offset:4096
	ds_read_b128 v[192:195], v248 offset:6144
	ds_read_b128 v[232:235], v250
	ds_read_b128 v[236:239], v250 offset:2048
	ds_read_b128 v[240:243], v250 offset:4096
	ds_read_b128 v[244:247], v250 offset:6144
	s_waitcnt lgkmcnt(8)
	v_mfma_f32_16x16x32_bf16 v[62:65], v[212:215], v[196:199], v[62:65]
	v_mfma_f32_16x16x32_bf16 v[58:61], v[218:221], v[196:199], v[58:61]
	v_mfma_f32_16x16x32_bf16 v[54:57], v[224:227], v[196:199], v[54:57]
	v_mfma_f32_16x16x32_bf16 v[50:53], v[228:231], v[196:199], v[50:53]
	v_mfma_f32_16x16x32_bf16 v[46:49], v[212:215], v[200:203], v[46:49]
	v_mfma_f32_16x16x32_bf16 v[42:45], v[218:221], v[200:203], v[42:45]
	v_mfma_f32_16x16x32_bf16 v[38:41], v[224:227], v[200:203], v[38:41]
	v_mfma_f32_16x16x32_bf16 v[34:37], v[228:231], v[200:203], v[34:37]
	v_mfma_f32_16x16x32_bf16 v[30:33], v[212:215], v[204:207], v[30:33]
	v_mfma_f32_16x16x32_bf16 v[26:29], v[218:221], v[204:207], v[26:29]
	v_mfma_f32_16x16x32_bf16 v[22:25], v[224:227], v[204:207], v[22:25]
	v_mfma_f32_16x16x32_bf16 v[18:21], v[228:231], v[204:207], v[18:21]
	v_mfma_f32_16x16x32_bf16 v[14:17], v[212:215], v[208:211], v[14:17]
	v_mfma_f32_16x16x32_bf16 v[10:13], v[218:221], v[208:211], v[10:13]
	v_mfma_f32_16x16x32_bf16 v[6:9], v[224:227], v[208:211], v[6:9]
	v_mfma_f32_16x16x32_bf16 v[2:5], v[228:231], v[208:211], v[2:5]
	ds_read_b128 v[196:199], v248 offset:8192
	ds_read_b128 v[200:203], v248 offset:10240
	ds_read_b128 v[204:207], v248 offset:12288
	ds_read_b128 v[208:211], v248 offset:14336
	s_waitcnt lgkmcnt(4)
	v_mfma_f32_16x16x32_bf16 v[126:129], v[232:235], v[180:183], v[126:129]
	v_mfma_f32_16x16x32_bf16 v[122:125], v[236:239], v[180:183], v[122:125]
	s_waitcnt vmcnt(7)
	ds_write_b128 v251, v[140:143]
	v_mfma_f32_16x16x32_bf16 v[118:121], v[240:243], v[180:183], v[118:121]
	v_mfma_f32_16x16x32_bf16 v[114:117], v[244:247], v[180:183], v[114:117]
	s_waitcnt vmcnt(6)
	ds_write_b128 v251, v[152:155] offset:8192
	v_mfma_f32_16x16x32_bf16 v[110:113], v[232:235], v[184:187], v[110:113]
	v_mfma_f32_16x16x32_bf16 v[106:109], v[236:239], v[184:187], v[106:109]
	s_waitcnt vmcnt(5)
	ds_write_b128 v251, v[156:159] offset:16384
	v_mfma_f32_16x16x32_bf16 v[102:105], v[240:243], v[184:187], v[102:105]
	v_mfma_f32_16x16x32_bf16 v[98:101], v[244:247], v[184:187], v[98:101]
	s_waitcnt vmcnt(4)
	ds_write_b128 v251, v[160:163] offset:24576
	v_mfma_f32_16x16x32_bf16 v[94:97], v[232:235], v[188:191], v[94:97]
	v_mfma_f32_16x16x32_bf16 v[90:93], v[236:239], v[188:191], v[90:93]
	s_waitcnt vmcnt(3)
	ds_write_b128 v252, v[164:167]
	v_mfma_f32_16x16x32_bf16 v[86:89], v[240:243], v[188:191], v[86:89]
	v_mfma_f32_16x16x32_bf16 v[82:85], v[244:247], v[188:191], v[82:85]
	s_waitcnt vmcnt(2)
	ds_write_b128 v252, v[168:171] offset:8192
	v_mfma_f32_16x16x32_bf16 v[78:81], v[232:235], v[192:195], v[78:81]
	v_mfma_f32_16x16x32_bf16 v[74:77], v[236:239], v[192:195], v[74:77]
	s_waitcnt vmcnt(1)
	ds_write_b128 v252, v[172:175] offset:16384
	v_mfma_f32_16x16x32_bf16 v[70:73], v[240:243], v[192:195], v[70:73]
	v_mfma_f32_16x16x32_bf16 v[66:69], v[244:247], v[192:195], v[66:69]
	s_waitcnt vmcnt(0)
	ds_write_b128 v252, v[176:179] offset:24576
	s_waitcnt lgkmcnt(0)
	s_barrier
	s_add_u32 s8, s8, 0x80
	s_addc_u32 s9, s9, 0
	s_cmpk_eq_i32 s8, 0x1580
	s_cbranch_scc1 .Lg2_p7_tail
	v_xor_b32_e32 v223, 0x8000, v223
	v_xor_b32_e32 v249, 0x8000, v249
	v_xor_b32_e32 v248, 0x8000, v248
	v_xor_b32_e32 v250, 0x8000, v250
	v_xor_b32_e32 v251, 0x8000, v251
	v_xor_b32_e32 v252, 0x8000, v252
	ds_read_b128 v[180:183], v223
	ds_read_b128 v[184:187], v223 offset:2048
	ds_read_b128 v[188:191], v223 offset:4096
	ds_read_b128 v[192:195], v223 offset:6144
	ds_read_b128 v[212:215], v249
	ds_read_b128 v[218:221], v249 offset:2048
	ds_read_b128 v[224:227], v249 offset:4096
	ds_read_b128 v[228:231], v249 offset:6144
	v_mfma_f32_16x16x32_bf16 v[62:65], v[232:235], v[196:199], v[62:65]
	v_lshl_add_u64 v[140:141], v[136:137], 0, s[8:9]
	v_add_co_u32_e32 v142, vcc, s16, v140
	v_mfma_f32_16x16x32_bf16 v[58:61], v[236:239], v[196:199], v[58:61]
	s_nop 1
	v_addc_co_u32_e32 v143, vcc, 0, v141, vcc
	v_mfma_f32_16x16x32_bf16 v[54:57], v[240:243], v[196:199], v[54:57]
	v_add_co_u32_e32 v144, vcc, s17, v140
	s_nop 1
	v_mfma_f32_16x16x32_bf16 v[50:53], v[244:247], v[196:199], v[50:53]
	v_addc_co_u32_e32 v145, vcc, 0, v141, vcc
	v_add_co_u32_e32 v156, vcc, s28, v140
	v_mfma_f32_16x16x32_bf16 v[46:49], v[232:235], v[200:203], v[46:49]
	s_nop 1
	v_addc_co_u32_e32 v157, vcc, 0, v141, vcc
	v_mfma_f32_16x16x32_bf16 v[42:45], v[236:239], v[200:203], v[42:45]
	v_add_co_u32_e32 v160, vcc, s29, v140
	s_nop 1
	v_mfma_f32_16x16x32_bf16 v[38:41], v[240:243], v[200:203], v[38:41]
	v_addc_co_u32_e32 v161, vcc, 0, v141, vcc
	global_load_dwordx4 v[140:143], v[142:143], off offset:128
	v_mfma_f32_16x16x32_bf16 v[34:37], v[244:247], v[200:203], v[34:37]
	global_load_dwordx4 v[152:155], v[144:145], off offset:128
	global_load_dwordx4 v[156:159], v[156:157], off offset:128
	global_load_dwordx4 v[160:163], v[160:161], off offset:128
	v_mfma_f32_16x16x32_bf16 v[30:33], v[232:235], v[204:207], v[30:33]
	v_lshl_add_u64 v[144:145], v[138:139], 0, s[8:9]
	v_add_co_u32_e32 v164, vcc, s36, v144
	v_mfma_f32_16x16x32_bf16 v[26:29], v[236:239], v[204:207], v[26:29]
	s_nop 1
	v_addc_co_u32_e32 v165, vcc, 0, v145, vcc
	v_mfma_f32_16x16x32_bf16 v[22:25], v[240:243], v[204:207], v[22:25]
	v_add_co_u32_e32 v168, vcc, s37, v144
	s_nop 1
	v_mfma_f32_16x16x32_bf16 v[18:21], v[244:247], v[204:207], v[18:21]
	v_addc_co_u32_e32 v169, vcc, 0, v145, vcc
	v_add_co_u32_e32 v172, vcc, s38, v144
	v_mfma_f32_16x16x32_bf16 v[14:17], v[232:235], v[208:211], v[14:17]
	s_nop 1
	v_addc_co_u32_e32 v173, vcc, 0, v145, vcc
	v_mfma_f32_16x16x32_bf16 v[10:13], v[236:239], v[208:211], v[10:13]
	v_add_co_u32_e32 v144, vcc, s39, v144
	s_nop 1
	v_mfma_f32_16x16x32_bf16 v[6:9], v[240:243], v[208:211], v[6:9]
	v_addc_co_u32_e32 v145, vcc, 0, v145, vcc
	global_load_dwordx4 v[164:167], v[164:165], off offset:128
	v_mfma_f32_16x16x32_bf16 v[2:5], v[244:247], v[208:211], v[2:5]
	global_load_dwordx4 v[168:171], v[168:169], off offset:128
	global_load_dwordx4 v[172:175], v[172:173], off offset:128
	global_load_dwordx4 v[176:179], v[144:145], off offset:128
	s_branch .Lg2_p7_loop
.Lg2_p7_tail:
	v_mfma_f32_16x16x32_bf16 v[62:65], v[232:235], v[196:199], v[62:65]
	v_mfma_f32_16x16x32_bf16 v[58:61], v[236:239], v[196:199], v[58:61]
	v_mfma_f32_16x16x32_bf16 v[54:57], v[240:243], v[196:199], v[54:57]
	v_mfma_f32_16x16x32_bf16 v[50:53], v[244:247], v[196:199], v[50:53]
	v_mfma_f32_16x16x32_bf16 v[46:49], v[232:235], v[200:203], v[46:49]
	v_mfma_f32_16x16x32_bf16 v[42:45], v[236:239], v[200:203], v[42:45]
	v_mfma_f32_16x16x32_bf16 v[38:41], v[240:243], v[200:203], v[38:41]
	v_mfma_f32_16x16x32_bf16 v[34:37], v[244:247], v[200:203], v[34:37]
	v_mfma_f32_16x16x32_bf16 v[30:33], v[232:235], v[204:207], v[30:33]
	v_mfma_f32_16x16x32_bf16 v[26:29], v[236:239], v[204:207], v[26:29]
	v_mfma_f32_16x16x32_bf16 v[22:25], v[240:243], v[204:207], v[22:25]
	v_mfma_f32_16x16x32_bf16 v[18:21], v[244:247], v[204:207], v[18:21]
	v_mfma_f32_16x16x32_bf16 v[14:17], v[232:235], v[208:211], v[14:17]
	v_mfma_f32_16x16x32_bf16 v[10:13], v[236:239], v[208:211], v[10:13]
	v_mfma_f32_16x16x32_bf16 v[6:9], v[240:243], v[208:211], v[6:9]
	v_mfma_f32_16x16x32_bf16 v[2:5], v[244:247], v[208:211], v[2:5]
	ds_read_b128 v[136:139], v149 offset:32768
	ds_read_b128 v[140:143], v149 offset:34816
	ds_read_b128 v[152:155], v149 offset:36864
	ds_read_b128 v[156:159], v149 offset:38912
	ds_read_b128 v[160:163], v148 offset:32768
	ds_read_b128 v[164:167], v148 offset:34816
	ds_read_b128 v[168:171], v148 offset:36864
	ds_read_b128 v[172:175], v148 offset:38912
	s_setprio 1
	s_waitcnt lgkmcnt(3)
	v_mfma_f32_16x16x32_bf16 v[126:129], v[136:139], v[160:163], v[126:129]
	v_mfma_f32_16x16x32_bf16 v[122:125], v[140:143], v[160:163], v[122:125]
	v_mfma_f32_16x16x32_bf16 v[118:121], v[152:155], v[160:163], v[118:121]
	v_mfma_f32_16x16x32_bf16 v[114:117], v[156:159], v[160:163], v[114:117]
	s_waitcnt lgkmcnt(2)
	v_mfma_f32_16x16x32_bf16 v[110:113], v[136:139], v[164:167], v[110:113]
	v_mfma_f32_16x16x32_bf16 v[106:109], v[140:143], v[164:167], v[106:109]
	v_mfma_f32_16x16x32_bf16 v[102:105], v[152:155], v[164:167], v[102:105]
	v_mfma_f32_16x16x32_bf16 v[98:101], v[156:159], v[164:167], v[98:101]
	s_waitcnt lgkmcnt(1)
	v_mfma_f32_16x16x32_bf16 v[94:97], v[136:139], v[168:171], v[94:97]
	v_mfma_f32_16x16x32_bf16 v[90:93], v[140:143], v[168:171], v[90:93]
	v_mfma_f32_16x16x32_bf16 v[86:89], v[152:155], v[168:171], v[86:89]
	v_mfma_f32_16x16x32_bf16 v[82:85], v[156:159], v[168:171], v[82:85]
	s_waitcnt lgkmcnt(0)
	v_mfma_f32_16x16x32_bf16 v[78:81], v[136:139], v[172:175], v[78:81]
	v_mfma_f32_16x16x32_bf16 v[74:77], v[140:143], v[172:175], v[74:77]
	v_mfma_f32_16x16x32_bf16 v[70:73], v[152:155], v[172:175], v[70:73]
	v_mfma_f32_16x16x32_bf16 v[66:69], v[156:159], v[172:175], v[66:69]
	s_setprio 0
	ds_read_b128 v[160:163], v148 offset:40960
	ds_read_b128 v[164:167], v148 offset:43008
	ds_read_b128 v[168:171], v148 offset:45056
	ds_read_b128 v[172:175], v148 offset:47104
	s_setprio 1
	s_waitcnt lgkmcnt(3)
	v_mfma_f32_16x16x32_bf16 v[62:65], v[136:139], v[160:163], v[62:65]
	v_mfma_f32_16x16x32_bf16 v[58:61], v[140:143], v[160:163], v[58:61]
	v_mfma_f32_16x16x32_bf16 v[54:57], v[152:155], v[160:163], v[54:57]
	v_mfma_f32_16x16x32_bf16 v[50:53], v[156:159], v[160:163], v[50:53]
	s_waitcnt lgkmcnt(2)
	v_mfma_f32_16x16x32_bf16 v[46:49], v[136:139], v[164:167], v[46:49]
	v_mfma_f32_16x16x32_bf16 v[42:45], v[140:143], v[164:167], v[42:45]
	v_mfma_f32_16x16x32_bf16 v[38:41], v[152:155], v[164:167], v[38:41]
	v_mfma_f32_16x16x32_bf16 v[34:37], v[156:159], v[164:167], v[34:37]
	s_waitcnt lgkmcnt(1)
	v_mfma_f32_16x16x32_bf16 v[30:33], v[136:139], v[168:171], v[30:33]
	v_mfma_f32_16x16x32_bf16 v[26:29], v[140:143], v[168:171], v[26:29]
	v_mfma_f32_16x16x32_bf16 v[22:25], v[152:155], v[168:171], v[22:25]
	v_mfma_f32_16x16x32_bf16 v[18:21], v[156:159], v[168:171], v[18:21]
	s_waitcnt lgkmcnt(0)
	v_mfma_f32_16x16x32_bf16 v[14:17], v[136:139], v[172:175], v[14:17]
	v_mfma_f32_16x16x32_bf16 v[10:13], v[140:143], v[172:175], v[10:13]
	v_mfma_f32_16x16x32_bf16 v[6:9], v[152:155], v[172:175], v[6:9]
	v_mfma_f32_16x16x32_bf16 v[2:5], v[156:159], v[172:175], v[2:5]
	s_setprio 0
	ds_read_b128 v[136:139], v217 offset:32768
	ds_read_b128 v[140:143], v217 offset:34816
	ds_read_b128 v[152:155], v217 offset:36864
	ds_read_b128 v[156:159], v217 offset:38912
	ds_read_b128 v[160:163], v216 offset:32768
	ds_read_b128 v[164:167], v216 offset:34816
	ds_read_b128 v[168:171], v216 offset:36864
	ds_read_b128 v[172:175], v216 offset:38912
	s_setprio 1
	s_waitcnt lgkmcnt(3)
	v_mfma_f32_16x16x32_bf16 v[126:129], v[136:139], v[160:163], v[126:129]
	v_mfma_f32_16x16x32_bf16 v[122:125], v[140:143], v[160:163], v[122:125]
	v_mfma_f32_16x16x32_bf16 v[118:121], v[152:155], v[160:163], v[118:121]
	v_mfma_f32_16x16x32_bf16 v[114:117], v[156:159], v[160:163], v[114:117]
	s_waitcnt lgkmcnt(2)
	v_mfma_f32_16x16x32_bf16 v[110:113], v[136:139], v[164:167], v[110:113]
	v_mfma_f32_16x16x32_bf16 v[106:109], v[140:143], v[164:167], v[106:109]
	v_mfma_f32_16x16x32_bf16 v[102:105], v[152:155], v[164:167], v[102:105]
	v_mfma_f32_16x16x32_bf16 v[98:101], v[156:159], v[164:167], v[98:101]
	s_waitcnt lgkmcnt(1)
	v_mfma_f32_16x16x32_bf16 v[94:97], v[136:139], v[168:171], v[94:97]
	v_mfma_f32_16x16x32_bf16 v[90:93], v[140:143], v[168:171], v[90:93]
	v_mfma_f32_16x16x32_bf16 v[86:89], v[152:155], v[168:171], v[86:89]
	v_mfma_f32_16x16x32_bf16 v[82:85], v[156:159], v[168:171], v[82:85]
	s_waitcnt lgkmcnt(0)
	v_mfma_f32_16x16x32_bf16 v[78:81], v[136:139], v[172:175], v[78:81]
	v_mfma_f32_16x16x32_bf16 v[74:77], v[140:143], v[172:175], v[74:77]
	v_mfma_f32_16x16x32_bf16 v[70:73], v[152:155], v[172:175], v[70:73]
	v_mfma_f32_16x16x32_bf16 v[66:69], v[156:159], v[172:175], v[66:69]
	s_setprio 0
	ds_read_b128 v[160:163], v216 offset:40960
	ds_read_b128 v[164:167], v216 offset:43008
	ds_read_b128 v[168:171], v216 offset:45056
	ds_read_b128 v[172:175], v216 offset:47104
	s_setprio 1
	s_waitcnt lgkmcnt(3)
	v_mfma_f32_16x16x32_bf16 v[62:65], v[136:139], v[160:163], v[62:65]
	v_mfma_f32_16x16x32_bf16 v[58:61], v[140:143], v[160:163], v[58:61]
	v_mfma_f32_16x16x32_bf16 v[54:57], v[152:155], v[160:163], v[54:57]
	v_mfma_f32_16x16x32_bf16 v[50:53], v[156:159], v[160:163], v[50:53]
	s_waitcnt lgkmcnt(2)
	v_mfma_f32_16x16x32_bf16 v[46:49], v[136:139], v[164:167], v[46:49]
	v_mfma_f32_16x16x32_bf16 v[42:45], v[140:143], v[164:167], v[42:45]
	v_mfma_f32_16x16x32_bf16 v[38:41], v[152:155], v[164:167], v[38:41]
	v_mfma_f32_16x16x32_bf16 v[34:37], v[156:159], v[164:167], v[34:37]
	s_waitcnt lgkmcnt(1)
	v_mfma_f32_16x16x32_bf16 v[30:33], v[136:139], v[168:171], v[30:33]
	v_mfma_f32_16x16x32_bf16 v[26:29], v[140:143], v[168:171], v[26:29]
	v_mfma_f32_16x16x32_bf16 v[22:25], v[152:155], v[168:171], v[22:25]
	v_mfma_f32_16x16x32_bf16 v[18:21], v[156:159], v[168:171], v[18:21]
	s_waitcnt lgkmcnt(0)
	v_mfma_f32_16x16x32_bf16 v[14:17], v[136:139], v[172:175], v[14:17]
	v_mfma_f32_16x16x32_bf16 v[10:13], v[140:143], v[172:175], v[10:13]
	v_mfma_f32_16x16x32_bf16 v[6:9], v[152:155], v[172:175], v[6:9]
	v_mfma_f32_16x16x32_bf16 v[2:5], v[156:159], v[172:175], v[2:5]
	s_setprio 0
	v_add_u32_e32 v152, s47, v150
	v_mul_hi_i32 v136, v152, s40
	v_lshrrev_b32_e32 v137, 31, v136
	v_ashrrev_i32_e32 v136, 11, v136
	v_add_u32_e32 v137, v136, v137
	v_mad_i32_i24 v142, v137, s41, v152
	v_lshlrev_b32_e32 v139, 13, v137
	v_cmp_lt_i32_e32 vcc, s42, v142
	v_add3_u32 v138, v139, v142, s43
	s_barrier
	s_and_saveexec_b64 s[8:9], vcc
	s_xor_b64 s[8:9], exec, s[8:9]
	v_add3_u32 v136, v139, v142, s43
	s_or_saveexec_b64 s[8:9], s[8:9]
	v_mov_b64_e32 v[140:141], s[84:85]
	v_lshl_add_u32 v139, v137, 8, v142
	s_xor_b64 exec, exec, s[8:9]
	v_lshl_add_u32 v136, v137, 8, v142
	v_mov_b64_e32 v[140:141], s[4:5]
	s_or_b64 exec, exec, s[8:9]
	s_and_saveexec_b64 s[8:9], vcc
	s_xor_b64 s[8:9], exec, s[8:9]
	s_cbranch_execz .LBB0_386
	v_mul_hi_i32_i24_e32 v143, 0x6000, v137
	v_mul_i32_i24_e32 v142, 0x6000, v137
	s_or_saveexec_b64 s[8:9], s[8:9]
	v_mov_b64_e32 v[144:145], s[84:85]
	s_xor_b64 exec, exec, s[8:9]
	s_cbranch_execnz .LBB0_387
	s_branch .LBB0_388

.LBB0_639:
	s_add_u32 s0, s86, 0x3c50000
	v_lshlrev_b32_e32 v4, 4, v2
	s_addc_u32 s1, s87, 0
	s_and_b32 s6, s2, 7
	v_and_b32_e32 v4, 0x70, v4
	v_mov_b32_e32 v5, 0
	s_mul_i32 s10, s6, 33
	v_lshl_add_u64 v[6:7], s[86:87], 0, v[4:5]
	s_mov_b64 s[6:7], 0x14c50000
	v_lshrrev_b32_e32 v1, 3, v2
	v_lshl_add_u64 v[130:131], v[6:7], 0, s[6:7]
	s_mov_b64 s[6:7], 0x2d80000
	v_lshl_add_u64 v[132:133], v[6:7], 0, s[6:7]
	v_mul_u32_u24_e32 v6, 0x48, v1
	v_lshlrev_b32_e32 v6, 1, v6
	s_add_i32 s6, 0, 0x12000
	v_add3_u32 v146, 0, v6, v4
	v_add3_u32 v147, s6, v6, v4
	v_and_b32_e32 v4, 15, v2
	v_lshrrev_b32_e32 v6, 1, v2
	s_movk_i32 s7, 0x180
	v_and_or_b32 v4, v6, s7, v4
	v_mul_u32_u24_e32 v4, 0x90, v4
	v_and_b32_e32 v6, 48, v2
	v_add3_u32 v148, 0, v4, v6
	v_and_b32_e32 v4, 0xcf, v2
	v_mov_b32_e32 v3, v2
	v_mul_u32_u24_e32 v4, 0x90, v4
	s_lshr_b32 s3, s2, 3
	s_add_i32 s10, s10, 1
	v_add3_u32 v149, s6, v4, v6
	v_lshrrev_b32_e32 v4, 1, v1
	v_and_b32_e32 v4, 7, v4
	v_and_b32_e32 v7, 7, v2
	v_xor_b32_e32 v4, v4, v7
	v_lshlrev_b32_e32 v4, 4, v4
	v_lshl_add_u32 v146, v1, 7, v4
	v_add_u32_e32 v147, 0x10000, v146
	v_and_b32_e32 v4, 15, v2
	v_lshrrev_b32_e32 v7, 1, v4
	v_bfe_u32 v216, v2, 4, 2
	v_xor_b32_e32 v7, v7, v216
	v_lshlrev_b32_e32 v7, 4, v7
	v_lshrrev_b32_e32 v216, 8, v2
	v_lshl_add_u32 v216, v216, 7, v4
	v_lshl_add_u32 v148, v216, 7, v7
	v_xor_b32_e32 v216, 64, v148
	v_bfe_u32 v217, v2, 6, 2
	v_lshl_add_u32 v217, v217, 6, v4
	v_lshl_add_u32 v149, v217, 7, v7
	v_add_u32_e32 v149, 0x10000, v149
	v_xor_b32_e32 v217, 64, v149
	v_ashrrev_i32_e32 v4, 1, v3
	v_and_b32_e32 v7, 15, v3
	s_movk_i32 s6, 0xff80
	v_and_b32_e32 v2, 7, v2
	v_and_b32_e32 v6, 0xc0, v3
	v_and_or_b32 v150, v4, s6, v7
	s_add_u32 s6, s86, 0x2fb8000
	v_lshrrev_b32_e32 v3, 2, v3
	v_lshlrev_b32_e32 v4, 4, v2
	s_addc_u32 s7, s87, 0
	v_and_or_b32 v151, v3, 12, v6
	s_ashr_i32 s11, s33, 3
	v_lshl_add_u64 v[134:135], s[86:87], 0, v[4:5]
	s_mov_b32 s12, 0x20000
	s_mov_b32 s13, 0x40000
	s_mov_b32 s14, 0x60000
	s_mov_b32 s15, 0x14c50000
	s_waitcnt lgkmcnt(0)
	s_mov_b32 s16, 0x14c70000
	s_mov_b32 s17, 0x14c90000
	s_mov_b32 s18, 0x14cb0000
	s_mov_b32 s19, 0x2d80000
	s_mov_b32 s20, 0x2da0000
	s_mov_b32 s21, 0x2dc0000
	s_mov_b32 s22, 0x2de0000
	s_mov_b32 s23, 0x3e0f83e1
	s_movk_i32 s24, 0xdf00
	s_movk_i32 s25, 0xff
	s_movk_i32 s26, 0xff00
	s_branch .LBB0_642

.LBB0_645:
	s_lshl_b32 s36, s28, 8
	v_or_b32_e32 v2, s36, v1
	v_ashrrev_i32_e32 v3, 31, v2
	v_lshlrev_b64 v[62:63], 11, v[2:3]
	v_lshl_add_u64 v[2:3], v[130:131], 0, v[62:63]
	v_add_co_u32_e32 v6, vcc, 0x20000, v2
	s_lshl_b32 s29, s27, 8
	s_nop 0
	v_addc_co_u32_e32 v7, vcc, 0, v3, vcc
	v_or_b32_e32 v4, s29, v1
	global_load_dwordx4 v[30:33], v[2:3], off
	global_load_dwordx4 v[34:37], v[6:7], off
	v_add_co_u32_e32 v6, vcc, 0x40000, v2
	v_ashrrev_i32_e32 v5, 31, v4
	s_nop 0
	v_addc_co_u32_e32 v7, vcc, 0, v3, vcc
	v_lshlrev_b64 v[64:65], 11, v[4:5]
	v_add_co_u32_e32 v2, vcc, 0x60000, v2
	v_lshl_add_u64 v[4:5], v[132:133], 0, v[64:65]
	s_nop 0
	v_addc_co_u32_e32 v3, vcc, 0, v3, vcc
	global_load_dwordx4 v[38:41], v[6:7], off
	global_load_dwordx4 v[42:45], v[2:3], off
	v_add_co_u32_e32 v2, vcc, s12, v4
	s_waitcnt vmcnt(63) expcnt(7) lgkmcnt(15)
	s_nop 0
	v_addc_co_u32_e32 v3, vcc, 0, v5, vcc
	s_barrier
	global_load_dwordx4 v[46:49], v[4:5], off
	global_load_dwordx4 v[50:53], v[2:3], off
	v_add_co_u32_e32 v2, vcc, s13, v4
	s_mov_b32 s37, 0
	s_nop 0
	v_addc_co_u32_e32 v3, vcc, 0, v5, vcc
	v_add_co_u32_e32 v4, vcc, s14, v4
	s_mov_b64 s[8:9], 0
	s_nop 0
	v_addc_co_u32_e32 v5, vcc, 0, v5, vcc
	global_load_dwordx4 v[54:57], v[2:3], off
	global_load_dwordx4 v[58:61], v[4:5], off
	v_mov_b32_e32 v2, 0
	v_mov_b32_e32 v3, v2
	v_mov_b32_e32 v4, v2
	v_mov_b32_e32 v5, v2
	v_mov_b32_e32 v6, v2
	v_mov_b32_e32 v7, v2
	v_mov_b32_e32 v8, v2
	v_mov_b32_e32 v9, v2
	v_mov_b32_e32 v10, v2
	v_mov_b32_e32 v11, v2
	v_mov_b32_e32 v12, v2
	v_mov_b32_e32 v13, v2
	v_mov_b32_e32 v14, v2
	v_mov_b32_e32 v15, v2
	v_mov_b32_e32 v16, v2
	v_mov_b32_e32 v17, v2
	v_mov_b32_e32 v18, v2
	v_mov_b32_e32 v19, v2
	v_mov_b32_e32 v20, v2
	v_mov_b32_e32 v21, v2
	v_mov_b32_e32 v22, v2
	v_mov_b32_e32 v23, v2
	v_mov_b32_e32 v24, v2
	v_mov_b32_e32 v25, v2
	v_mov_b32_e32 v26, v2
	v_mov_b32_e32 v27, v2
	v_mov_b32_e32 v28, v2
	v_lshl_add_u64 v[136:137], v[134:135], 0, v[62:63]
	v_lshl_add_u64 v[138:139], v[134:135], 0, v[64:65]
	v_mov_b32_e32 v29, v2
	v_mov_b32_e32 v62, v2
	v_mov_b32_e32 v63, v2
	v_mov_b32_e32 v64, v2
	v_mov_b32_e32 v65, v2
	v_mov_b32_e32 v66, v2
	v_mov_b32_e32 v67, v2
	v_mov_b32_e32 v68, v2
	v_mov_b32_e32 v69, v2
	v_mov_b32_e32 v70, v2
	v_mov_b32_e32 v71, v2
	v_mov_b32_e32 v72, v2
	v_mov_b32_e32 v73, v2
	v_mov_b32_e32 v74, v2
	v_mov_b32_e32 v75, v2
	v_mov_b32_e32 v76, v2
	v_mov_b32_e32 v77, v2
	v_mov_b32_e32 v78, v2
	v_mov_b32_e32 v79, v2
	v_mov_b32_e32 v80, v2
	v_mov_b32_e32 v81, v2
	v_mov_b32_e32 v82, v2
	v_mov_b32_e32 v83, v2
	v_mov_b32_e32 v84, v2
	s_waitcnt vmcnt(7)
	ds_write_b128 v146, v[30:33]
	s_waitcnt vmcnt(6)
	ds_write_b128 v146, v[34:37] offset:8192
	s_waitcnt vmcnt(5)
	ds_write_b128 v146, v[38:41] offset:16384
	s_waitcnt vmcnt(4)
	ds_write_b128 v146, v[42:45] offset:24576
	s_waitcnt vmcnt(3)
	ds_write_b128 v147, v[46:49]
	s_waitcnt vmcnt(2)
	ds_write_b128 v147, v[50:53] offset:8192
	s_waitcnt vmcnt(1)
	ds_write_b128 v147, v[54:57] offset:16384
	s_waitcnt vmcnt(0)
	ds_write_b128 v147, v[58:61] offset:24576
	v_mov_b32_e32 v30, v2
	v_mov_b32_e32 v31, v2
	v_mov_b32_e32 v32, v2
	v_mov_b32_e32 v33, v2
	v_mov_b32_e32 v34, v2
	v_mov_b32_e32 v35, v2
	v_mov_b32_e32 v36, v2
	v_mov_b32_e32 v37, v2
	v_mov_b32_e32 v38, v2
	v_mov_b32_e32 v39, v2
	v_mov_b32_e32 v40, v2
	v_mov_b32_e32 v41, v2
	v_mov_b32_e32 v42, v2
	v_mov_b32_e32 v43, v2
	v_mov_b32_e32 v44, v2
	v_mov_b32_e32 v45, v2
	v_mov_b32_e32 v46, v2
	v_mov_b32_e32 v47, v2
	v_mov_b32_e32 v48, v2
	v_mov_b32_e32 v49, v2
	v_mov_b32_e32 v50, v2
	v_mov_b32_e32 v51, v2
	v_mov_b32_e32 v52, v2
	v_mov_b32_e32 v53, v2
	v_mov_b32_e32 v54, v2
	v_mov_b32_e32 v55, v2
	v_mov_b32_e32 v56, v2
	v_mov_b32_e32 v57, v2
	v_mov_b32_e32 v58, v2
	v_mov_b32_e32 v59, v2
	v_mov_b32_e32 v60, v2
	v_mov_b32_e32 v61, v2
	v_mov_b32_e32 v85, v2
	v_mov_b32_e32 v86, v2
	v_mov_b32_e32 v87, v2
	v_mov_b32_e32 v88, v2
	v_mov_b32_e32 v89, v2
	v_mov_b32_e32 v90, v2
	v_mov_b32_e32 v91, v2
	v_mov_b32_e32 v92, v2
	v_mov_b32_e32 v93, v2
	v_mov_b32_e32 v94, v2
	v_mov_b32_e32 v95, v2
	v_mov_b32_e32 v96, v2
	v_mov_b32_e32 v97, v2
	v_mov_b32_e32 v98, v2
	v_mov_b32_e32 v99, v2
	v_mov_b32_e32 v100, v2
	v_mov_b32_e32 v101, v2
	v_mov_b32_e32 v102, v2
	v_mov_b32_e32 v103, v2
	v_mov_b32_e32 v104, v2
	v_mov_b32_e32 v105, v2
	v_mov_b32_e32 v106, v2
	v_mov_b32_e32 v107, v2
	v_mov_b32_e32 v108, v2
	v_mov_b32_e32 v109, v2
	v_mov_b32_e32 v110, v2
	v_mov_b32_e32 v111, v2
	v_mov_b32_e32 v112, v2
	v_mov_b32_e32 v113, v2
	v_mov_b32_e32 v114, v2
	v_mov_b32_e32 v115, v2
	v_mov_b32_e32 v116, v2
	v_mov_b32_e32 v117, v2
	v_mov_b32_e32 v118, v2
	v_mov_b32_e32 v119, v2
	v_mov_b32_e32 v120, v2
	v_mov_b32_e32 v121, v2
	v_mov_b32_e32 v122, v2
	v_mov_b32_e32 v123, v2
	v_mov_b32_e32 v124, v2
	v_mov_b32_e32 v125, v2
	v_mov_b32_e32 v126, v2
	v_mov_b32_e32 v127, v2
	v_mov_b32_e32 v128, v2
	v_mov_b32_e32 v129, v2
	s_waitcnt lgkmcnt(0)
	s_barrier
	v_lshl_add_u64 v[140:141], v[136:137], 0, s[8:9]
	v_add_co_u32_e32 v142, vcc, s15, v140
	s_nop 1
	v_addc_co_u32_e32 v143, vcc, 0, v141, vcc
	v_add_co_u32_e32 v144, vcc, s16, v140
	s_nop 1
	v_addc_co_u32_e32 v145, vcc, 0, v141, vcc
	v_add_co_u32_e32 v156, vcc, s17, v140
	s_nop 1
	v_addc_co_u32_e32 v157, vcc, 0, v141, vcc
	v_add_co_u32_e32 v160, vcc, s18, v140
	s_nop 1
	v_addc_co_u32_e32 v161, vcc, 0, v141, vcc
	global_load_dwordx4 v[140:143], v[142:143], off offset:128
	global_load_dwordx4 v[152:155], v[144:145], off offset:128
	global_load_dwordx4 v[156:159], v[156:157], off offset:128
	global_load_dwordx4 v[160:163], v[160:161], off offset:128
	v_lshl_add_u64 v[144:145], v[138:139], 0, s[8:9]
	v_add_co_u32_e32 v164, vcc, s19, v144
	s_nop 1
	v_addc_co_u32_e32 v165, vcc, 0, v145, vcc
	v_add_co_u32_e32 v168, vcc, s20, v144
	s_nop 1
	v_addc_co_u32_e32 v169, vcc, 0, v145, vcc
	v_add_co_u32_e32 v172, vcc, s21, v144
	s_nop 1
	v_addc_co_u32_e32 v173, vcc, 0, v145, vcc
	v_add_co_u32_e32 v144, vcc, s22, v144
	s_nop 1
	v_addc_co_u32_e32 v145, vcc, 0, v145, vcc
	global_load_dwordx4 v[164:167], v[164:165], off offset:128
	global_load_dwordx4 v[168:171], v[168:169], off offset:128
	global_load_dwordx4 v[172:175], v[172:173], off offset:128
	global_load_dwordx4 v[176:179], v[144:145], off offset:128
	v_mov_b32_e32 v223, v148
	v_mov_b32_e32 v248, v216
	v_mov_b32_e32 v249, v149
	v_mov_b32_e32 v250, v217
	v_xor_b32_e32 v251, 0x8000, v146
	v_xor_b32_e32 v252, 0x8000, v147
	ds_read_b128 v[180:183], v223
	ds_read_b128 v[184:187], v223 offset:2048
	ds_read_b128 v[188:191], v223 offset:4096
	ds_read_b128 v[192:195], v223 offset:6144
	ds_read_b128 v[212:215], v249
	ds_read_b128 v[218:221], v249 offset:2048
	ds_read_b128 v[224:227], v249 offset:4096
	ds_read_b128 v[228:231], v249 offset:6144
.Lg2_p12_loop:
	ds_read_b128 v[196:199], v223 offset:8192
	ds_read_b128 v[200:203], v223 offset:10240
	ds_read_b128 v[204:207], v223 offset:12288
	ds_read_b128 v[208:211], v223 offset:14336
	s_waitcnt lgkmcnt(4)
	v_mfma_f32_16x16x32_bf16 v[126:129], v[212:215], v[180:183], v[126:129]
	v_mfma_f32_16x16x32_bf16 v[122:125], v[218:221], v[180:183], v[122:125]
	v_mfma_f32_16x16x32_bf16 v[118:121], v[224:227], v[180:183], v[118:121]
	v_mfma_f32_16x16x32_bf16 v[114:117], v[228:231], v[180:183], v[114:117]
	v_mfma_f32_16x16x32_bf16 v[110:113], v[212:215], v[184:187], v[110:113]
	v_mfma_f32_16x16x32_bf16 v[106:109], v[218:221], v[184:187], v[106:109]
	v_mfma_f32_16x16x32_bf16 v[102:105], v[224:227], v[184:187], v[102:105]
	v_mfma_f32_16x16x32_bf16 v[98:101], v[228:231], v[184:187], v[98:101]
	v_mfma_f32_16x16x32_bf16 v[94:97], v[212:215], v[188:191], v[94:97]
	v_mfma_f32_16x16x32_bf16 v[90:93], v[218:221], v[188:191], v[90:93]
	v_mfma_f32_16x16x32_bf16 v[86:89], v[224:227], v[188:191], v[86:89]
	v_mfma_f32_16x16x32_bf16 v[82:85], v[228:231], v[188:191], v[82:85]
	v_mfma_f32_16x16x32_bf16 v[78:81], v[212:215], v[192:195], v[78:81]
	v_mfma_f32_16x16x32_bf16 v[74:77], v[218:221], v[192:195], v[74:77]
	v_mfma_f32_16x16x32_bf16 v[70:73], v[224:227], v[192:195], v[70:73]
	v_mfma_f32_16x16x32_bf16 v[66:69], v[228:231], v[192:195], v[66:69]
	ds_read_b128 v[180:183], v248
	ds_read_b128 v[184:187], v248 offset:2048
	ds_read_b128 v[188:191], v248 offset:4096
	ds_read_b128 v[192:195], v248 offset:6144
	ds_read_b128 v[232:235], v250
	ds_read_b128 v[236:239], v250 offset:2048
	ds_read_b128 v[240:243], v250 offset:4096
	ds_read_b128 v[244:247], v250 offset:6144
	s_waitcnt lgkmcnt(8)
	v_mfma_f32_16x16x32_bf16 v[62:65], v[212:215], v[196:199], v[62:65]
	v_mfma_f32_16x16x32_bf16 v[58:61], v[218:221], v[196:199], v[58:61]
	v_mfma_f32_16x16x32_bf16 v[54:57], v[224:227], v[196:199], v[54:57]
	v_mfma_f32_16x16x32_bf16 v[50:53], v[228:231], v[196:199], v[50:53]
	v_mfma_f32_16x16x32_bf16 v[46:49], v[212:215], v[200:203], v[46:49]
	v_mfma_f32_16x16x32_bf16 v[42:45], v[218:221], v[200:203], v[42:45]
	v_mfma_f32_16x16x32_bf16 v[38:41], v[224:227], v[200:203], v[38:41]
	v_mfma_f32_16x16x32_bf16 v[34:37], v[228:231], v[200:203], v[34:37]
	v_mfma_f32_16x16x32_bf16 v[30:33], v[212:215], v[204:207], v[30:33]
	v_mfma_f32_16x16x32_bf16 v[26:29], v[218:221], v[204:207], v[26:29]
	v_mfma_f32_16x16x32_bf16 v[22:25], v[224:227], v[204:207], v[22:25]
	v_mfma_f32_16x16x32_bf16 v[18:21], v[228:231], v[204:207], v[18:21]
	v_mfma_f32_16x16x32_bf16 v[14:17], v[212:215], v[208:211], v[14:17]
	v_mfma_f32_16x16x32_bf16 v[10:13], v[218:221], v[208:211], v[10:13]
	v_mfma_f32_16x16x32_bf16 v[6:9], v[224:227], v[208:211], v[6:9]
	v_mfma_f32_16x16x32_bf16 v[2:5], v[228:231], v[208:211], v[2:5]
	ds_read_b128 v[196:199], v248 offset:8192
	ds_read_b128 v[200:203], v248 offset:10240
	ds_read_b128 v[204:207], v248 offset:12288
	ds_read_b128 v[208:211], v248 offset:14336
	s_waitcnt lgkmcnt(4)
	v_mfma_f32_16x16x32_bf16 v[126:129], v[232:235], v[180:183], v[126:129]
	v_mfma_f32_16x16x32_bf16 v[122:125], v[236:239], v[180:183], v[122:125]
	s_waitcnt vmcnt(7)
	ds_write_b128 v251, v[140:143]
	v_mfma_f32_16x16x32_bf16 v[118:121], v[240:243], v[180:183], v[118:121]
	v_mfma_f32_16x16x32_bf16 v[114:117], v[244:247], v[180:183], v[114:117]
	s_waitcnt vmcnt(6)
	ds_write_b128 v251, v[152:155] offset:8192
	v_mfma_f32_16x16x32_bf16 v[110:113], v[232:235], v[184:187], v[110:113]
	v_mfma_f32_16x16x32_bf16 v[106:109], v[236:239], v[184:187], v[106:109]
	s_waitcnt vmcnt(5)
	ds_write_b128 v251, v[156:159] offset:16384
	v_mfma_f32_16x16x32_bf16 v[102:105], v[240:243], v[184:187], v[102:105]
	v_mfma_f32_16x16x32_bf16 v[98:101], v[244:247], v[184:187], v[98:101]
	s_waitcnt vmcnt(4)
	ds_write_b128 v251, v[160:163] offset:24576
	v_mfma_f32_16x16x32_bf16 v[94:97], v[232:235], v[188:191], v[94:97]
	v_mfma_f32_16x16x32_bf16 v[90:93], v[236:239], v[188:191], v[90:93]
	s_waitcnt vmcnt(3)
	ds_write_b128 v252, v[164:167]
	v_mfma_f32_16x16x32_bf16 v[86:89], v[240:243], v[188:191], v[86:89]
	v_mfma_f32_16x16x32_bf16 v[82:85], v[244:247], v[188:191], v[82:85]
	s_waitcnt vmcnt(2)
	ds_write_b128 v252, v[168:171] offset:8192
	v_mfma_f32_16x16x32_bf16 v[78:81], v[232:235], v[192:195], v[78:81]
	v_mfma_f32_16x16x32_bf16 v[74:77], v[236:239], v[192:195], v[74:77]
	s_waitcnt vmcnt(1)
	ds_write_b128 v252, v[172:175] offset:16384
	v_mfma_f32_16x16x32_bf16 v[70:73], v[240:243], v[192:195], v[70:73]
	v_mfma_f32_16x16x32_bf16 v[66:69], v[244:247], v[192:195], v[66:69]
	s_waitcnt vmcnt(0)
	ds_write_b128 v252, v[176:179] offset:24576
	s_waitcnt lgkmcnt(0)
	s_barrier
	s_add_u32 s8, s8, 0x80
	s_addc_u32 s9, s9, 0
	s_cmpk_eq_i32 s8, 0x780
	s_cbranch_scc1 .Lg2_p12_tail
	v_xor_b32_e32 v223, 0x8000, v223
	v_xor_b32_e32 v249, 0x8000, v249
	v_xor_b32_e32 v248, 0x8000, v248
	v_xor_b32_e32 v250, 0x8000, v250
	v_xor_b32_e32 v251, 0x8000, v251
	v_xor_b32_e32 v252, 0x8000, v252
	ds_read_b128 v[180:183], v223
	ds_read_b128 v[184:187], v223 offset:2048
	ds_read_b128 v[188:191], v223 offset:4096
	ds_read_b128 v[192:195], v223 offset:6144
	ds_read_b128 v[212:215], v249
	ds_read_b128 v[218:221], v249 offset:2048
	ds_read_b128 v[224:227], v249 offset:4096
	ds_read_b128 v[228:231], v249 offset:6144
	v_mfma_f32_16x16x32_bf16 v[62:65], v[232:235], v[196:199], v[62:65]
	v_lshl_add_u64 v[140:141], v[136:137], 0, s[8:9]
	v_add_co_u32_e32 v142, vcc, s15, v140
	v_mfma_f32_16x16x32_bf16 v[58:61], v[236:239], v[196:199], v[58:61]
	s_nop 1
	v_addc_co_u32_e32 v143, vcc, 0, v141, vcc
	v_mfma_f32_16x16x32_bf16 v[54:57], v[240:243], v[196:199], v[54:57]
	v_add_co_u32_e32 v144, vcc, s16, v140
	s_nop 1
	v_mfma_f32_16x16x32_bf16 v[50:53], v[244:247], v[196:199], v[50:53]
	v_addc_co_u32_e32 v145, vcc, 0, v141, vcc
	v_add_co_u32_e32 v156, vcc, s17, v140
	v_mfma_f32_16x16x32_bf16 v[46:49], v[232:235], v[200:203], v[46:49]
	s_nop 1
	v_addc_co_u32_e32 v157, vcc, 0, v141, vcc
	v_mfma_f32_16x16x32_bf16 v[42:45], v[236:239], v[200:203], v[42:45]
	v_add_co_u32_e32 v160, vcc, s18, v140
	s_nop 1
	v_mfma_f32_16x16x32_bf16 v[38:41], v[240:243], v[200:203], v[38:41]
	v_addc_co_u32_e32 v161, vcc, 0, v141, vcc
	global_load_dwordx4 v[140:143], v[142:143], off offset:128
	v_mfma_f32_16x16x32_bf16 v[34:37], v[244:247], v[200:203], v[34:37]
	global_load_dwordx4 v[152:155], v[144:145], off offset:128
	global_load_dwordx4 v[156:159], v[156:157], off offset:128
	global_load_dwordx4 v[160:163], v[160:161], off offset:128
	v_mfma_f32_16x16x32_bf16 v[30:33], v[232:235], v[204:207], v[30:33]
	v_lshl_add_u64 v[144:145], v[138:139], 0, s[8:9]
	v_add_co_u32_e32 v164, vcc, s19, v144
	v_mfma_f32_16x16x32_bf16 v[26:29], v[236:239], v[204:207], v[26:29]
	s_nop 1
	v_addc_co_u32_e32 v165, vcc, 0, v145, vcc
	v_mfma_f32_16x16x32_bf16 v[22:25], v[240:243], v[204:207], v[22:25]
	v_add_co_u32_e32 v168, vcc, s20, v144
	s_nop 1
	v_mfma_f32_16x16x32_bf16 v[18:21], v[244:247], v[204:207], v[18:21]
	v_addc_co_u32_e32 v169, vcc, 0, v145, vcc
	v_add_co_u32_e32 v172, vcc, s21, v144
	v_mfma_f32_16x16x32_bf16 v[14:17], v[232:235], v[208:211], v[14:17]
	s_nop 1
	v_addc_co_u32_e32 v173, vcc, 0, v145, vcc
	v_mfma_f32_16x16x32_bf16 v[10:13], v[236:239], v[208:211], v[10:13]
	v_add_co_u32_e32 v144, vcc, s22, v144
	s_nop 1
	v_mfma_f32_16x16x32_bf16 v[6:9], v[240:243], v[208:211], v[6:9]
	v_addc_co_u32_e32 v145, vcc, 0, v145, vcc
	global_load_dwordx4 v[164:167], v[164:165], off offset:128
	v_mfma_f32_16x16x32_bf16 v[2:5], v[244:247], v[208:211], v[2:5]
	global_load_dwordx4 v[168:171], v[168:169], off offset:128
	global_load_dwordx4 v[172:175], v[172:173], off offset:128
	global_load_dwordx4 v[176:179], v[144:145], off offset:128
	s_branch .Lg2_p12_loop
.Lg2_p12_tail:
	v_mfma_f32_16x16x32_bf16 v[62:65], v[232:235], v[196:199], v[62:65]
	v_mfma_f32_16x16x32_bf16 v[58:61], v[236:239], v[196:199], v[58:61]
	v_mfma_f32_16x16x32_bf16 v[54:57], v[240:243], v[196:199], v[54:57]
	v_mfma_f32_16x16x32_bf16 v[50:53], v[244:247], v[196:199], v[50:53]
	v_mfma_f32_16x16x32_bf16 v[46:49], v[232:235], v[200:203], v[46:49]
	v_mfma_f32_16x16x32_bf16 v[42:45], v[236:239], v[200:203], v[42:45]
	v_mfma_f32_16x16x32_bf16 v[38:41], v[240:243], v[200:203], v[38:41]
	v_mfma_f32_16x16x32_bf16 v[34:37], v[244:247], v[200:203], v[34:37]
	v_mfma_f32_16x16x32_bf16 v[30:33], v[232:235], v[204:207], v[30:33]
	v_mfma_f32_16x16x32_bf16 v[26:29], v[236:239], v[204:207], v[26:29]
	v_mfma_f32_16x16x32_bf16 v[22:25], v[240:243], v[204:207], v[22:25]
	v_mfma_f32_16x16x32_bf16 v[18:21], v[244:247], v[204:207], v[18:21]
	v_mfma_f32_16x16x32_bf16 v[14:17], v[232:235], v[208:211], v[14:17]
	v_mfma_f32_16x16x32_bf16 v[10:13], v[236:239], v[208:211], v[10:13]
	v_mfma_f32_16x16x32_bf16 v[6:9], v[240:243], v[208:211], v[6:9]
	v_mfma_f32_16x16x32_bf16 v[2:5], v[244:247], v[208:211], v[2:5]
	ds_read_b128 v[136:139], v149 offset:32768
	ds_read_b128 v[140:143], v149 offset:34816
	ds_read_b128 v[152:155], v149 offset:36864
	ds_read_b128 v[156:159], v149 offset:38912
	ds_read_b128 v[160:163], v148 offset:32768
	ds_read_b128 v[164:167], v148 offset:34816
	ds_read_b128 v[168:171], v148 offset:36864
	ds_read_b128 v[172:175], v148 offset:38912
	s_setprio 1
	s_waitcnt lgkmcnt(3)
	v_mfma_f32_16x16x32_bf16 v[126:129], v[136:139], v[160:163], v[126:129]
	v_mfma_f32_16x16x32_bf16 v[122:125], v[140:143], v[160:163], v[122:125]
	v_mfma_f32_16x16x32_bf16 v[118:121], v[152:155], v[160:163], v[118:121]
	v_mfma_f32_16x16x32_bf16 v[114:117], v[156:159], v[160:163], v[114:117]
	s_waitcnt lgkmcnt(2)
	v_mfma_f32_16x16x32_bf16 v[110:113], v[136:139], v[164:167], v[110:113]
	v_mfma_f32_16x16x32_bf16 v[106:109], v[140:143], v[164:167], v[106:109]
	v_mfma_f32_16x16x32_bf16 v[102:105], v[152:155], v[164:167], v[102:105]
	v_mfma_f32_16x16x32_bf16 v[98:101], v[156:159], v[164:167], v[98:101]
	s_waitcnt lgkmcnt(1)
	v_mfma_f32_16x16x32_bf16 v[94:97], v[136:139], v[168:171], v[94:97]
	v_mfma_f32_16x16x32_bf16 v[90:93], v[140:143], v[168:171], v[90:93]
	v_mfma_f32_16x16x32_bf16 v[86:89], v[152:155], v[168:171], v[86:89]
	v_mfma_f32_16x16x32_bf16 v[82:85], v[156:159], v[168:171], v[82:85]
	s_waitcnt lgkmcnt(0)
	v_mfma_f32_16x16x32_bf16 v[78:81], v[136:139], v[172:175], v[78:81]
	v_mfma_f32_16x16x32_bf16 v[74:77], v[140:143], v[172:175], v[74:77]
	v_mfma_f32_16x16x32_bf16 v[70:73], v[152:155], v[172:175], v[70:73]
	v_mfma_f32_16x16x32_bf16 v[66:69], v[156:159], v[172:175], v[66:69]
	s_setprio 0
	ds_read_b128 v[160:163], v148 offset:40960
	ds_read_b128 v[164:167], v148 offset:43008
	ds_read_b128 v[168:171], v148 offset:45056
	ds_read_b128 v[172:175], v148 offset:47104
	s_setprio 1
	s_waitcnt lgkmcnt(3)
	v_mfma_f32_16x16x32_bf16 v[62:65], v[136:139], v[160:163], v[62:65]
	v_mfma_f32_16x16x32_bf16 v[58:61], v[140:143], v[160:163], v[58:61]
	v_mfma_f32_16x16x32_bf16 v[54:57], v[152:155], v[160:163], v[54:57]
	v_mfma_f32_16x16x32_bf16 v[50:53], v[156:159], v[160:163], v[50:53]
	s_waitcnt lgkmcnt(2)
	v_mfma_f32_16x16x32_bf16 v[46:49], v[136:139], v[164:167], v[46:49]
	v_mfma_f32_16x16x32_bf16 v[42:45], v[140:143], v[164:167], v[42:45]
	v_mfma_f32_16x16x32_bf16 v[38:41], v[152:155], v[164:167], v[38:41]
	v_mfma_f32_16x16x32_bf16 v[34:37], v[156:159], v[164:167], v[34:37]
	s_waitcnt lgkmcnt(1)
	v_mfma_f32_16x16x32_bf16 v[30:33], v[136:139], v[168:171], v[30:33]
	v_mfma_f32_16x16x32_bf16 v[26:29], v[140:143], v[168:171], v[26:29]
	v_mfma_f32_16x16x32_bf16 v[22:25], v[152:155], v[168:171], v[22:25]
	v_mfma_f32_16x16x32_bf16 v[18:21], v[156:159], v[168:171], v[18:21]
	s_waitcnt lgkmcnt(0)
	v_mfma_f32_16x16x32_bf16 v[14:17], v[136:139], v[172:175], v[14:17]
	v_mfma_f32_16x16x32_bf16 v[10:13], v[140:143], v[172:175], v[10:13]
	v_mfma_f32_16x16x32_bf16 v[6:9], v[152:155], v[172:175], v[6:9]
	v_mfma_f32_16x16x32_bf16 v[2:5], v[156:159], v[172:175], v[2:5]
	s_setprio 0
	ds_read_b128 v[136:139], v217 offset:32768
	ds_read_b128 v[140:143], v217 offset:34816
	ds_read_b128 v[152:155], v217 offset:36864
	ds_read_b128 v[156:159], v217 offset:38912
	ds_read_b128 v[160:163], v216 offset:32768
	ds_read_b128 v[164:167], v216 offset:34816
	ds_read_b128 v[168:171], v216 offset:36864
	ds_read_b128 v[172:175], v216 offset:38912
	s_setprio 1
	s_waitcnt lgkmcnt(3)
	v_mfma_f32_16x16x32_bf16 v[126:129], v[136:139], v[160:163], v[126:129]
	v_mfma_f32_16x16x32_bf16 v[122:125], v[140:143], v[160:163], v[122:125]
	v_mfma_f32_16x16x32_bf16 v[118:121], v[152:155], v[160:163], v[118:121]
	v_mfma_f32_16x16x32_bf16 v[114:117], v[156:159], v[160:163], v[114:117]
	s_waitcnt lgkmcnt(2)
	v_mfma_f32_16x16x32_bf16 v[110:113], v[136:139], v[164:167], v[110:113]
	v_mfma_f32_16x16x32_bf16 v[106:109], v[140:143], v[164:167], v[106:109]
	v_mfma_f32_16x16x32_bf16 v[102:105], v[152:155], v[164:167], v[102:105]
	v_mfma_f32_16x16x32_bf16 v[98:101], v[156:159], v[164:167], v[98:101]
	s_waitcnt lgkmcnt(1)
	v_mfma_f32_16x16x32_bf16 v[94:97], v[136:139], v[168:171], v[94:97]
	v_mfma_f32_16x16x32_bf16 v[90:93], v[140:143], v[168:171], v[90:93]
	v_mfma_f32_16x16x32_bf16 v[86:89], v[152:155], v[168:171], v[86:89]
	v_mfma_f32_16x16x32_bf16 v[82:85], v[156:159], v[168:171], v[82:85]
	s_waitcnt lgkmcnt(0)
	v_mfma_f32_16x16x32_bf16 v[78:81], v[136:139], v[172:175], v[78:81]
	v_mfma_f32_16x16x32_bf16 v[74:77], v[140:143], v[172:175], v[74:77]
	v_mfma_f32_16x16x32_bf16 v[70:73], v[152:155], v[172:175], v[70:73]
	v_mfma_f32_16x16x32_bf16 v[66:69], v[156:159], v[172:175], v[66:69]
	s_setprio 0
	ds_read_b128 v[160:163], v216 offset:40960
	ds_read_b128 v[164:167], v216 offset:43008
	ds_read_b128 v[168:171], v216 offset:45056
	ds_read_b128 v[172:175], v216 offset:47104
	s_setprio 1
	s_waitcnt lgkmcnt(3)
	v_mfma_f32_16x16x32_bf16 v[62:65], v[136:139], v[160:163], v[62:65]
	v_mfma_f32_16x16x32_bf16 v[58:61], v[140:143], v[160:163], v[58:61]
	v_mfma_f32_16x16x32_bf16 v[54:57], v[152:155], v[160:163], v[54:57]
	v_mfma_f32_16x16x32_bf16 v[50:53], v[156:159], v[160:163], v[50:53]
	s_waitcnt lgkmcnt(2)
	v_mfma_f32_16x16x32_bf16 v[46:49], v[136:139], v[164:167], v[46:49]
	v_mfma_f32_16x16x32_bf16 v[42:45], v[140:143], v[164:167], v[42:45]
	v_mfma_f32_16x16x32_bf16 v[38:41], v[152:155], v[164:167], v[38:41]
	v_mfma_f32_16x16x32_bf16 v[34:37], v[156:159], v[164:167], v[34:37]
	s_waitcnt lgkmcnt(1)
	v_mfma_f32_16x16x32_bf16 v[30:33], v[136:139], v[168:171], v[30:33]
	v_mfma_f32_16x16x32_bf16 v[26:29], v[140:143], v[168:171], v[26:29]
	v_mfma_f32_16x16x32_bf16 v[22:25], v[152:155], v[168:171], v[22:25]
	v_mfma_f32_16x16x32_bf16 v[18:21], v[156:159], v[168:171], v[18:21]
	s_waitcnt lgkmcnt(0)
	v_mfma_f32_16x16x32_bf16 v[14:17], v[136:139], v[172:175], v[14:17]
	v_mfma_f32_16x16x32_bf16 v[10:13], v[140:143], v[172:175], v[10:13]
	v_mfma_f32_16x16x32_bf16 v[6:9], v[152:155], v[172:175], v[6:9]
	v_mfma_f32_16x16x32_bf16 v[2:5], v[156:159], v[172:175], v[2:5]
	s_setprio 0
	v_add_u32_e32 v152, s36, v150
	v_mul_hi_i32 v136, v152, s23
	v_lshrrev_b32_e32 v137, 31, v136
	v_ashrrev_i32_e32 v136, 11, v136
	v_add_u32_e32 v137, v136, v137
	v_mad_i32_i24 v142, v137, s24, v152
	v_lshlrev_b32_e32 v139, 13, v137
	v_cmp_lt_i32_e32 vcc, s25, v142
	v_add3_u32 v138, v139, v142, s26
	s_barrier
	s_and_saveexec_b64 s[8:9], vcc
	s_xor_b64 s[8:9], exec, s[8:9]
	v_add3_u32 v136, v139, v142, s26
	s_or_saveexec_b64 s[8:9], s[8:9]
	v_mov_b64_e32 v[140:141], s[84:85]
	v_lshl_add_u32 v139, v137, 8, v142
	s_xor_b64 exec, exec, s[8:9]
	v_lshl_add_u32 v136, v137, 8, v142
	v_mov_b64_e32 v[140:141], s[0:1]
	s_or_b64 exec, exec, s[8:9]
	s_and_saveexec_b64 s[8:9], vcc
	s_xor_b64 s[8:9], exec, s[8:9]
	s_cbranch_execz .LBB0_653
	v_mul_hi_i32_i24_e32 v143, 0x6000, v137
	v_mul_i32_i24_e32 v142, 0x6000, v137
	s_or_saveexec_b64 s[8:9], s[8:9]
	v_mov_b64_e32 v[144:145], s[84:85]
	s_xor_b64 exec, exec, s[8:9]
	s_cbranch_execnz .LBB0_654
	s_branch .LBB0_655

.LBB0_749:
	s_mul_hi_i32 s0, s3, 0x2e8ba2e9
	s_lshr_b32 s1, s0, 31
	s_ashr_i32 s0, s0, 4
	s_add_i32 s24, s0, s1
	s_mul_i32 s1, s24, 0xffffffa8
	s_add_i32 s1, s1, s3
	s_ashr_i32 s21, s1, 31
	s_lshl_b32 s0, s24, 2
	s_lshr_b32 s21, s21, 30
	s_add_i32 s21, s1, s21
	s_add_i32 s0, s6, s0
	s_ashr_i32 s22, s21, 2
	s_add_i32 s0, s0, s1
	s_lshl_b32 s25, s22, 10
	s_lshl_b32 s0, s0, 8
	s_sub_i32 s21, s0, s25
	v_or_b32_e32 v2, s21, v1
	v_ashrrev_i32_e32 v3, 31, v2
	v_lshlrev_b64 v[2:3], 11, v[2:3]
	v_lshl_add_u64 v[2:3], v[132:133], 0, v[2:3]
	v_add_co_u32_e32 v6, vcc, s9, v2
	s_lshl_b32 s22, s22, 8
	s_nop 0
	v_addc_co_u32_e32 v7, vcc, 0, v3, vcc
	v_or_b32_e32 v4, s22, v1
	global_load_dwordx4 v[20:23], v[2:3], off
	global_load_dwordx4 v[24:27], v[6:7], off
	v_add_co_u32_e32 v6, vcc, s10, v2
	v_ashrrev_i32_e32 v5, 31, v4
	s_nop 0
	v_addc_co_u32_e32 v7, vcc, 0, v3, vcc
	v_lshlrev_b64 v[52:53], 11, v[4:5]
	v_add_co_u32_e32 v2, vcc, s11, v2
	v_lshl_add_u64 v[4:5], v[134:135], 0, v[52:53]
	s_nop 0
	v_addc_co_u32_e32 v3, vcc, 0, v3, vcc
	global_load_dwordx4 v[28:31], v[6:7], off
	global_load_dwordx4 v[32:35], v[2:3], off
	v_add_co_u32_e32 v2, vcc, s9, v4
	s_waitcnt vmcnt(63) expcnt(7) lgkmcnt(15)
	s_nop 0
	v_addc_co_u32_e32 v3, vcc, 0, v5, vcc
	s_barrier
	global_load_dwordx4 v[36:39], v[4:5], off
	global_load_dwordx4 v[40:43], v[2:3], off
	v_add_co_u32_e32 v2, vcc, s10, v4
	s_mulk_i32 s24, 0x5400
	s_nop 0
	v_addc_co_u32_e32 v3, vcc, 0, v5, vcc
	v_add_co_u32_e32 v4, vcc, s11, v4
	v_subrev_u32_e32 v19, s25, v130
	s_nop 0
	v_addc_co_u32_e32 v5, vcc, 0, v5, vcc
	global_load_dwordx4 v[44:47], v[2:3], off
	global_load_dwordx4 v[48:51], v[4:5], off
	v_subrev_u32_e32 v54, s24, v19
	v_ashrrev_i32_e32 v55, 31, v54
	v_lshlrev_b64 v[54:55], 11, v[54:55]
	s_mov_b64 s[0:1], 0
	s_mov_b32 s23, 0
	v_mov_b32_e32 v2, 0
	v_mov_b32_e32 v3, v131
	v_mov_b32_e32 v4, v131
	v_mov_b32_e32 v5, v131
	v_mov_b32_e32 v6, 0
	v_mov_b32_e32 v7, v131
	v_mov_b32_e32 v8, v131
	v_mov_b32_e32 v9, v131
	v_mov_b32_e32 v10, 0
	v_mov_b32_e32 v11, v131
	v_mov_b32_e32 v12, v131
	v_mov_b32_e32 v13, v131
	v_mov_b32_e32 v14, 0
	v_mov_b32_e32 v15, v131
	v_mov_b32_e32 v16, v131
	v_mov_b32_e32 v17, v131
	v_mov_b32_e32 v18, 0
	v_lshl_add_u64 v[140:141], v[138:139], 0, v[52:53]
	v_lshl_add_u64 v[142:143], v[138:139], 0, v[54:55]
	v_mov_b32_e32 v19, v131
	v_mov_b32_e32 v52, v131
	v_mov_b32_e32 v53, v131
	v_mov_b32_e32 v54, 0
	v_mov_b32_e32 v55, v131
	v_mov_b32_e32 v56, v131
	v_mov_b32_e32 v57, v131
	v_mov_b32_e32 v58, 0
	v_mov_b32_e32 v59, v131
	v_mov_b32_e32 v60, v131
	v_mov_b32_e32 v61, v131
	v_mov_b32_e32 v62, 0
	v_mov_b32_e32 v63, v131
	v_mov_b32_e32 v64, v131
	v_mov_b32_e32 v65, v131
	v_mov_b32_e32 v66, 0
	v_mov_b32_e32 v67, v131
	v_mov_b32_e32 v68, v131
	v_mov_b32_e32 v69, v131
	v_mov_b32_e32 v70, 0
	v_mov_b32_e32 v71, v131
	v_mov_b32_e32 v72, v131
	v_mov_b32_e32 v73, v131
	v_mov_b32_e32 v74, 0
	s_waitcnt vmcnt(7)
	ds_write_b128 v144, v[20:23]
	s_waitcnt vmcnt(6)
	ds_write_b128 v144, v[24:27] offset:8192
	s_waitcnt vmcnt(5)
	ds_write_b128 v144, v[28:31] offset:16384
	s_waitcnt vmcnt(4)
	ds_write_b128 v144, v[32:35] offset:24576
	s_waitcnt vmcnt(3)
	ds_write_b128 v145, v[36:39]
	s_waitcnt vmcnt(2)
	ds_write_b128 v145, v[40:43] offset:8192
	s_waitcnt vmcnt(1)
	ds_write_b128 v145, v[44:47] offset:16384
	s_waitcnt vmcnt(0)
	ds_write_b128 v145, v[48:51] offset:24576
	v_mov_b32_e32 v20, v131
	v_mov_b32_e32 v21, v131
	v_mov_b32_e32 v22, 0
	v_mov_b32_e32 v23, v131
	v_mov_b32_e32 v24, v131
	v_mov_b32_e32 v25, v131
	v_mov_b32_e32 v26, 0
	v_mov_b32_e32 v27, v131
	v_mov_b32_e32 v28, v131
	v_mov_b32_e32 v29, v131
	v_mov_b32_e32 v30, 0
	v_mov_b32_e32 v31, v131
	v_mov_b32_e32 v32, v131
	v_mov_b32_e32 v33, v131
	v_mov_b32_e32 v34, 0
	v_mov_b32_e32 v35, v131
	v_mov_b32_e32 v36, v131
	v_mov_b32_e32 v37, v131
	v_mov_b32_e32 v38, 0
	v_mov_b32_e32 v39, v131
	v_mov_b32_e32 v40, v131
	v_mov_b32_e32 v41, v131
	v_mov_b32_e32 v42, 0
	v_mov_b32_e32 v43, v131
	v_mov_b32_e32 v44, v131
	v_mov_b32_e32 v45, v131
	v_mov_b32_e32 v46, 0
	v_mov_b32_e32 v47, v131
	v_mov_b32_e32 v48, v131
	v_mov_b32_e32 v49, v131
	v_mov_b32_e32 v50, 0
	v_mov_b32_e32 v51, v131
	v_mov_b32_e32 v75, v131
	v_mov_b32_e32 v76, v131
	v_mov_b32_e32 v77, v131
	v_mov_b32_e32 v78, 0
	v_mov_b32_e32 v79, v131
	v_mov_b32_e32 v80, v131
	v_mov_b32_e32 v81, v131
	v_mov_b32_e32 v82, 0
	v_mov_b32_e32 v83, v131
	v_mov_b32_e32 v84, v131
	v_mov_b32_e32 v85, v131
	v_mov_b32_e32 v86, 0
	v_mov_b32_e32 v87, v131
	v_mov_b32_e32 v88, v131
	v_mov_b32_e32 v89, v131
	v_mov_b32_e32 v90, 0
	v_mov_b32_e32 v91, v131
	v_mov_b32_e32 v92, v131
	v_mov_b32_e32 v93, v131
	v_mov_b32_e32 v94, 0
	v_mov_b32_e32 v95, v131
	v_mov_b32_e32 v96, v131
	v_mov_b32_e32 v97, v131
	v_mov_b32_e32 v98, 0
	v_mov_b32_e32 v99, v131
	v_mov_b32_e32 v100, v131
	v_mov_b32_e32 v101, v131
	v_mov_b32_e32 v102, 0
	v_mov_b32_e32 v103, v131
	v_mov_b32_e32 v104, v131
	v_mov_b32_e32 v105, v131
	v_mov_b32_e32 v106, 0
	v_mov_b32_e32 v107, v131
	v_mov_b32_e32 v108, v131
	v_mov_b32_e32 v109, v131
	v_mov_b32_e32 v110, 0
	v_mov_b32_e32 v111, v131
	v_mov_b32_e32 v112, v131
	v_mov_b32_e32 v113, v131
	v_mov_b32_e32 v114, 0
	v_mov_b32_e32 v115, v131
	v_mov_b32_e32 v116, v131
	v_mov_b32_e32 v117, v131
	v_mov_b32_e32 v118, 0
	v_mov_b32_e32 v119, v131
	v_mov_b32_e32 v120, v131
	v_mov_b32_e32 v121, v131
	v_mov_b32_e32 v122, 0
	v_mov_b32_e32 v123, v131
	v_mov_b32_e32 v124, v131
	v_mov_b32_e32 v125, v131
	v_mov_b32_e32 v126, 0
	v_mov_b32_e32 v127, v131
	v_mov_b32_e32 v128, v131
	v_mov_b32_e32 v129, v131
	s_waitcnt lgkmcnt(0)
	s_barrier
	v_lshl_add_u64 v[150:151], v[142:143], 0, s[0:1]
	v_add_co_u32_e32 v152, vcc, s12, v150
	s_nop 1
	v_addc_co_u32_e32 v153, vcc, 0, v151, vcc
	v_add_co_u32_e32 v154, vcc, s13, v150
	s_nop 1
	v_addc_co_u32_e32 v155, vcc, 0, v151, vcc
	v_add_co_u32_e32 v158, vcc, s14, v150
	s_nop 1
	v_addc_co_u32_e32 v159, vcc, 0, v151, vcc
	v_add_co_u32_e32 v162, vcc, s15, v150
	s_nop 1
	v_addc_co_u32_e32 v163, vcc, 0, v151, vcc
	global_load_dwordx4 v[150:153], v[152:153], off offset:128
	global_load_dwordx4 v[154:157], v[154:155], off offset:128
	global_load_dwordx4 v[158:161], v[158:159], off offset:128
	global_load_dwordx4 v[162:165], v[162:163], off offset:128
	v_lshl_add_u64 v[174:175], v[140:141], 0, s[0:1]
	v_add_co_u32_e32 v166, vcc, s16, v174
	s_nop 1
	v_addc_co_u32_e32 v167, vcc, 0, v175, vcc
	v_add_co_u32_e32 v170, vcc, s17, v174
	s_nop 1
	v_addc_co_u32_e32 v171, vcc, 0, v175, vcc
	v_add_co_u32_e32 v176, vcc, s18, v174
	s_nop 1
	v_addc_co_u32_e32 v177, vcc, 0, v175, vcc
	v_add_co_u32_e32 v178, vcc, s19, v174
	s_nop 1
	v_addc_co_u32_e32 v179, vcc, 0, v175, vcc
	global_load_dwordx4 v[166:169], v[166:167], off offset:128
	global_load_dwordx4 v[170:173], v[170:171], off offset:128
	global_load_dwordx4 v[174:177], v[176:177], off offset:128
	global_load_dwordx4 v[178:181], v[178:179], off offset:128
	v_mov_b32_e32 v214, v146
	v_mov_b32_e32 v215, v216
	v_mov_b32_e32 v223, v147
	v_mov_b32_e32 v252, v217
	v_xor_b32_e32 v253, 0x8000, v144
	v_xor_b32_e32 v254, 0x8000, v145
	ds_read_b128 v[182:185], v214
	ds_read_b128 v[186:189], v214 offset:2048
	ds_read_b128 v[190:193], v214 offset:4096
	ds_read_b128 v[194:197], v214 offset:6144
	ds_read_b128 v[218:221], v223
	ds_read_b128 v[224:227], v223 offset:2048
	ds_read_b128 v[228:231], v223 offset:4096
	ds_read_b128 v[232:235], v223 offset:6144
.Lg2_p14_loop:
	ds_read_b128 v[198:201], v214 offset:8192
	ds_read_b128 v[202:205], v214 offset:10240
	ds_read_b128 v[206:209], v214 offset:12288
	ds_read_b128 v[210:213], v214 offset:14336
	s_waitcnt lgkmcnt(4)
	v_mfma_f32_16x16x32_bf16 v[126:129], v[218:221], v[182:185], v[126:129]
	v_mfma_f32_16x16x32_bf16 v[122:125], v[224:227], v[182:185], v[122:125]
	v_mfma_f32_16x16x32_bf16 v[118:121], v[228:231], v[182:185], v[118:121]
	v_mfma_f32_16x16x32_bf16 v[114:117], v[232:235], v[182:185], v[114:117]
	v_mfma_f32_16x16x32_bf16 v[110:113], v[218:221], v[186:189], v[110:113]
	v_mfma_f32_16x16x32_bf16 v[106:109], v[224:227], v[186:189], v[106:109]
	v_mfma_f32_16x16x32_bf16 v[102:105], v[228:231], v[186:189], v[102:105]
	v_mfma_f32_16x16x32_bf16 v[98:101], v[232:235], v[186:189], v[98:101]
	v_mfma_f32_16x16x32_bf16 v[94:97], v[218:221], v[190:193], v[94:97]
	v_mfma_f32_16x16x32_bf16 v[90:93], v[224:227], v[190:193], v[90:93]
	v_mfma_f32_16x16x32_bf16 v[86:89], v[228:231], v[190:193], v[86:89]
	v_mfma_f32_16x16x32_bf16 v[82:85], v[232:235], v[190:193], v[82:85]
	v_mfma_f32_16x16x32_bf16 v[78:81], v[218:221], v[194:197], v[78:81]
	v_mfma_f32_16x16x32_bf16 v[74:77], v[224:227], v[194:197], v[74:77]
	v_mfma_f32_16x16x32_bf16 v[70:73], v[228:231], v[194:197], v[70:73]
	v_mfma_f32_16x16x32_bf16 v[66:69], v[232:235], v[194:197], v[66:69]
	ds_read_b128 v[182:185], v215
	ds_read_b128 v[186:189], v215 offset:2048
	ds_read_b128 v[190:193], v215 offset:4096
	ds_read_b128 v[194:197], v215 offset:6144
	ds_read_b128 v[236:239], v252
	ds_read_b128 v[240:243], v252 offset:2048
	ds_read_b128 v[244:247], v252 offset:4096
	ds_read_b128 v[248:251], v252 offset:6144
	s_waitcnt lgkmcnt(8)
	v_mfma_f32_16x16x32_bf16 v[62:65], v[218:221], v[198:201], v[62:65]
	v_mfma_f32_16x16x32_bf16 v[58:61], v[224:227], v[198:201], v[58:61]
	v_mfma_f32_16x16x32_bf16 v[54:57], v[228:231], v[198:201], v[54:57]
	v_mfma_f32_16x16x32_bf16 v[50:53], v[232:235], v[198:201], v[50:53]
	v_mfma_f32_16x16x32_bf16 v[46:49], v[218:221], v[202:205], v[46:49]
	v_mfma_f32_16x16x32_bf16 v[42:45], v[224:227], v[202:205], v[42:45]
	v_mfma_f32_16x16x32_bf16 v[38:41], v[228:231], v[202:205], v[38:41]
	v_mfma_f32_16x16x32_bf16 v[34:37], v[232:235], v[202:205], v[34:37]
	v_mfma_f32_16x16x32_bf16 v[30:33], v[218:221], v[206:209], v[30:33]
	v_mfma_f32_16x16x32_bf16 v[26:29], v[224:227], v[206:209], v[26:29]
	v_mfma_f32_16x16x32_bf16 v[22:25], v[228:231], v[206:209], v[22:25]
	v_mfma_f32_16x16x32_bf16 v[18:21], v[232:235], v[206:209], v[18:21]
	v_mfma_f32_16x16x32_bf16 v[14:17], v[218:221], v[210:213], v[14:17]
	v_mfma_f32_16x16x32_bf16 v[10:13], v[224:227], v[210:213], v[10:13]
	v_mfma_f32_16x16x32_bf16 v[6:9], v[228:231], v[210:213], v[6:9]
	v_mfma_f32_16x16x32_bf16 v[2:5], v[232:235], v[210:213], v[2:5]
	ds_read_b128 v[198:201], v215 offset:8192
	ds_read_b128 v[202:205], v215 offset:10240
	ds_read_b128 v[206:209], v215 offset:12288
	ds_read_b128 v[210:213], v215 offset:14336
	s_waitcnt lgkmcnt(4)
	v_mfma_f32_16x16x32_bf16 v[126:129], v[236:239], v[182:185], v[126:129]
	v_mfma_f32_16x16x32_bf16 v[122:125], v[240:243], v[182:185], v[122:125]
	s_waitcnt vmcnt(7)
	ds_write_b128 v253, v[150:153]
	v_mfma_f32_16x16x32_bf16 v[118:121], v[244:247], v[182:185], v[118:121]
	v_mfma_f32_16x16x32_bf16 v[114:117], v[248:251], v[182:185], v[114:117]
	s_waitcnt vmcnt(6)
	ds_write_b128 v253, v[154:157] offset:8192
	v_mfma_f32_16x16x32_bf16 v[110:113], v[236:239], v[186:189], v[110:113]
	v_mfma_f32_16x16x32_bf16 v[106:109], v[240:243], v[186:189], v[106:109]
	s_waitcnt vmcnt(5)
	ds_write_b128 v253, v[158:161] offset:16384
	v_mfma_f32_16x16x32_bf16 v[102:105], v[244:247], v[186:189], v[102:105]
	v_mfma_f32_16x16x32_bf16 v[98:101], v[248:251], v[186:189], v[98:101]
	s_waitcnt vmcnt(4)
	ds_write_b128 v253, v[162:165] offset:24576
	v_mfma_f32_16x16x32_bf16 v[94:97], v[236:239], v[190:193], v[94:97]
	v_mfma_f32_16x16x32_bf16 v[90:93], v[240:243], v[190:193], v[90:93]
	s_waitcnt vmcnt(3)
	ds_write_b128 v254, v[166:169]
	v_mfma_f32_16x16x32_bf16 v[86:89], v[244:247], v[190:193], v[86:89]
	v_mfma_f32_16x16x32_bf16 v[82:85], v[248:251], v[190:193], v[82:85]
	s_waitcnt vmcnt(2)
	ds_write_b128 v254, v[170:173] offset:8192
	v_mfma_f32_16x16x32_bf16 v[78:81], v[236:239], v[194:197], v[78:81]
	v_mfma_f32_16x16x32_bf16 v[74:77], v[240:243], v[194:197], v[74:77]
	s_waitcnt vmcnt(1)
	ds_write_b128 v254, v[174:177] offset:16384
	v_mfma_f32_16x16x32_bf16 v[70:73], v[244:247], v[194:197], v[70:73]
	v_mfma_f32_16x16x32_bf16 v[66:69], v[248:251], v[194:197], v[66:69]
	s_waitcnt vmcnt(0)
	ds_write_b128 v254, v[178:181] offset:24576
	s_waitcnt lgkmcnt(0)
	s_barrier
	s_add_u32 s0, s0, 0x80
	s_addc_u32 s1, s1, 0
	s_cmpk_eq_i32 s0, 0x780
	s_cbranch_scc1 .Lg2_p14_tail
	v_xor_b32_e32 v214, 0x8000, v214
	v_xor_b32_e32 v223, 0x8000, v223
	v_xor_b32_e32 v215, 0x8000, v215
	v_xor_b32_e32 v252, 0x8000, v252
	v_xor_b32_e32 v253, 0x8000, v253
	v_xor_b32_e32 v254, 0x8000, v254
	ds_read_b128 v[182:185], v214
	ds_read_b128 v[186:189], v214 offset:2048
	ds_read_b128 v[190:193], v214 offset:4096
	ds_read_b128 v[194:197], v214 offset:6144
	ds_read_b128 v[218:221], v223
	ds_read_b128 v[224:227], v223 offset:2048
	ds_read_b128 v[228:231], v223 offset:4096
	ds_read_b128 v[232:235], v223 offset:6144
	v_mfma_f32_16x16x32_bf16 v[62:65], v[236:239], v[198:201], v[62:65]
	v_lshl_add_u64 v[150:151], v[142:143], 0, s[0:1]
	v_add_co_u32_e32 v152, vcc, s12, v150
	v_mfma_f32_16x16x32_bf16 v[58:61], v[240:243], v[198:201], v[58:61]
	s_nop 1
	v_addc_co_u32_e32 v153, vcc, 0, v151, vcc
	v_mfma_f32_16x16x32_bf16 v[54:57], v[244:247], v[198:201], v[54:57]
	v_add_co_u32_e32 v154, vcc, s13, v150
	s_nop 1
	v_mfma_f32_16x16x32_bf16 v[50:53], v[248:251], v[198:201], v[50:53]
	v_addc_co_u32_e32 v155, vcc, 0, v151, vcc
	v_add_co_u32_e32 v158, vcc, s14, v150
	v_mfma_f32_16x16x32_bf16 v[46:49], v[236:239], v[202:205], v[46:49]
	s_nop 1
	v_addc_co_u32_e32 v159, vcc, 0, v151, vcc
	v_mfma_f32_16x16x32_bf16 v[42:45], v[240:243], v[202:205], v[42:45]
	v_add_co_u32_e32 v162, vcc, s15, v150
	s_nop 1
	v_mfma_f32_16x16x32_bf16 v[38:41], v[244:247], v[202:205], v[38:41]
	v_addc_co_u32_e32 v163, vcc, 0, v151, vcc
	global_load_dwordx4 v[150:153], v[152:153], off offset:128
	v_mfma_f32_16x16x32_bf16 v[34:37], v[248:251], v[202:205], v[34:37]
	global_load_dwordx4 v[154:157], v[154:155], off offset:128
	global_load_dwordx4 v[158:161], v[158:159], off offset:128
	global_load_dwordx4 v[162:165], v[162:163], off offset:128
	v_mfma_f32_16x16x32_bf16 v[30:33], v[236:239], v[206:209], v[30:33]
	v_lshl_add_u64 v[174:175], v[140:141], 0, s[0:1]
	v_add_co_u32_e32 v166, vcc, s16, v174
	v_mfma_f32_16x16x32_bf16 v[26:29], v[240:243], v[206:209], v[26:29]
	s_nop 1
	v_addc_co_u32_e32 v167, vcc, 0, v175, vcc
	v_mfma_f32_16x16x32_bf16 v[22:25], v[244:247], v[206:209], v[22:25]
	v_add_co_u32_e32 v170, vcc, s17, v174
	s_nop 1
	v_mfma_f32_16x16x32_bf16 v[18:21], v[248:251], v[206:209], v[18:21]
	v_addc_co_u32_e32 v171, vcc, 0, v175, vcc
	v_add_co_u32_e32 v176, vcc, s18, v174
	v_mfma_f32_16x16x32_bf16 v[14:17], v[236:239], v[210:213], v[14:17]
	s_nop 1
	v_addc_co_u32_e32 v177, vcc, 0, v175, vcc
	v_mfma_f32_16x16x32_bf16 v[10:13], v[240:243], v[210:213], v[10:13]
	v_add_co_u32_e32 v178, vcc, s19, v174
	s_nop 1
	v_mfma_f32_16x16x32_bf16 v[6:9], v[244:247], v[210:213], v[6:9]
	v_addc_co_u32_e32 v179, vcc, 0, v175, vcc
	global_load_dwordx4 v[166:169], v[166:167], off offset:128
	v_mfma_f32_16x16x32_bf16 v[2:5], v[248:251], v[210:213], v[2:5]
	global_load_dwordx4 v[170:173], v[170:171], off offset:128
	global_load_dwordx4 v[174:177], v[176:177], off offset:128
	global_load_dwordx4 v[178:181], v[178:179], off offset:128
	s_branch .Lg2_p14_loop
.Lg2_p14_tail:
	v_mfma_f32_16x16x32_bf16 v[62:65], v[236:239], v[198:201], v[62:65]
	v_mfma_f32_16x16x32_bf16 v[58:61], v[240:243], v[198:201], v[58:61]
	v_mfma_f32_16x16x32_bf16 v[54:57], v[244:247], v[198:201], v[54:57]
	v_mfma_f32_16x16x32_bf16 v[50:53], v[248:251], v[198:201], v[50:53]
	v_mfma_f32_16x16x32_bf16 v[46:49], v[236:239], v[202:205], v[46:49]
	v_mfma_f32_16x16x32_bf16 v[42:45], v[240:243], v[202:205], v[42:45]
	v_mfma_f32_16x16x32_bf16 v[38:41], v[244:247], v[202:205], v[38:41]
	v_mfma_f32_16x16x32_bf16 v[34:37], v[248:251], v[202:205], v[34:37]
	v_mfma_f32_16x16x32_bf16 v[30:33], v[236:239], v[206:209], v[30:33]
	v_mfma_f32_16x16x32_bf16 v[26:29], v[240:243], v[206:209], v[26:29]
	v_mfma_f32_16x16x32_bf16 v[22:25], v[244:247], v[206:209], v[22:25]
	v_mfma_f32_16x16x32_bf16 v[18:21], v[248:251], v[206:209], v[18:21]
	v_mfma_f32_16x16x32_bf16 v[14:17], v[236:239], v[210:213], v[14:17]
	v_mfma_f32_16x16x32_bf16 v[10:13], v[240:243], v[210:213], v[10:13]
	v_mfma_f32_16x16x32_bf16 v[6:9], v[244:247], v[210:213], v[6:9]
	v_mfma_f32_16x16x32_bf16 v[2:5], v[248:251], v[210:213], v[2:5]
	ds_read_b128 v[140:143], v147 offset:32768
	ds_read_b128 v[150:153], v147 offset:34816
	ds_read_b128 v[154:157], v147 offset:36864
	ds_read_b128 v[158:161], v147 offset:38912
	ds_read_b128 v[162:165], v146 offset:32768
	ds_read_b128 v[166:169], v146 offset:34816
	ds_read_b128 v[170:173], v146 offset:36864
	ds_read_b128 v[174:177], v146 offset:38912
	s_setprio 1
	s_waitcnt lgkmcnt(3)
	v_mfma_f32_16x16x32_bf16 v[126:129], v[140:143], v[162:165], v[126:129]
	v_mfma_f32_16x16x32_bf16 v[122:125], v[150:153], v[162:165], v[122:125]
	v_mfma_f32_16x16x32_bf16 v[118:121], v[154:157], v[162:165], v[118:121]
	v_mfma_f32_16x16x32_bf16 v[114:117], v[158:161], v[162:165], v[114:117]
	s_waitcnt lgkmcnt(2)
	v_mfma_f32_16x16x32_bf16 v[110:113], v[140:143], v[166:169], v[110:113]
	v_mfma_f32_16x16x32_bf16 v[106:109], v[150:153], v[166:169], v[106:109]
	v_mfma_f32_16x16x32_bf16 v[102:105], v[154:157], v[166:169], v[102:105]
	v_mfma_f32_16x16x32_bf16 v[98:101], v[158:161], v[166:169], v[98:101]
	s_waitcnt lgkmcnt(1)
	v_mfma_f32_16x16x32_bf16 v[94:97], v[140:143], v[170:173], v[94:97]
	v_mfma_f32_16x16x32_bf16 v[90:93], v[150:153], v[170:173], v[90:93]
	v_mfma_f32_16x16x32_bf16 v[86:89], v[154:157], v[170:173], v[86:89]
	v_mfma_f32_16x16x32_bf16 v[82:85], v[158:161], v[170:173], v[82:85]
	s_waitcnt lgkmcnt(0)
	v_mfma_f32_16x16x32_bf16 v[78:81], v[140:143], v[174:177], v[78:81]
	v_mfma_f32_16x16x32_bf16 v[74:77], v[150:153], v[174:177], v[74:77]
	v_mfma_f32_16x16x32_bf16 v[70:73], v[154:157], v[174:177], v[70:73]
	v_mfma_f32_16x16x32_bf16 v[66:69], v[158:161], v[174:177], v[66:69]
	s_setprio 0
	ds_read_b128 v[162:165], v146 offset:40960
	ds_read_b128 v[166:169], v146 offset:43008
	ds_read_b128 v[170:173], v146 offset:45056
	ds_read_b128 v[174:177], v146 offset:47104
	s_setprio 1
	s_waitcnt lgkmcnt(3)
	v_mfma_f32_16x16x32_bf16 v[62:65], v[140:143], v[162:165], v[62:65]
	v_mfma_f32_16x16x32_bf16 v[58:61], v[150:153], v[162:165], v[58:61]
	v_mfma_f32_16x16x32_bf16 v[54:57], v[154:157], v[162:165], v[54:57]
	v_mfma_f32_16x16x32_bf16 v[50:53], v[158:161], v[162:165], v[50:53]
	s_waitcnt lgkmcnt(2)
	v_mfma_f32_16x16x32_bf16 v[46:49], v[140:143], v[166:169], v[46:49]
	v_mfma_f32_16x16x32_bf16 v[42:45], v[150:153], v[166:169], v[42:45]
	v_mfma_f32_16x16x32_bf16 v[38:41], v[154:157], v[166:169], v[38:41]
	v_mfma_f32_16x16x32_bf16 v[34:37], v[158:161], v[166:169], v[34:37]
	s_waitcnt lgkmcnt(1)
	v_mfma_f32_16x16x32_bf16 v[30:33], v[140:143], v[170:173], v[30:33]
	v_mfma_f32_16x16x32_bf16 v[26:29], v[150:153], v[170:173], v[26:29]
	v_mfma_f32_16x16x32_bf16 v[22:25], v[154:157], v[170:173], v[22:25]
	v_mfma_f32_16x16x32_bf16 v[18:21], v[158:161], v[170:173], v[18:21]
	s_waitcnt lgkmcnt(0)
	v_mfma_f32_16x16x32_bf16 v[14:17], v[140:143], v[174:177], v[14:17]
	v_mfma_f32_16x16x32_bf16 v[10:13], v[150:153], v[174:177], v[10:13]
	v_mfma_f32_16x16x32_bf16 v[6:9], v[154:157], v[174:177], v[6:9]
	v_mfma_f32_16x16x32_bf16 v[2:5], v[158:161], v[174:177], v[2:5]
	s_setprio 0
	ds_read_b128 v[140:143], v217 offset:32768
	ds_read_b128 v[150:153], v217 offset:34816
	ds_read_b128 v[154:157], v217 offset:36864
	ds_read_b128 v[158:161], v217 offset:38912
	ds_read_b128 v[162:165], v216 offset:32768
	ds_read_b128 v[166:169], v216 offset:34816
	ds_read_b128 v[170:173], v216 offset:36864
	ds_read_b128 v[174:177], v216 offset:38912
	s_setprio 1
	s_waitcnt lgkmcnt(3)
	v_mfma_f32_16x16x32_bf16 v[126:129], v[140:143], v[162:165], v[126:129]
	v_mfma_f32_16x16x32_bf16 v[122:125], v[150:153], v[162:165], v[122:125]
	v_mfma_f32_16x16x32_bf16 v[118:121], v[154:157], v[162:165], v[118:121]
	v_mfma_f32_16x16x32_bf16 v[114:117], v[158:161], v[162:165], v[114:117]
	s_waitcnt lgkmcnt(2)
	v_mfma_f32_16x16x32_bf16 v[110:113], v[140:143], v[166:169], v[110:113]
	v_mfma_f32_16x16x32_bf16 v[106:109], v[150:153], v[166:169], v[106:109]
	v_mfma_f32_16x16x32_bf16 v[102:105], v[154:157], v[166:169], v[102:105]
	v_mfma_f32_16x16x32_bf16 v[98:101], v[158:161], v[166:169], v[98:101]
	s_waitcnt lgkmcnt(1)
	v_mfma_f32_16x16x32_bf16 v[94:97], v[140:143], v[170:173], v[94:97]
	v_mfma_f32_16x16x32_bf16 v[162:165], v[150:153], v[170:173], v[90:93]
	v_mfma_f32_16x16x32_bf16 v[86:89], v[154:157], v[170:173], v[86:89]
	v_mfma_f32_16x16x32_bf16 v[82:85], v[158:161], v[170:173], v[82:85]
	s_waitcnt lgkmcnt(0)
	v_mfma_f32_16x16x32_bf16 v[78:81], v[140:143], v[174:177], v[78:81]
	v_mfma_f32_16x16x32_bf16 v[74:77], v[150:153], v[174:177], v[74:77]
	v_mfma_f32_16x16x32_bf16 v[70:73], v[154:157], v[174:177], v[70:73]
	v_mfma_f32_16x16x32_bf16 v[66:69], v[158:161], v[174:177], v[66:69]
	s_setprio 0
	ds_read_b128 v[90:93], v216 offset:40960
	ds_read_b128 v[166:169], v216 offset:43008
	ds_read_b128 v[170:173], v216 offset:45056
	ds_read_b128 v[174:177], v216 offset:47104
	s_setprio 1
	s_waitcnt lgkmcnt(3)
	v_mfma_f32_16x16x32_bf16 v[62:65], v[140:143], v[90:93], v[62:65]
	v_mfma_f32_16x16x32_bf16 v[58:61], v[150:153], v[90:93], v[58:61]
	v_mfma_f32_16x16x32_bf16 v[54:57], v[154:157], v[90:93], v[54:57]
	v_mfma_f32_16x16x32_bf16 v[50:53], v[158:161], v[90:93], v[50:53]
	s_waitcnt lgkmcnt(2)
	v_mfma_f32_16x16x32_bf16 v[46:49], v[140:143], v[166:169], v[46:49]
	v_mfma_f32_16x16x32_bf16 v[42:45], v[150:153], v[166:169], v[42:45]
	v_mfma_f32_16x16x32_bf16 v[38:41], v[154:157], v[166:169], v[38:41]
	v_mfma_f32_16x16x32_bf16 v[34:37], v[158:161], v[166:169], v[34:37]
	s_waitcnt lgkmcnt(1)
	v_mfma_f32_16x16x32_bf16 v[30:33], v[140:143], v[170:173], v[30:33]
	v_mfma_f32_16x16x32_bf16 v[26:29], v[150:153], v[170:173], v[26:29]
	v_mfma_f32_16x16x32_bf16 v[22:25], v[154:157], v[170:173], v[22:25]
	v_mfma_f32_16x16x32_bf16 v[18:21], v[158:161], v[170:173], v[18:21]
	s_waitcnt lgkmcnt(0)
	v_mfma_f32_16x16x32_bf16 v[14:17], v[140:143], v[174:177], v[14:17]
	v_mfma_f32_16x16x32_bf16 v[10:13], v[150:153], v[174:177], v[10:13]
	v_mfma_f32_16x16x32_bf16 v[6:9], v[154:157], v[174:177], v[6:9]
	v_mfma_f32_16x16x32_bf16 v[2:5], v[158:161], v[174:177], v[2:5]
	s_setprio 0
	v_mul_f32_e32 v93, 0xbfb8aa3b, v126
	v_exp_f32_e32 v93, v93
	v_mul_f32_e32 v140, 0xbfb8aa3b, v127
	v_exp_f32_e32 v141, v140
	v_or_b32_e32 v90, s22, v148
	v_add_f32_e32 v93, 1.0, v93
	v_rcp_f32_e32 v140, v93
	v_add_f32_e32 v93, 1.0, v141
	v_mul_f32_e32 v141, 0xbfb8aa3b, v128
	v_exp_f32_e32 v142, v141
	v_mul_f32_e32 v141, 0xbfb8aa3b, v129
	v_exp_f32_e32 v143, v141
	v_rcp_f32_e32 v141, v93
	v_add_f32_e32 v93, 1.0, v142
	v_rcp_f32_e32 v142, v93
	v_add_f32_e32 v93, 1.0, v143
	v_rcp_f32_e32 v143, v93
	v_pk_mul_f32 v[126:127], v[126:127], v[140:141]
	v_mul_f32_e32 v93, 0xbfb8aa3b, v118
	v_pk_mul_f32 v[122:123], v[122:123], v[126:127]
	v_pk_mul_f32 v[126:127], v[128:129], v[142:143]
	v_cvt_pk_bf16_f32 v122, v122, v123
	v_exp_f32_e32 v93, v93
	v_mul_f32_e32 v123, 0xbfb8aa3b, v119
	v_pk_mul_f32 v[124:125], v[124:125], v[126:127]
	v_exp_f32_e32 v126, v123
	v_cvt_pk_bf16_f32 v123, v124, v125
	v_add_f32_e32 v93, 1.0, v93
	v_mul_f32_e32 v125, 0xbfb8aa3b, v120
	v_rcp_f32_e32 v124, v93
	v_add_f32_e32 v93, 1.0, v126
	v_exp_f32_e32 v126, v125
	v_mul_f32_e32 v125, 0xbfb8aa3b, v121
	v_exp_f32_e32 v127, v125
	v_rcp_f32_e32 v125, v93
	v_add_f32_e32 v93, 1.0, v126
	v_rcp_f32_e32 v126, v93
	v_add_f32_e32 v93, 1.0, v127
	v_rcp_f32_e32 v127, v93
	v_ashrrev_i32_e32 v90, 1, v90
	v_pk_mul_f32 v[118:119], v[118:119], v[124:125]
	v_ashrrev_i32_e32 v91, 31, v90
	v_pk_mul_f32 v[114:115], v[114:115], v[118:119]
	v_pk_mul_f32 v[118:119], v[120:121], v[126:127]
	v_add_u32_e32 v92, s21, v149
	v_lshl_add_u64 v[90:91], v[90:91], 1, v[136:137]
	v_pk_mul_f32 v[116:117], v[116:117], v[118:119]
	v_mad_i64_i32 v[150:151], s[0:1], v92, s20, v[90:91]
	v_cvt_pk_bf16_f32 v114, v114, v115
	v_cvt_pk_bf16_f32 v115, v116, v117
	v_mul_f32_e32 v93, 0xbfb8aa3b, v110
	s_barrier
	global_store_dwordx2 v[150:151], v[114:115], off offset:32
	v_exp_f32_e32 v93, v93
	v_mul_f32_e32 v114, 0xbfb8aa3b, v111
	v_exp_f32_e32 v115, v114
	v_or_b32_e32 v118, 16, v92
	v_add_f32_e32 v93, 1.0, v93
	v_rcp_f32_e32 v114, v93
	v_add_f32_e32 v93, 1.0, v115
	v_mul_f32_e32 v115, 0xbfb8aa3b, v112
	v_exp_f32_e32 v116, v115
	v_mul_f32_e32 v115, 0xbfb8aa3b, v113
	v_exp_f32_e32 v117, v115
	v_rcp_f32_e32 v115, v93
	v_add_f32_e32 v93, 1.0, v116
	v_rcp_f32_e32 v116, v93
	v_add_f32_e32 v93, 1.0, v117
	v_rcp_f32_e32 v117, v93
	v_pk_mul_f32 v[110:111], v[110:111], v[114:115]
	v_mul_f32_e32 v93, 0xbfb8aa3b, v102
	v_pk_mul_f32 v[106:107], v[106:107], v[110:111]
	v_pk_mul_f32 v[110:111], v[112:113], v[116:117]
	v_cvt_pk_bf16_f32 v106, v106, v107
	v_exp_f32_e32 v93, v93
	v_mul_f32_e32 v107, 0xbfb8aa3b, v103
	v_pk_mul_f32 v[108:109], v[108:109], v[110:111]
	v_exp_f32_e32 v110, v107
	v_cvt_pk_bf16_f32 v107, v108, v109
	v_add_f32_e32 v93, 1.0, v93
	v_mul_f32_e32 v109, 0xbfb8aa3b, v104
	v_rcp_f32_e32 v108, v93
	v_add_f32_e32 v93, 1.0, v110
	v_exp_f32_e32 v110, v109
	v_mul_f32_e32 v109, 0xbfb8aa3b, v105
	v_exp_f32_e32 v111, v109
	v_rcp_f32_e32 v109, v93
	v_add_f32_e32 v93, 1.0, v110
	v_rcp_f32_e32 v110, v93
	v_add_f32_e32 v93, 1.0, v111
	v_rcp_f32_e32 v111, v93
	v_pk_mul_f32 v[102:103], v[102:103], v[108:109]
	v_mad_i64_i32 v[118:119], s[0:1], v118, s20, v[90:91]
	v_pk_mul_f32 v[98:99], v[98:99], v[102:103]
	v_pk_mul_f32 v[102:103], v[104:105], v[110:111]
	v_cvt_pk_bf16_f32 v98, v98, v99
	v_pk_mul_f32 v[100:101], v[100:101], v[102:103]
	v_mul_f32_e32 v93, 0xbfb8aa3b, v94
	v_cvt_pk_bf16_f32 v99, v100, v101
	global_store_dwordx2 v[118:119], v[98:99], off offset:32
	v_exp_f32_e32 v93, v93
	v_mul_f32_e32 v98, 0xbfb8aa3b, v95
	v_exp_f32_e32 v99, v98
	v_or_b32_e32 v102, 32, v92
	v_add_f32_e32 v93, 1.0, v93
	v_rcp_f32_e32 v98, v93
	v_add_f32_e32 v93, 1.0, v99
	v_mul_f32_e32 v99, 0xbfb8aa3b, v96
	v_exp_f32_e32 v100, v99
	v_mul_f32_e32 v99, 0xbfb8aa3b, v97
	v_exp_f32_e32 v101, v99
	v_rcp_f32_e32 v99, v93
	v_add_f32_e32 v93, 1.0, v100
	v_rcp_f32_e32 v100, v93
	v_add_f32_e32 v93, 1.0, v101
	v_rcp_f32_e32 v101, v93
	v_pk_mul_f32 v[94:95], v[94:95], v[98:99]
	v_mul_f32_e32 v93, 0xbfb8aa3b, v86
	v_pk_mul_f32 v[94:95], v[162:163], v[94:95]
	v_exp_f32_e32 v93, v93
	v_cvt_pk_bf16_f32 v94, v94, v95
	v_mul_f32_e32 v95, 0xbfb8aa3b, v87
	v_exp_f32_e32 v98, v95
	v_pk_mul_f32 v[96:97], v[96:97], v[100:101]
	v_add_f32_e32 v93, 1.0, v93
	v_pk_mul_f32 v[96:97], v[164:165], v[96:97]
	v_mad_i64_i32 v[102:103], s[0:1], v102, s20, v[90:91]
	v_cvt_pk_bf16_f32 v95, v96, v97
	v_mul_f32_e32 v97, 0xbfb8aa3b, v88
	v_rcp_f32_e32 v96, v93
	v_add_f32_e32 v93, 1.0, v98
	v_exp_f32_e32 v98, v97
	v_mul_f32_e32 v97, 0xbfb8aa3b, v89
	v_exp_f32_e32 v99, v97
	v_rcp_f32_e32 v97, v93
	v_add_f32_e32 v93, 1.0, v98
	v_rcp_f32_e32 v98, v93
	v_add_f32_e32 v93, 1.0, v99
	v_rcp_f32_e32 v99, v93
	v_pk_mul_f32 v[86:87], v[86:87], v[96:97]
	s_add_i32 s3, s3, s7
	v_pk_mul_f32 v[82:83], v[82:83], v[86:87]
	v_pk_mul_f32 v[86:87], v[88:89], v[98:99]
	v_cvt_pk_bf16_f32 v82, v82, v83
	v_pk_mul_f32 v[84:85], v[84:85], v[86:87]
	v_or_b32_e32 v86, 48, v92
	v_cvt_pk_bf16_f32 v83, v84, v85
	global_store_dwordx2 v[102:103], v[82:83], off offset:32
	v_mul_f32_e32 v82, 0xbfb8aa3b, v78
	v_mul_f32_e32 v83, 0xbfb8aa3b, v79
	v_exp_f32_e32 v82, v82
	v_exp_f32_e32 v83, v83
	v_mul_f32_e32 v84, 0xbfb8aa3b, v80
	v_mul_f32_e32 v85, 0xbfb8aa3b, v81
	v_exp_f32_e32 v84, v84
	v_exp_f32_e32 v85, v85
	v_add_f32_e32 v82, 1.0, v82
	v_add_f32_e32 v83, 1.0, v83
	v_rcp_f32_e32 v82, v82
	v_rcp_f32_e32 v83, v83
	v_add_f32_e32 v84, 1.0, v84
	v_add_f32_e32 v85, 1.0, v85
	v_rcp_f32_e32 v84, v84
	v_rcp_f32_e32 v85, v85
	v_pk_mul_f32 v[78:79], v[78:79], v[82:83]
	v_mad_i64_i32 v[86:87], s[0:1], v86, s20, v[90:91]
	v_pk_mul_f32 v[74:75], v[74:75], v[78:79]
	v_pk_mul_f32 v[78:79], v[80:81], v[84:85]
	v_cvt_pk_bf16_f32 v74, v74, v75
	v_mul_f32_e32 v75, 0xbfb8aa3b, v70
	v_pk_mul_f32 v[76:77], v[76:77], v[78:79]
	v_exp_f32_e32 v78, v75
	v_mul_f32_e32 v75, 0xbfb8aa3b, v71
	v_exp_f32_e32 v79, v75
	v_cvt_pk_bf16_f32 v75, v76, v77
	v_add_f32_e32 v76, 1.0, v78
	v_mul_f32_e32 v78, 0xbfb8aa3b, v72
	v_add_f32_e32 v77, 1.0, v79
	v_mul_f32_e32 v79, 0xbfb8aa3b, v73
	v_exp_f32_e32 v78, v78
	v_exp_f32_e32 v79, v79
	v_rcp_f32_e32 v76, v76
	v_rcp_f32_e32 v77, v77
	v_add_f32_e32 v78, 1.0, v78
	v_add_f32_e32 v79, 1.0, v79
	v_rcp_f32_e32 v78, v78
	v_rcp_f32_e32 v79, v79
	v_pk_mul_f32 v[70:71], v[70:71], v[76:77]
	s_cmpk_gt_i32 s3, 0x2bf
	v_pk_mul_f32 v[66:67], v[66:67], v[70:71]
	v_pk_mul_f32 v[70:71], v[72:73], v[78:79]
	v_cvt_pk_bf16_f32 v66, v66, v67
	v_pk_mul_f32 v[68:69], v[68:69], v[70:71]
	v_or_b32_e32 v70, 64, v92
	v_cvt_pk_bf16_f32 v67, v68, v69
	global_store_dwordx2 v[86:87], v[66:67], off offset:32
	v_mul_f32_e32 v66, 0xbfb8aa3b, v62
	v_mul_f32_e32 v67, 0xbfb8aa3b, v63
	v_exp_f32_e32 v66, v66
	v_exp_f32_e32 v67, v67
	v_mul_f32_e32 v68, 0xbfb8aa3b, v64
	v_mul_f32_e32 v69, 0xbfb8aa3b, v65
	v_exp_f32_e32 v68, v68
	v_exp_f32_e32 v69, v69
	v_add_f32_e32 v66, 1.0, v66
	v_add_f32_e32 v67, 1.0, v67
	v_rcp_f32_e32 v66, v66
	v_rcp_f32_e32 v67, v67
	v_add_f32_e32 v68, 1.0, v68
	v_add_f32_e32 v69, 1.0, v69
	v_rcp_f32_e32 v68, v68
	v_rcp_f32_e32 v69, v69
	v_pk_mul_f32 v[62:63], v[62:63], v[66:67]
	v_mad_i64_i32 v[70:71], s[0:1], v70, s20, v[90:91]
	v_pk_mul_f32 v[58:59], v[58:59], v[62:63]
	v_pk_mul_f32 v[62:63], v[64:65], v[68:69]
	v_cvt_pk_bf16_f32 v58, v58, v59
	v_mul_f32_e32 v59, 0xbfb8aa3b, v54
	v_pk_mul_f32 v[60:61], v[60:61], v[62:63]
	v_exp_f32_e32 v62, v59
	v_mul_f32_e32 v59, 0xbfb8aa3b, v55
	v_exp_f32_e32 v63, v59
	v_cvt_pk_bf16_f32 v59, v60, v61
	v_add_f32_e32 v60, 1.0, v62
	v_mul_f32_e32 v62, 0xbfb8aa3b, v56
	v_add_f32_e32 v61, 1.0, v63
	v_mul_f32_e32 v63, 0xbfb8aa3b, v57
	v_exp_f32_e32 v62, v62
	v_exp_f32_e32 v63, v63
	v_rcp_f32_e32 v60, v60
	v_rcp_f32_e32 v61, v61
	v_add_f32_e32 v62, 1.0, v62
	v_add_f32_e32 v63, 1.0, v63
	v_rcp_f32_e32 v62, v62
	v_rcp_f32_e32 v63, v63
	v_pk_mul_f32 v[54:55], v[54:55], v[60:61]
	v_add_u32_e32 v130, s8, v130
	v_pk_mul_f32 v[50:51], v[50:51], v[54:55]
	v_pk_mul_f32 v[54:55], v[56:57], v[62:63]
	v_cvt_pk_bf16_f32 v50, v50, v51
	v_pk_mul_f32 v[52:53], v[52:53], v[54:55]
	v_or_b32_e32 v54, 0x50, v92
	v_cvt_pk_bf16_f32 v51, v52, v53
	global_store_dwordx2 v[70:71], v[50:51], off offset:32
	v_mul_f32_e32 v50, 0xbfb8aa3b, v46
	v_mul_f32_e32 v51, 0xbfb8aa3b, v47
	v_exp_f32_e32 v50, v50
	v_exp_f32_e32 v51, v51
	v_mul_f32_e32 v52, 0xbfb8aa3b, v48
	v_mul_f32_e32 v53, 0xbfb8aa3b, v49
	v_exp_f32_e32 v52, v52
	v_exp_f32_e32 v53, v53
	v_add_f32_e32 v50, 1.0, v50
	v_add_f32_e32 v51, 1.0, v51
	v_rcp_f32_e32 v50, v50
	v_rcp_f32_e32 v51, v51
	v_add_f32_e32 v52, 1.0, v52
	v_add_f32_e32 v53, 1.0, v53
	v_rcp_f32_e32 v52, v52
	v_rcp_f32_e32 v53, v53
	v_pk_mul_f32 v[46:47], v[46:47], v[50:51]
	v_mad_i64_i32 v[54:55], s[0:1], v54, s20, v[90:91]
	v_pk_mul_f32 v[42:43], v[42:43], v[46:47]
	v_pk_mul_f32 v[46:47], v[48:49], v[52:53]
	v_cvt_pk_bf16_f32 v42, v42, v43
	v_mul_f32_e32 v43, 0xbfb8aa3b, v38
	v_pk_mul_f32 v[44:45], v[44:45], v[46:47]
	v_exp_f32_e32 v46, v43
	v_mul_f32_e32 v43, 0xbfb8aa3b, v39
	v_exp_f32_e32 v47, v43
	v_cvt_pk_bf16_f32 v43, v44, v45
	v_add_f32_e32 v44, 1.0, v46
	v_mul_f32_e32 v46, 0xbfb8aa3b, v40
	v_add_f32_e32 v45, 1.0, v47
	v_mul_f32_e32 v47, 0xbfb8aa3b, v41
	v_exp_f32_e32 v46, v46
	v_exp_f32_e32 v47, v47
	v_rcp_f32_e32 v44, v44
	v_rcp_f32_e32 v45, v45
	v_add_f32_e32 v46, 1.0, v46
	v_add_f32_e32 v47, 1.0, v47
	v_rcp_f32_e32 v46, v46
	v_rcp_f32_e32 v47, v47
	v_pk_mul_f32 v[38:39], v[38:39], v[44:45]
	global_store_dwordx2 v[150:151], v[122:123], off
	v_pk_mul_f32 v[34:35], v[34:35], v[38:39]
	v_pk_mul_f32 v[38:39], v[40:41], v[46:47]
	v_cvt_pk_bf16_f32 v34, v34, v35
	v_pk_mul_f32 v[36:37], v[36:37], v[38:39]
	v_or_b32_e32 v38, 0x60, v92
	v_cvt_pk_bf16_f32 v35, v36, v37
	global_store_dwordx2 v[54:55], v[34:35], off offset:32
	v_mul_f32_e32 v34, 0xbfb8aa3b, v30
	v_mul_f32_e32 v35, 0xbfb8aa3b, v31
	v_exp_f32_e32 v34, v34
	v_exp_f32_e32 v35, v35
	v_mul_f32_e32 v36, 0xbfb8aa3b, v32
	v_mul_f32_e32 v37, 0xbfb8aa3b, v33
	v_exp_f32_e32 v36, v36
	v_exp_f32_e32 v37, v37
	v_add_f32_e32 v34, 1.0, v34
	v_add_f32_e32 v35, 1.0, v35
	v_rcp_f32_e32 v34, v34
	v_rcp_f32_e32 v35, v35
	v_add_f32_e32 v36, 1.0, v36
	v_add_f32_e32 v37, 1.0, v37
	v_rcp_f32_e32 v36, v36
	v_rcp_f32_e32 v37, v37
	v_pk_mul_f32 v[30:31], v[30:31], v[34:35]
	v_mad_i64_i32 v[38:39], s[0:1], v38, s20, v[90:91]
	v_pk_mul_f32 v[26:27], v[26:27], v[30:31]
	v_pk_mul_f32 v[30:31], v[32:33], v[36:37]
	v_cvt_pk_bf16_f32 v26, v26, v27
	v_mul_f32_e32 v27, 0xbfb8aa3b, v22
	v_pk_mul_f32 v[28:29], v[28:29], v[30:31]
	v_exp_f32_e32 v30, v27
	v_mul_f32_e32 v27, 0xbfb8aa3b, v23
	v_exp_f32_e32 v31, v27
	v_cvt_pk_bf16_f32 v27, v28, v29
	v_add_f32_e32 v28, 1.0, v30
	v_mul_f32_e32 v30, 0xbfb8aa3b, v24
	v_add_f32_e32 v29, 1.0, v31
	v_mul_f32_e32 v31, 0xbfb8aa3b, v25
	v_exp_f32_e32 v30, v30
	v_exp_f32_e32 v31, v31
	v_rcp_f32_e32 v28, v28
	v_rcp_f32_e32 v29, v29
	v_add_f32_e32 v30, 1.0, v30
	v_add_f32_e32 v31, 1.0, v31
	v_rcp_f32_e32 v30, v30
	v_rcp_f32_e32 v31, v31
	v_pk_mul_f32 v[22:23], v[22:23], v[28:29]
	global_store_dwordx2 v[118:119], v[106:107], off
	v_pk_mul_f32 v[18:19], v[18:19], v[22:23]
	v_pk_mul_f32 v[22:23], v[24:25], v[30:31]
	v_cvt_pk_bf16_f32 v18, v18, v19
	v_pk_mul_f32 v[20:21], v[20:21], v[22:23]
	v_or_b32_e32 v22, 0x70, v92
	v_cvt_pk_bf16_f32 v19, v20, v21
	global_store_dwordx2 v[38:39], v[18:19], off offset:32
	v_mul_f32_e32 v18, 0xbfb8aa3b, v14
	v_mul_f32_e32 v19, 0xbfb8aa3b, v15
	v_exp_f32_e32 v18, v18
	v_exp_f32_e32 v19, v19
	v_mul_f32_e32 v20, 0xbfb8aa3b, v16
	v_mul_f32_e32 v21, 0xbfb8aa3b, v17
	v_exp_f32_e32 v20, v20
	v_exp_f32_e32 v21, v21
	v_add_f32_e32 v18, 1.0, v18
	v_add_f32_e32 v19, 1.0, v19
	v_rcp_f32_e32 v18, v18
	v_rcp_f32_e32 v19, v19
	v_add_f32_e32 v20, 1.0, v20
	v_add_f32_e32 v21, 1.0, v21
	v_rcp_f32_e32 v20, v20
	v_rcp_f32_e32 v21, v21
	v_pk_mul_f32 v[14:15], v[14:15], v[18:19]
	v_mad_i64_i32 v[22:23], s[0:1], v22, s20, v[90:91]
	v_pk_mul_f32 v[10:11], v[10:11], v[14:15]
	v_pk_mul_f32 v[14:15], v[16:17], v[20:21]
	v_cvt_pk_bf16_f32 v10, v10, v11
	v_mul_f32_e32 v11, 0xbfb8aa3b, v6
	v_pk_mul_f32 v[12:13], v[12:13], v[14:15]
	v_exp_f32_e32 v14, v11
	v_mul_f32_e32 v11, 0xbfb8aa3b, v7
	v_exp_f32_e32 v15, v11
	v_cvt_pk_bf16_f32 v11, v12, v13
	v_add_f32_e32 v12, 1.0, v14
	v_mul_f32_e32 v14, 0xbfb8aa3b, v8
	v_add_f32_e32 v13, 1.0, v15
	v_mul_f32_e32 v15, 0xbfb8aa3b, v9
	v_exp_f32_e32 v14, v14
	v_exp_f32_e32 v15, v15
	v_rcp_f32_e32 v12, v12
	v_rcp_f32_e32 v13, v13
	v_add_f32_e32 v14, 1.0, v14
	v_add_f32_e32 v15, 1.0, v15
	v_rcp_f32_e32 v14, v14
	v_rcp_f32_e32 v15, v15
	v_pk_mul_f32 v[6:7], v[6:7], v[12:13]
	global_store_dwordx2 v[102:103], v[94:95], off
	v_pk_mul_f32 v[2:3], v[2:3], v[6:7]
	v_pk_mul_f32 v[6:7], v[8:9], v[14:15]
	v_cvt_pk_bf16_f32 v2, v2, v3
	v_pk_mul_f32 v[4:5], v[4:5], v[6:7]
	global_store_dwordx2 v[86:87], v[74:75], off
	v_cvt_pk_bf16_f32 v3, v4, v5
	global_store_dwordx2 v[70:71], v[58:59], off
	global_store_dwordx2 v[54:55], v[42:43], off
	global_store_dwordx2 v[38:39], v[26:27], off
	global_store_dwordx2 v[22:23], v[10:11], off
	global_store_dwordx2 v[22:23], v[2:3], off offset:32
	s_cbranch_scc0 .LBB0_749

.LBB0_767:
	s_add_u32 s4, s86, 0x3c50000
	v_lshlrev_b32_e32 v4, 4, v2
	s_addc_u32 s5, s87, 0
	s_and_b32 s6, s2, 7
	v_and_b32_e32 v4, 0x70, v4
	v_mov_b32_e32 v5, 0
	s_mul_i32 s10, s6, 33
	v_lshl_add_u64 v[6:7], s[86:87], 0, v[4:5]
	s_mov_b64 s[6:7], 0x1d050000
	v_lshrrev_b32_e32 v1, 3, v2
	v_lshl_add_u64 v[130:131], v[6:7], 0, s[6:7]
	s_mov_b64 s[6:7], 0x2080000
	v_lshl_add_u64 v[132:133], v[6:7], 0, s[6:7]
	v_mul_u32_u24_e32 v6, 0x48, v1
	v_lshlrev_b32_e32 v6, 1, v6
	s_add_i32 s6, 0, 0x12000
	v_add3_u32 v146, 0, v6, v4
	v_add3_u32 v147, s6, v6, v4
	v_and_b32_e32 v4, 15, v2
	v_lshrrev_b32_e32 v6, 1, v2
	s_movk_i32 s7, 0x180
	v_and_or_b32 v4, v6, s7, v4
	v_mul_u32_u24_e32 v4, 0x90, v4
	v_and_b32_e32 v6, 48, v2
	v_add3_u32 v148, 0, v4, v6
	v_and_b32_e32 v4, 0xcf, v2
	v_mov_b32_e32 v3, v2
	v_mul_u32_u24_e32 v4, 0x90, v4
	s_lshr_b32 s3, s2, 3
	s_add_i32 s10, s10, 1
	v_add3_u32 v149, s6, v4, v6
	v_lshrrev_b32_e32 v4, 1, v1
	v_and_b32_e32 v4, 7, v4
	v_and_b32_e32 v7, 7, v2
	v_xor_b32_e32 v4, v4, v7
	v_lshlrev_b32_e32 v4, 4, v4
	v_lshl_add_u32 v146, v1, 7, v4
	v_add_u32_e32 v147, 0x10000, v146
	v_and_b32_e32 v4, 15, v2
	v_lshrrev_b32_e32 v7, 1, v4
	v_bfe_u32 v216, v2, 4, 2
	v_xor_b32_e32 v7, v7, v216
	v_lshlrev_b32_e32 v7, 4, v7
	v_lshrrev_b32_e32 v216, 8, v2
	v_lshl_add_u32 v216, v216, 7, v4
	v_lshl_add_u32 v148, v216, 7, v7
	v_xor_b32_e32 v216, 64, v148
	v_bfe_u32 v217, v2, 6, 2
	v_lshl_add_u32 v217, v217, 6, v4
	v_lshl_add_u32 v149, v217, 7, v7
	v_add_u32_e32 v149, 0x10000, v149
	v_xor_b32_e32 v217, 64, v149
	v_ashrrev_i32_e32 v4, 1, v3
	v_and_b32_e32 v7, 15, v3
	s_movk_i32 s6, 0xff80
	v_and_b32_e32 v2, 7, v2
	v_and_b32_e32 v6, 0xc0, v3
	v_and_or_b32 v150, v4, s6, v7
	s_add_u32 s6, s86, 0x2fbb000
	v_lshrrev_b32_e32 v3, 2, v3
	v_lshlrev_b32_e32 v4, 4, v2
	s_addc_u32 s7, s87, 0
	v_and_or_b32 v151, v3, 12, v6
	s_ashr_i32 s11, s33, 3
	v_lshl_add_u64 v[134:135], s[86:87], 0, v[4:5]
	s_movk_i32 s12, 0x1600
	s_mov_b32 s13, 0x58000
	s_mov_b32 s14, 0xb0000
	s_mov_b32 s15, 0x108000
	s_waitcnt lgkmcnt(0)
	s_mov_b32 s16, 0x1d050000
	s_mov_b32 s17, 0x1d0a8000
	s_mov_b32 s18, 0x1d100000
	s_mov_b32 s19, 0x1d158000
	s_mov_b32 s20, 0x2080000
	s_mov_b32 s21, 0x20d8000
	s_mov_b32 s22, 0x2130000
	s_mov_b32 s23, 0x2188000
	s_mov_b32 s24, 0x3e0f83e1
	s_movk_i32 s25, 0xdf00
	s_movk_i32 s26, 0xff
	s_movk_i32 s27, 0xff00
	s_branch .LBB0_770

.LBB0_773:
	s_lshl_b32 s37, s29, 8
	v_or_b32_e32 v27, s37, v1
	v_mad_i64_i32 v[2:3], s[8:9], v27, s12, v[130:131]
	v_add_co_u32_e32 v6, vcc, 0x58000, v2
	s_lshl_b32 s36, s28, 8
	s_nop 0
	v_addc_co_u32_e32 v7, vcc, 0, v3, vcc
	global_load_dwordx4 v[28:31], v[2:3], off
	global_load_dwordx4 v[32:35], v[6:7], off
	v_add_co_u32_e32 v6, vcc, 0xb0000, v2
	v_or_b32_e32 v60, s36, v1
	s_nop 0
	v_addc_co_u32_e32 v7, vcc, 0, v3, vcc
	v_add_co_u32_e32 v2, vcc, 0x108000, v2
	v_mad_i64_i32 v[4:5], s[8:9], v60, s12, v[132:133]
	s_nop 0
	v_addc_co_u32_e32 v3, vcc, 0, v3, vcc
	global_load_dwordx4 v[36:39], v[6:7], off
	global_load_dwordx4 v[40:43], v[2:3], off
	v_add_co_u32_e32 v2, vcc, s13, v4
	s_waitcnt vmcnt(63) expcnt(7) lgkmcnt(15)
	s_nop 0
	v_addc_co_u32_e32 v3, vcc, 0, v5, vcc
	s_barrier
	global_load_dwordx4 v[44:47], v[4:5], off
	global_load_dwordx4 v[48:51], v[2:3], off
	v_add_co_u32_e32 v2, vcc, s14, v4
	s_mov_b32 s38, 0
	s_nop 0
	v_addc_co_u32_e32 v3, vcc, 0, v5, vcc
	v_add_co_u32_e32 v4, vcc, s15, v4
	s_mov_b64 s[8:9], 0
	s_nop 0
	v_addc_co_u32_e32 v5, vcc, 0, v5, vcc
	global_load_dwordx4 v[52:55], v[2:3], off
	global_load_dwordx4 v[56:59], v[4:5], off
	v_mov_b32_e32 v2, 0
	v_mov_b32_e32 v3, v2
	v_mov_b32_e32 v4, v2
	v_mov_b32_e32 v5, v2
	v_mov_b32_e32 v6, v2
	v_mov_b32_e32 v7, v2
	v_mov_b32_e32 v8, v2
	v_mov_b32_e32 v9, v2
	v_mov_b32_e32 v10, v2
	v_mov_b32_e32 v11, v2
	v_mov_b32_e32 v12, v2
	v_mov_b32_e32 v13, v2
	v_mov_b32_e32 v14, v2
	v_mov_b32_e32 v15, v2
	v_mov_b32_e32 v16, v2
	v_mov_b32_e32 v17, v2
	v_mov_b32_e32 v18, v2
	v_mov_b32_e32 v19, v2
	v_mov_b32_e32 v20, v2
	v_mov_b32_e32 v21, v2
	v_mov_b32_e32 v22, v2
	v_mov_b32_e32 v23, v2
	v_mov_b32_e32 v24, v2
	v_mov_b32_e32 v25, v2
	v_mov_b32_e32 v26, v2
	v_mad_i64_i32 v[136:137], s[40:41], v27, s12, v[134:135]
	v_mad_i64_i32 v[138:139], s[40:41], v60, s12, v[134:135]
	v_mov_b32_e32 v27, v2
	v_mov_b32_e32 v60, v2
	v_mov_b32_e32 v61, v2
	v_mov_b32_e32 v62, v2
	v_mov_b32_e32 v63, v2
	v_mov_b32_e32 v64, v2
	v_mov_b32_e32 v65, v2
	v_mov_b32_e32 v66, v2
	v_mov_b32_e32 v67, v2
	v_mov_b32_e32 v68, v2
	v_mov_b32_e32 v69, v2
	v_mov_b32_e32 v70, v2
	v_mov_b32_e32 v71, v2
	v_mov_b32_e32 v72, v2
	v_mov_b32_e32 v73, v2
	v_mov_b32_e32 v74, v2
	v_mov_b32_e32 v75, v2
	v_mov_b32_e32 v76, v2
	v_mov_b32_e32 v77, v2
	v_mov_b32_e32 v78, v2
	v_mov_b32_e32 v79, v2
	v_mov_b32_e32 v80, v2
	v_mov_b32_e32 v81, v2
	v_mov_b32_e32 v82, v2
	s_waitcnt vmcnt(7)
	ds_write_b128 v146, v[28:31]
	s_waitcnt vmcnt(6)
	ds_write_b128 v146, v[32:35] offset:8192
	s_waitcnt vmcnt(5)
	ds_write_b128 v146, v[36:39] offset:16384
	s_waitcnt vmcnt(4)
	ds_write_b128 v146, v[40:43] offset:24576
	s_waitcnt vmcnt(3)
	ds_write_b128 v147, v[44:47]
	s_waitcnt vmcnt(2)
	ds_write_b128 v147, v[48:51] offset:8192
	s_waitcnt vmcnt(1)
	ds_write_b128 v147, v[52:55] offset:16384
	s_waitcnt vmcnt(0)
	ds_write_b128 v147, v[56:59] offset:24576
	v_mov_b32_e32 v28, v2
	v_mov_b32_e32 v29, v2
	v_mov_b32_e32 v30, v2
	v_mov_b32_e32 v31, v2
	v_mov_b32_e32 v32, v2
	v_mov_b32_e32 v33, v2
	v_mov_b32_e32 v34, v2
	v_mov_b32_e32 v35, v2
	v_mov_b32_e32 v36, v2
	v_mov_b32_e32 v37, v2
	v_mov_b32_e32 v38, v2
	v_mov_b32_e32 v39, v2
	v_mov_b32_e32 v40, v2
	v_mov_b32_e32 v41, v2
	v_mov_b32_e32 v42, v2
	v_mov_b32_e32 v43, v2
	v_mov_b32_e32 v44, v2
	v_mov_b32_e32 v45, v2
	v_mov_b32_e32 v46, v2
	v_mov_b32_e32 v47, v2
	v_mov_b32_e32 v48, v2
	v_mov_b32_e32 v49, v2
	v_mov_b32_e32 v50, v2
	v_mov_b32_e32 v51, v2
	v_mov_b32_e32 v52, v2
	v_mov_b32_e32 v53, v2
	v_mov_b32_e32 v54, v2
	v_mov_b32_e32 v55, v2
	v_mov_b32_e32 v56, v2
	v_mov_b32_e32 v57, v2
	v_mov_b32_e32 v58, v2
	v_mov_b32_e32 v59, v2
	v_mov_b32_e32 v83, v2
	v_mov_b32_e32 v84, v2
	v_mov_b32_e32 v85, v2
	v_mov_b32_e32 v86, v2
	v_mov_b32_e32 v87, v2
	v_mov_b32_e32 v88, v2
	v_mov_b32_e32 v89, v2
	v_mov_b32_e32 v90, v2
	v_mov_b32_e32 v91, v2
	v_mov_b32_e32 v92, v2
	v_mov_b32_e32 v93, v2
	v_mov_b32_e32 v94, v2
	v_mov_b32_e32 v95, v2
	v_mov_b32_e32 v96, v2
	v_mov_b32_e32 v97, v2
	v_mov_b32_e32 v98, v2
	v_mov_b32_e32 v99, v2
	v_mov_b32_e32 v100, v2
	v_mov_b32_e32 v101, v2
	v_mov_b32_e32 v102, v2
	v_mov_b32_e32 v103, v2
	v_mov_b32_e32 v104, v2
	v_mov_b32_e32 v105, v2
	v_mov_b32_e32 v106, v2
	v_mov_b32_e32 v107, v2
	v_mov_b32_e32 v108, v2
	v_mov_b32_e32 v109, v2
	v_mov_b32_e32 v110, v2
	v_mov_b32_e32 v111, v2
	v_mov_b32_e32 v112, v2
	v_mov_b32_e32 v113, v2
	v_mov_b32_e32 v114, v2
	v_mov_b32_e32 v115, v2
	v_mov_b32_e32 v116, v2
	v_mov_b32_e32 v117, v2
	v_mov_b32_e32 v118, v2
	v_mov_b32_e32 v119, v2
	v_mov_b32_e32 v120, v2
	v_mov_b32_e32 v121, v2
	v_mov_b32_e32 v122, v2
	v_mov_b32_e32 v123, v2
	v_mov_b32_e32 v124, v2
	v_mov_b32_e32 v125, v2
	v_mov_b32_e32 v126, v2
	v_mov_b32_e32 v127, v2
	v_mov_b32_e32 v128, v2
	v_mov_b32_e32 v129, v2
	s_waitcnt lgkmcnt(0)
	s_barrier
	v_lshl_add_u64 v[140:141], v[136:137], 0, s[8:9]
	v_add_co_u32_e32 v142, vcc, s16, v140
	s_nop 1
	v_addc_co_u32_e32 v143, vcc, 0, v141, vcc
	v_add_co_u32_e32 v144, vcc, s17, v140
	s_nop 1
	v_addc_co_u32_e32 v145, vcc, 0, v141, vcc
	v_add_co_u32_e32 v156, vcc, s18, v140
	s_nop 1
	v_addc_co_u32_e32 v157, vcc, 0, v141, vcc
	v_add_co_u32_e32 v160, vcc, s19, v140
	s_nop 1
	v_addc_co_u32_e32 v161, vcc, 0, v141, vcc
	global_load_dwordx4 v[140:143], v[142:143], off offset:128
	global_load_dwordx4 v[152:155], v[144:145], off offset:128
	global_load_dwordx4 v[156:159], v[156:157], off offset:128
	global_load_dwordx4 v[160:163], v[160:161], off offset:128
	v_lshl_add_u64 v[144:145], v[138:139], 0, s[8:9]
	v_add_co_u32_e32 v164, vcc, s20, v144
	s_nop 1
	v_addc_co_u32_e32 v165, vcc, 0, v145, vcc
	v_add_co_u32_e32 v168, vcc, s21, v144
	s_nop 1
	v_addc_co_u32_e32 v169, vcc, 0, v145, vcc
	v_add_co_u32_e32 v172, vcc, s22, v144
	s_nop 1
	v_addc_co_u32_e32 v173, vcc, 0, v145, vcc
	v_add_co_u32_e32 v144, vcc, s23, v144
	s_nop 1
	v_addc_co_u32_e32 v145, vcc, 0, v145, vcc
	global_load_dwordx4 v[164:167], v[164:165], off offset:128
	global_load_dwordx4 v[168:171], v[168:169], off offset:128
	global_load_dwordx4 v[172:175], v[172:173], off offset:128
	global_load_dwordx4 v[176:179], v[144:145], off offset:128
	v_mov_b32_e32 v223, v148
	v_mov_b32_e32 v248, v216
	v_mov_b32_e32 v249, v149
	v_mov_b32_e32 v250, v217
	v_xor_b32_e32 v251, 0x8000, v146
	v_xor_b32_e32 v252, 0x8000, v147
	ds_read_b128 v[180:183], v223
	ds_read_b128 v[184:187], v223 offset:2048
	ds_read_b128 v[188:191], v223 offset:4096
	ds_read_b128 v[192:195], v223 offset:6144
	ds_read_b128 v[212:215], v249
	ds_read_b128 v[218:221], v249 offset:2048
	ds_read_b128 v[224:227], v249 offset:4096
	ds_read_b128 v[228:231], v249 offset:6144
.Lg2_p15_loop:
	ds_read_b128 v[196:199], v223 offset:8192
	ds_read_b128 v[200:203], v223 offset:10240
	ds_read_b128 v[204:207], v223 offset:12288
	ds_read_b128 v[208:211], v223 offset:14336
	s_waitcnt lgkmcnt(4)
	v_mfma_f32_16x16x32_bf16 v[126:129], v[212:215], v[180:183], v[126:129]
	v_mfma_f32_16x16x32_bf16 v[122:125], v[218:221], v[180:183], v[122:125]
	v_mfma_f32_16x16x32_bf16 v[118:121], v[224:227], v[180:183], v[118:121]
	v_mfma_f32_16x16x32_bf16 v[114:117], v[228:231], v[180:183], v[114:117]
	v_mfma_f32_16x16x32_bf16 v[110:113], v[212:215], v[184:187], v[110:113]
	v_mfma_f32_16x16x32_bf16 v[106:109], v[218:221], v[184:187], v[106:109]
	v_mfma_f32_16x16x32_bf16 v[102:105], v[224:227], v[184:187], v[102:105]
	v_mfma_f32_16x16x32_bf16 v[98:101], v[228:231], v[184:187], v[98:101]
	v_mfma_f32_16x16x32_bf16 v[94:97], v[212:215], v[188:191], v[94:97]
	v_mfma_f32_16x16x32_bf16 v[90:93], v[218:221], v[188:191], v[90:93]
	v_mfma_f32_16x16x32_bf16 v[86:89], v[224:227], v[188:191], v[86:89]
	v_mfma_f32_16x16x32_bf16 v[82:85], v[228:231], v[188:191], v[82:85]
	v_mfma_f32_16x16x32_bf16 v[78:81], v[212:215], v[192:195], v[78:81]
	v_mfma_f32_16x16x32_bf16 v[74:77], v[218:221], v[192:195], v[74:77]
	v_mfma_f32_16x16x32_bf16 v[70:73], v[224:227], v[192:195], v[70:73]
	v_mfma_f32_16x16x32_bf16 v[66:69], v[228:231], v[192:195], v[66:69]
	ds_read_b128 v[180:183], v248
	ds_read_b128 v[184:187], v248 offset:2048
	ds_read_b128 v[188:191], v248 offset:4096
	ds_read_b128 v[192:195], v248 offset:6144
	ds_read_b128 v[232:235], v250
	ds_read_b128 v[236:239], v250 offset:2048
	ds_read_b128 v[240:243], v250 offset:4096
	ds_read_b128 v[244:247], v250 offset:6144
	s_waitcnt lgkmcnt(8)
	v_mfma_f32_16x16x32_bf16 v[62:65], v[212:215], v[196:199], v[62:65]
	v_mfma_f32_16x16x32_bf16 v[58:61], v[218:221], v[196:199], v[58:61]
	v_mfma_f32_16x16x32_bf16 v[54:57], v[224:227], v[196:199], v[54:57]
	v_mfma_f32_16x16x32_bf16 v[50:53], v[228:231], v[196:199], v[50:53]
	v_mfma_f32_16x16x32_bf16 v[46:49], v[212:215], v[200:203], v[46:49]
	v_mfma_f32_16x16x32_bf16 v[42:45], v[218:221], v[200:203], v[42:45]
	v_mfma_f32_16x16x32_bf16 v[38:41], v[224:227], v[200:203], v[38:41]
	v_mfma_f32_16x16x32_bf16 v[34:37], v[228:231], v[200:203], v[34:37]
	v_mfma_f32_16x16x32_bf16 v[30:33], v[212:215], v[204:207], v[30:33]
	v_mfma_f32_16x16x32_bf16 v[26:29], v[218:221], v[204:207], v[26:29]
	v_mfma_f32_16x16x32_bf16 v[22:25], v[224:227], v[204:207], v[22:25]
	v_mfma_f32_16x16x32_bf16 v[18:21], v[228:231], v[204:207], v[18:21]
	v_mfma_f32_16x16x32_bf16 v[14:17], v[212:215], v[208:211], v[14:17]
	v_mfma_f32_16x16x32_bf16 v[10:13], v[218:221], v[208:211], v[10:13]
	v_mfma_f32_16x16x32_bf16 v[6:9], v[224:227], v[208:211], v[6:9]
	v_mfma_f32_16x16x32_bf16 v[2:5], v[228:231], v[208:211], v[2:5]
	ds_read_b128 v[196:199], v248 offset:8192
	ds_read_b128 v[200:203], v248 offset:10240
	ds_read_b128 v[204:207], v248 offset:12288
	ds_read_b128 v[208:211], v248 offset:14336
	s_waitcnt lgkmcnt(4)
	v_mfma_f32_16x16x32_bf16 v[126:129], v[232:235], v[180:183], v[126:129]
	v_mfma_f32_16x16x32_bf16 v[122:125], v[236:239], v[180:183], v[122:125]
	s_waitcnt vmcnt(7)
	ds_write_b128 v251, v[140:143]
	v_mfma_f32_16x16x32_bf16 v[118:121], v[240:243], v[180:183], v[118:121]
	v_mfma_f32_16x16x32_bf16 v[114:117], v[244:247], v[180:183], v[114:117]
	s_waitcnt vmcnt(6)
	ds_write_b128 v251, v[152:155] offset:8192
	v_mfma_f32_16x16x32_bf16 v[110:113], v[232:235], v[184:187], v[110:113]
	v_mfma_f32_16x16x32_bf16 v[106:109], v[236:239], v[184:187], v[106:109]
	s_waitcnt vmcnt(5)
	ds_write_b128 v251, v[156:159] offset:16384
	v_mfma_f32_16x16x32_bf16 v[102:105], v[240:243], v[184:187], v[102:105]
	v_mfma_f32_16x16x32_bf16 v[98:101], v[244:247], v[184:187], v[98:101]
	s_waitcnt vmcnt(4)
	ds_write_b128 v251, v[160:163] offset:24576
	v_mfma_f32_16x16x32_bf16 v[94:97], v[232:235], v[188:191], v[94:97]
	v_mfma_f32_16x16x32_bf16 v[90:93], v[236:239], v[188:191], v[90:93]
	s_waitcnt vmcnt(3)
	ds_write_b128 v252, v[164:167]
	v_mfma_f32_16x16x32_bf16 v[86:89], v[240:243], v[188:191], v[86:89]
	v_mfma_f32_16x16x32_bf16 v[82:85], v[244:247], v[188:191], v[82:85]
	s_waitcnt vmcnt(2)
	ds_write_b128 v252, v[168:171] offset:8192
	v_mfma_f32_16x16x32_bf16 v[78:81], v[232:235], v[192:195], v[78:81]
	v_mfma_f32_16x16x32_bf16 v[74:77], v[236:239], v[192:195], v[74:77]
	s_waitcnt vmcnt(1)
	ds_write_b128 v252, v[172:175] offset:16384
	v_mfma_f32_16x16x32_bf16 v[70:73], v[240:243], v[192:195], v[70:73]
	v_mfma_f32_16x16x32_bf16 v[66:69], v[244:247], v[192:195], v[66:69]
	s_waitcnt vmcnt(0)
	ds_write_b128 v252, v[176:179] offset:24576
	s_waitcnt lgkmcnt(0)
	s_barrier
	s_add_u32 s8, s8, 0x80
	s_addc_u32 s9, s9, 0
	s_cmpk_eq_i32 s8, 0x1580
	s_cbranch_scc1 .Lg2_p15_tail
	v_xor_b32_e32 v223, 0x8000, v223
	v_xor_b32_e32 v249, 0x8000, v249
	v_xor_b32_e32 v248, 0x8000, v248
	v_xor_b32_e32 v250, 0x8000, v250
	v_xor_b32_e32 v251, 0x8000, v251
	v_xor_b32_e32 v252, 0x8000, v252
	ds_read_b128 v[180:183], v223
	ds_read_b128 v[184:187], v223 offset:2048
	ds_read_b128 v[188:191], v223 offset:4096
	ds_read_b128 v[192:195], v223 offset:6144
	ds_read_b128 v[212:215], v249
	ds_read_b128 v[218:221], v249 offset:2048
	ds_read_b128 v[224:227], v249 offset:4096
	ds_read_b128 v[228:231], v249 offset:6144
	v_mfma_f32_16x16x32_bf16 v[62:65], v[232:235], v[196:199], v[62:65]
	v_lshl_add_u64 v[140:141], v[136:137], 0, s[8:9]
	v_add_co_u32_e32 v142, vcc, s16, v140
	v_mfma_f32_16x16x32_bf16 v[58:61], v[236:239], v[196:199], v[58:61]
	s_nop 1
	v_addc_co_u32_e32 v143, vcc, 0, v141, vcc
	v_mfma_f32_16x16x32_bf16 v[54:57], v[240:243], v[196:199], v[54:57]
	v_add_co_u32_e32 v144, vcc, s17, v140
	s_nop 1
	v_mfma_f32_16x16x32_bf16 v[50:53], v[244:247], v[196:199], v[50:53]
	v_addc_co_u32_e32 v145, vcc, 0, v141, vcc
	v_add_co_u32_e32 v156, vcc, s18, v140
	v_mfma_f32_16x16x32_bf16 v[46:49], v[232:235], v[200:203], v[46:49]
	s_nop 1
	v_addc_co_u32_e32 v157, vcc, 0, v141, vcc
	v_mfma_f32_16x16x32_bf16 v[42:45], v[236:239], v[200:203], v[42:45]
	v_add_co_u32_e32 v160, vcc, s19, v140
	s_nop 1
	v_mfma_f32_16x16x32_bf16 v[38:41], v[240:243], v[200:203], v[38:41]
	v_addc_co_u32_e32 v161, vcc, 0, v141, vcc
	global_load_dwordx4 v[140:143], v[142:143], off offset:128
	v_mfma_f32_16x16x32_bf16 v[34:37], v[244:247], v[200:203], v[34:37]
	global_load_dwordx4 v[152:155], v[144:145], off offset:128
	global_load_dwordx4 v[156:159], v[156:157], off offset:128
	global_load_dwordx4 v[160:163], v[160:161], off offset:128
	v_mfma_f32_16x16x32_bf16 v[30:33], v[232:235], v[204:207], v[30:33]
	v_lshl_add_u64 v[144:145], v[138:139], 0, s[8:9]
	v_add_co_u32_e32 v164, vcc, s20, v144
	v_mfma_f32_16x16x32_bf16 v[26:29], v[236:239], v[204:207], v[26:29]
	s_nop 1
	v_addc_co_u32_e32 v165, vcc, 0, v145, vcc
	v_mfma_f32_16x16x32_bf16 v[22:25], v[240:243], v[204:207], v[22:25]
	v_add_co_u32_e32 v168, vcc, s21, v144
	s_nop 1
	v_mfma_f32_16x16x32_bf16 v[18:21], v[244:247], v[204:207], v[18:21]
	v_addc_co_u32_e32 v169, vcc, 0, v145, vcc
	v_add_co_u32_e32 v172, vcc, s22, v144
	v_mfma_f32_16x16x32_bf16 v[14:17], v[232:235], v[208:211], v[14:17]
	s_nop 1
	v_addc_co_u32_e32 v173, vcc, 0, v145, vcc
	v_mfma_f32_16x16x32_bf16 v[10:13], v[236:239], v[208:211], v[10:13]
	v_add_co_u32_e32 v144, vcc, s23, v144
	s_nop 1
	v_mfma_f32_16x16x32_bf16 v[6:9], v[240:243], v[208:211], v[6:9]
	v_addc_co_u32_e32 v145, vcc, 0, v145, vcc
	global_load_dwordx4 v[164:167], v[164:165], off offset:128
	v_mfma_f32_16x16x32_bf16 v[2:5], v[244:247], v[208:211], v[2:5]
	global_load_dwordx4 v[168:171], v[168:169], off offset:128
	global_load_dwordx4 v[172:175], v[172:173], off offset:128
	global_load_dwordx4 v[176:179], v[144:145], off offset:128
	s_branch .Lg2_p15_loop
.Lg2_p15_tail:
	v_mfma_f32_16x16x32_bf16 v[62:65], v[232:235], v[196:199], v[62:65]
	v_mfma_f32_16x16x32_bf16 v[58:61], v[236:239], v[196:199], v[58:61]
	v_mfma_f32_16x16x32_bf16 v[54:57], v[240:243], v[196:199], v[54:57]
	v_mfma_f32_16x16x32_bf16 v[50:53], v[244:247], v[196:199], v[50:53]
	v_mfma_f32_16x16x32_bf16 v[46:49], v[232:235], v[200:203], v[46:49]
	v_mfma_f32_16x16x32_bf16 v[42:45], v[236:239], v[200:203], v[42:45]
	v_mfma_f32_16x16x32_bf16 v[38:41], v[240:243], v[200:203], v[38:41]
	v_mfma_f32_16x16x32_bf16 v[34:37], v[244:247], v[200:203], v[34:37]
	v_mfma_f32_16x16x32_bf16 v[30:33], v[232:235], v[204:207], v[30:33]
	v_mfma_f32_16x16x32_bf16 v[26:29], v[236:239], v[204:207], v[26:29]
	v_mfma_f32_16x16x32_bf16 v[22:25], v[240:243], v[204:207], v[22:25]
	v_mfma_f32_16x16x32_bf16 v[18:21], v[244:247], v[204:207], v[18:21]
	v_mfma_f32_16x16x32_bf16 v[14:17], v[232:235], v[208:211], v[14:17]
	v_mfma_f32_16x16x32_bf16 v[10:13], v[236:239], v[208:211], v[10:13]
	v_mfma_f32_16x16x32_bf16 v[6:9], v[240:243], v[208:211], v[6:9]
	v_mfma_f32_16x16x32_bf16 v[2:5], v[244:247], v[208:211], v[2:5]
	ds_read_b128 v[136:139], v149 offset:32768
	ds_read_b128 v[140:143], v149 offset:34816
	ds_read_b128 v[152:155], v149 offset:36864
	ds_read_b128 v[156:159], v149 offset:38912
	ds_read_b128 v[160:163], v148 offset:32768
	ds_read_b128 v[164:167], v148 offset:34816
	ds_read_b128 v[168:171], v148 offset:36864
	ds_read_b128 v[172:175], v148 offset:38912
	s_setprio 1
	s_waitcnt lgkmcnt(3)
	v_mfma_f32_16x16x32_bf16 v[126:129], v[136:139], v[160:163], v[126:129]
	v_mfma_f32_16x16x32_bf16 v[122:125], v[140:143], v[160:163], v[122:125]
	v_mfma_f32_16x16x32_bf16 v[118:121], v[152:155], v[160:163], v[118:121]
	v_mfma_f32_16x16x32_bf16 v[114:117], v[156:159], v[160:163], v[114:117]
	s_waitcnt lgkmcnt(2)
	v_mfma_f32_16x16x32_bf16 v[110:113], v[136:139], v[164:167], v[110:113]
	v_mfma_f32_16x16x32_bf16 v[106:109], v[140:143], v[164:167], v[106:109]
	v_mfma_f32_16x16x32_bf16 v[102:105], v[152:155], v[164:167], v[102:105]
	v_mfma_f32_16x16x32_bf16 v[98:101], v[156:159], v[164:167], v[98:101]
	s_waitcnt lgkmcnt(1)
	v_mfma_f32_16x16x32_bf16 v[94:97], v[136:139], v[168:171], v[94:97]
	v_mfma_f32_16x16x32_bf16 v[90:93], v[140:143], v[168:171], v[90:93]
	v_mfma_f32_16x16x32_bf16 v[86:89], v[152:155], v[168:171], v[86:89]
	v_mfma_f32_16x16x32_bf16 v[82:85], v[156:159], v[168:171], v[82:85]
	s_waitcnt lgkmcnt(0)
	v_mfma_f32_16x16x32_bf16 v[78:81], v[136:139], v[172:175], v[78:81]
	v_mfma_f32_16x16x32_bf16 v[74:77], v[140:143], v[172:175], v[74:77]
	v_mfma_f32_16x16x32_bf16 v[70:73], v[152:155], v[172:175], v[70:73]
	v_mfma_f32_16x16x32_bf16 v[66:69], v[156:159], v[172:175], v[66:69]
	s_setprio 0
	ds_read_b128 v[160:163], v148 offset:40960
	ds_read_b128 v[164:167], v148 offset:43008
	ds_read_b128 v[168:171], v148 offset:45056
	ds_read_b128 v[172:175], v148 offset:47104
	s_setprio 1
	s_waitcnt lgkmcnt(3)
	v_mfma_f32_16x16x32_bf16 v[62:65], v[136:139], v[160:163], v[62:65]
	v_mfma_f32_16x16x32_bf16 v[58:61], v[140:143], v[160:163], v[58:61]
	v_mfma_f32_16x16x32_bf16 v[54:57], v[152:155], v[160:163], v[54:57]
	v_mfma_f32_16x16x32_bf16 v[50:53], v[156:159], v[160:163], v[50:53]
	s_waitcnt lgkmcnt(2)
	v_mfma_f32_16x16x32_bf16 v[46:49], v[136:139], v[164:167], v[46:49]
	v_mfma_f32_16x16x32_bf16 v[42:45], v[140:143], v[164:167], v[42:45]
	v_mfma_f32_16x16x32_bf16 v[38:41], v[152:155], v[164:167], v[38:41]
	v_mfma_f32_16x16x32_bf16 v[34:37], v[156:159], v[164:167], v[34:37]
	s_waitcnt lgkmcnt(1)
	v_mfma_f32_16x16x32_bf16 v[30:33], v[136:139], v[168:171], v[30:33]
	v_mfma_f32_16x16x32_bf16 v[26:29], v[140:143], v[168:171], v[26:29]
	v_mfma_f32_16x16x32_bf16 v[22:25], v[152:155], v[168:171], v[22:25]
	v_mfma_f32_16x16x32_bf16 v[18:21], v[156:159], v[168:171], v[18:21]
	s_waitcnt lgkmcnt(0)
	v_mfma_f32_16x16x32_bf16 v[14:17], v[136:139], v[172:175], v[14:17]
	v_mfma_f32_16x16x32_bf16 v[10:13], v[140:143], v[172:175], v[10:13]
	v_mfma_f32_16x16x32_bf16 v[6:9], v[152:155], v[172:175], v[6:9]
	v_mfma_f32_16x16x32_bf16 v[2:5], v[156:159], v[172:175], v[2:5]
	s_setprio 0
	ds_read_b128 v[136:139], v217 offset:32768
	ds_read_b128 v[140:143], v217 offset:34816
	ds_read_b128 v[152:155], v217 offset:36864
	ds_read_b128 v[156:159], v217 offset:38912
	ds_read_b128 v[160:163], v216 offset:32768
	ds_read_b128 v[164:167], v216 offset:34816
	ds_read_b128 v[168:171], v216 offset:36864
	ds_read_b128 v[172:175], v216 offset:38912
	s_setprio 1
	s_waitcnt lgkmcnt(3)
	v_mfma_f32_16x16x32_bf16 v[126:129], v[136:139], v[160:163], v[126:129]
	v_mfma_f32_16x16x32_bf16 v[122:125], v[140:143], v[160:163], v[122:125]
	v_mfma_f32_16x16x32_bf16 v[118:121], v[152:155], v[160:163], v[118:121]
	v_mfma_f32_16x16x32_bf16 v[114:117], v[156:159], v[160:163], v[114:117]
	s_waitcnt lgkmcnt(2)
	v_mfma_f32_16x16x32_bf16 v[110:113], v[136:139], v[164:167], v[110:113]
	v_mfma_f32_16x16x32_bf16 v[106:109], v[140:143], v[164:167], v[106:109]
	v_mfma_f32_16x16x32_bf16 v[102:105], v[152:155], v[164:167], v[102:105]
	v_mfma_f32_16x16x32_bf16 v[98:101], v[156:159], v[164:167], v[98:101]
	s_waitcnt lgkmcnt(1)
	v_mfma_f32_16x16x32_bf16 v[94:97], v[136:139], v[168:171], v[94:97]
	v_mfma_f32_16x16x32_bf16 v[90:93], v[140:143], v[168:171], v[90:93]
	v_mfma_f32_16x16x32_bf16 v[86:89], v[152:155], v[168:171], v[86:89]
	v_mfma_f32_16x16x32_bf16 v[82:85], v[156:159], v[168:171], v[82:85]
	s_waitcnt lgkmcnt(0)
	v_mfma_f32_16x16x32_bf16 v[78:81], v[136:139], v[172:175], v[78:81]
	v_mfma_f32_16x16x32_bf16 v[74:77], v[140:143], v[172:175], v[74:77]
	v_mfma_f32_16x16x32_bf16 v[70:73], v[152:155], v[172:175], v[70:73]
	v_mfma_f32_16x16x32_bf16 v[66:69], v[156:159], v[172:175], v[66:69]
	s_setprio 0
	ds_read_b128 v[160:163], v216 offset:40960
	ds_read_b128 v[164:167], v216 offset:43008
	ds_read_b128 v[168:171], v216 offset:45056
	ds_read_b128 v[172:175], v216 offset:47104
	s_setprio 1
	s_waitcnt lgkmcnt(3)
	v_mfma_f32_16x16x32_bf16 v[62:65], v[136:139], v[160:163], v[62:65]
	v_mfma_f32_16x16x32_bf16 v[58:61], v[140:143], v[160:163], v[58:61]
	v_mfma_f32_16x16x32_bf16 v[54:57], v[152:155], v[160:163], v[54:57]
	v_mfma_f32_16x16x32_bf16 v[50:53], v[156:159], v[160:163], v[50:53]
	s_waitcnt lgkmcnt(2)
	v_mfma_f32_16x16x32_bf16 v[46:49], v[136:139], v[164:167], v[46:49]
	v_mfma_f32_16x16x32_bf16 v[42:45], v[140:143], v[164:167], v[42:45]
	v_mfma_f32_16x16x32_bf16 v[38:41], v[152:155], v[164:167], v[38:41]
	v_mfma_f32_16x16x32_bf16 v[34:37], v[156:159], v[164:167], v[34:37]
	s_waitcnt lgkmcnt(1)
	v_mfma_f32_16x16x32_bf16 v[30:33], v[136:139], v[168:171], v[30:33]
	v_mfma_f32_16x16x32_bf16 v[26:29], v[140:143], v[168:171], v[26:29]
	v_mfma_f32_16x16x32_bf16 v[22:25], v[152:155], v[168:171], v[22:25]
	v_mfma_f32_16x16x32_bf16 v[18:21], v[156:159], v[168:171], v[18:21]
	s_waitcnt lgkmcnt(0)
	v_mfma_f32_16x16x32_bf16 v[14:17], v[136:139], v[172:175], v[14:17]
	v_mfma_f32_16x16x32_bf16 v[10:13], v[140:143], v[172:175], v[10:13]
	v_mfma_f32_16x16x32_bf16 v[6:9], v[152:155], v[172:175], v[6:9]
	v_mfma_f32_16x16x32_bf16 v[2:5], v[156:159], v[172:175], v[2:5]
	s_setprio 0
	v_add_u32_e32 v152, s37, v150
	v_mul_hi_i32 v136, v152, s24
	v_lshrrev_b32_e32 v137, 31, v136
	v_ashrrev_i32_e32 v136, 11, v136
	v_add_u32_e32 v137, v136, v137
	v_mad_i32_i24 v142, v137, s25, v152
	v_lshlrev_b32_e32 v139, 13, v137
	v_cmp_lt_i32_e32 vcc, s26, v142
	v_add3_u32 v138, v139, v142, s27
	s_barrier
	s_and_saveexec_b64 s[8:9], vcc
	s_xor_b64 s[8:9], exec, s[8:9]
	v_add3_u32 v136, v139, v142, s27
	s_or_saveexec_b64 s[8:9], s[8:9]
	v_mov_b64_e32 v[140:141], s[84:85]
	v_lshl_add_u32 v139, v137, 8, v142
	s_xor_b64 exec, exec, s[8:9]
	v_lshl_add_u32 v136, v137, 8, v142
	v_mov_b64_e32 v[140:141], s[4:5]
	s_or_b64 exec, exec, s[8:9]
	s_and_saveexec_b64 s[8:9], vcc
	s_xor_b64 s[8:9], exec, s[8:9]
	s_cbranch_execz .LBB0_781
	v_mul_hi_i32_i24_e32 v143, 0x6000, v137
	v_mul_i32_i24_e32 v142, 0x6000, v137
	s_or_saveexec_b64 s[8:9], s[8:9]
	v_mov_b64_e32 v[144:145], s[84:85]
	s_xor_b64 exec, exec, s[8:9]
	s_cbranch_execnz .LBB0_782
	s_branch .LBB0_783

	.amdhsa_kernel _Z10fwd_kernel2Pm
		.amdhsa_group_segment_fixed_size 0
		.amdhsa_private_segment_fixed_size 0
		.amdhsa_kernarg_size 536
		.amdhsa_user_sgpr_count 2
		.amdhsa_user_sgpr_dispatch_ptr 0
		.amdhsa_user_sgpr_queue_ptr 0
		.amdhsa_user_sgpr_kernarg_segment_ptr 1
		.amdhsa_user_sgpr_dispatch_id 0
		.amdhsa_user_sgpr_kernarg_preload_length 0
		.amdhsa_user_sgpr_kernarg_preload_offset 0
		.amdhsa_user_sgpr_private_segment_size 0
		.amdhsa_uses_dynamic_stack 0
		.amdhsa_enable_private_segment 0
		.amdhsa_system_sgpr_workgroup_id_x 1
		.amdhsa_system_sgpr_workgroup_id_y 0
		.amdhsa_system_sgpr_workgroup_id_z 0
		.amdhsa_system_sgpr_workgroup_info 0
		.amdhsa_system_vgpr_workitem_id 2
		.amdhsa_next_free_vgpr 256
		.amdhsa_next_free_sgpr 98
		.amdhsa_accum_offset 256
		.amdhsa_reserve_vcc 1
		.amdhsa_float_round_mode_32 0
		.amdhsa_float_round_mode_16_64 0
		.amdhsa_float_denorm_mode_32 3
		.amdhsa_float_denorm_mode_16_64 3
		.amdhsa_dx10_clamp 1
		.amdhsa_ieee_mode 1
		.amdhsa_fp16_overflow 0
		.amdhsa_tg_split 0
		.amdhsa_exception_fp_ieee_invalid_op 0
		.amdhsa_exception_fp_denorm_src 0
		.amdhsa_exception_fp_ieee_div_zero 0
		.amdhsa_exception_fp_ieee_overflow 0
		.amdhsa_exception_fp_ieee_underflow 0
		.amdhsa_exception_fp_ieee_inexact 0
		.amdhsa_exception_int_div_zero 0
	.end_amdhsa_kernel

amdhsa.kernels:
  - .agpr_count:     0
    .args:
      - .offset:         0
        .size:           280
        .value_kind:     by_value
      - .offset:         280
        .size:           4
        .value_kind:     hidden_block_count_x
      - .offset:         284
        .size:           4
        .value_kind:     hidden_block_count_y
      - .offset:         288
        .size:           4
        .value_kind:     hidden_block_count_z
      - .offset:         292
        .size:           2
        .value_kind:     hidden_group_size_x
      - .offset:         294
        .size:           2
        .value_kind:     hidden_group_size_y
      - .offset:         296
        .size:           2
        .value_kind:     hidden_group_size_z
      - .offset:         298
        .size:           2
        .value_kind:     hidden_remainder_x
      - .offset:         300
        .size:           2
        .value_kind:     hidden_remainder_y
      - .offset:         302
        .size:           2
        .value_kind:     hidden_remainder_z
      - .offset:         320
        .size:           8
        .value_kind:     hidden_global_offset_x
      - .offset:         328
        .size:           8
        .value_kind:     hidden_global_offset_y
      - .offset:         336
        .size:           8
        .value_kind:     hidden_global_offset_z
      - .offset:         344
        .size:           2
        .value_kind:     hidden_grid_dims
      - .offset:         368
        .size:           8
        .value_kind:     hidden_multigrid_sync_arg
      - .offset:         400
        .size:           4
        .value_kind:     hidden_dynamic_lds_size
    .group_segment_fixed_size: 0
    .kernarg_segment_align: 8
    .kernarg_segment_size: 536
    .language:       OpenCL C
    .language_version:
      - 2
      - 0
    .max_flat_workgroup_size: 512
    .name:           _Z10fwd_kernel2Pm
    .private_segment_fixed_size: 0
    .sgpr_count:     104
    .sgpr_spill_count: 2
    .symbol:         _Z10fwd_kernel2Pm.kd
    .uniform_work_group_size: 1
    .uses_dynamic_stack: false
    .vgpr_count:     256
    .vgpr_spill_count: 0
    .wavefront_size: 64
